# nt stores for the projection output and final output, nt loads for read-once f32 inputs in the prep phase, sc1 stores for FFN hidden; plus skinny beta/decay block
# speedup vs baseline: 1.0186x; 1.0019x over previous
; __device__ __forceinline__ void tr_item(const float* __restrict__ W, int K, int Nsrc, int col0, int nvalid, const float* __restrict__ gain, bf16_t* WT, int drow0, int k0, LAS float* scr, int lane) {
;     ...
;     for (int i = 0; i < 32; ++i) { const int kk = 2 * i + (lane >> 5), n = lane & 31; v[i] = 0.f; if (n < nvalid) v[i] = W[(size_t)(k0 + kk) * Nsrc + col0 + n]; }
; #pragma unroll
;     for (int i = 0; i < 32; ++i) { const int kk = 2 * i + (lane >> 5), n = lane & 31; float x = v[i]; if (gain) x *= gain[k0 + kk]; scr[kk * 33 + n] = x; }
; __device__ __forceinline__ void conv_job(int kind, const float* W, const float* W2, int K, int Nsrc, int Ndst, const float* gain, bf16_t* WT, LAS float* scr, int gw, int NGW, int lane) {
;     ...
;         const int kb = it / nb, db = it % nb, d0 = db * 32, k0 = kb * 64; const float* src = W; int col0 = d0, nvalid = 32;
;         if (kind == 1) { const int t = d0 >> 8; int r = d0 & 255; if (r >= 128) { src = W2; r -= 128; } col0 = t * 128 + r; }
.LBB0_10:
	s_mul_hi_i32 s6, s29, 0x2e8ba2e9
	s_lshr_b32 s7, s6, 31
	s_ashr_i32 s6, s6, 6
	s_add_i32 s7, s6, s7
	s_mul_i32 s6, s7, 0xffffd400
	s_add_i32 s30, s3, s6
	s_and_b32 s20, s30, 0xe0
	s_lshl_b32 s6, s7, 6
	s_add_i32 s21, s20, 0xffffff80
	s_cmpk_gt_u32 s20, 0x7f
	s_mulk_i32 s7, 0xea00
	s_cselect_b32 s31, s1, s11
	s_cselect_b32 s33, s0, s10
	s_add_i32 s7, s26, s7
	s_min_u32 s20, s21, s20
	s_and_b32 s7, s7, 0xffffff80
	s_add_i32 s20, s20, s7
	s_ashr_i32 s21, s20, 31
	s_lshl_b64 s[20:21], s[20:21], 2
	s_add_u32 s20, s33, s20
	v_or_b32_e32 v26, s6, v2
	s_addc_u32 s21, s31, s21
	v_lshl_add_u64 v[10:11], s[20:21], 0, v[6:7]
	v_or_b32_e32 v22, 10, v26
	v_or_b32_e32 v18, 6, v26
	v_mad_i64_i32 v[38:39], s[20:21], v22, s28, v[10:11]
	v_or_b32_e32 v22, 12, v26
	v_mad_i64_i32 v[12:13], s[20:21], v26, s28, v[10:11]
	v_or_b32_e32 v14, 2, v26
	v_or_b32_e32 v16, 4, v26
	v_mad_i64_i32 v[18:19], s[20:21], v18, s28, v[10:11]
	v_or_b32_e32 v20, 8, v26
	v_mad_i64_i32 v[40:41], s[20:21], v22, s28, v[10:11]
	v_or_b32_e32 v22, 14, v26
	v_mad_i64_i32 v[14:15], s[20:21], v14, s28, v[10:11]
	v_mad_i64_i32 v[16:17], s[20:21], v16, s28, v[10:11]
	v_mad_i64_i32 v[20:21], s[20:21], v20, s28, v[10:11]
	v_mad_i64_i32 v[42:43], s[20:21], v22, s28, v[10:11]
	global_load_dword v50, v[12:13], off nt
	global_load_dword v51, v[14:15], off nt
	global_load_dword v24, v[16:17], off nt
	global_load_dword v25, v[18:19], off nt
	global_load_dword v48, v[20:21], off nt
	global_load_dword v49, v[38:39], off nt
	global_load_dword v22, v[40:41], off nt
	global_load_dword v23, v[42:43], off nt
	v_or_b32_e32 v18, 22, v26
	v_mad_i64_i32 v[38:39], s[20:21], v18, s28, v[10:11]
	v_or_b32_e32 v18, 24, v26
	v_mad_i64_i32 v[40:41], s[20:21], v18, s28, v[10:11]
	v_or_b32_e32 v18, 26, v26
	v_or_b32_e32 v12, 16, v26
	v_or_b32_e32 v14, 18, v26
	v_mad_i64_i32 v[42:43], s[20:21], v18, s28, v[10:11]
	v_or_b32_e32 v18, 28, v26
	v_mad_i64_i32 v[12:13], s[20:21], v12, s28, v[10:11]
	v_mad_i64_i32 v[14:15], s[20:21], v14, s28, v[10:11]
	v_or_b32_e32 v16, 20, v26
	v_mad_i64_i32 v[52:53], s[20:21], v18, s28, v[10:11]
	v_or_b32_e32 v18, 30, v26
	v_mad_i64_i32 v[16:17], s[20:21], v16, s28, v[10:11]
	v_mad_i64_i32 v[54:55], s[20:21], v18, s28, v[10:11]
	global_load_dword v46, v[12:13], off nt
	global_load_dword v47, v[14:15], off nt
	global_load_dword v20, v[16:17], off nt
	global_load_dword v21, v[38:39], off nt
	global_load_dword v44, v[40:41], off nt
	global_load_dword v45, v[42:43], off nt
	global_load_dword v18, v[52:53], off nt
	global_load_dword v19, v[54:55], off nt
	v_or_b32_e32 v14, 34, v26
	v_mad_i64_i32 v[38:39], s[20:21], v14, s28, v[10:11]
	v_or_b32_e32 v14, 36, v26
	v_mad_i64_i32 v[52:53], s[20:21], v14, s28, v[10:11]
	v_or_b32_e32 v14, 38, v26
	v_mad_i64_i32 v[54:55], s[20:21], v14, s28, v[10:11]
	v_or_b32_e32 v14, 40, v26
	v_mad_i64_i32 v[56:57], s[20:21], v14, s28, v[10:11]
	v_or_b32_e32 v14, 42, v26
	v_or_b32_e32 v12, 32, v26
	v_mad_i64_i32 v[58:59], s[20:21], v14, s28, v[10:11]
	v_or_b32_e32 v14, 44, v26
	v_mad_i64_i32 v[12:13], s[20:21], v12, s28, v[10:11]
	v_mad_i64_i32 v[60:61], s[20:21], v14, s28, v[10:11]
	v_or_b32_e32 v14, 46, v26
	v_mad_i64_i32 v[62:63], s[20:21], v14, s28, v[10:11]
	global_load_dword v42, v[12:13], off nt
	global_load_dword v43, v[38:39], off nt
	global_load_dword v16, v[52:53], off nt
	global_load_dword v17, v[54:55], off nt
	global_load_dword v40, v[56:57], off nt
	global_load_dword v41, v[58:59], off nt
	global_load_dword v14, v[60:61], off nt
	global_load_dword v15, v[62:63], off nt
	v_or_b32_e32 v12, 48, v26
	v_mad_i64_i32 v[52:53], s[20:21], v12, s28, v[10:11]
	v_or_b32_e32 v12, 50, v26
	v_mad_i64_i32 v[54:55], s[20:21], v12, s28, v[10:11]
	v_or_b32_e32 v12, 52, v26
	v_mad_i64_i32 v[56:57], s[20:21], v12, s28, v[10:11]
	v_or_b32_e32 v12, 54, v26
	v_mad_i64_i32 v[58:59], s[20:21], v12, s28, v[10:11]
	v_or_b32_e32 v12, 56, v26
	v_mad_i64_i32 v[60:61], s[20:21], v12, s28, v[10:11]
	v_or_b32_e32 v12, 58, v26
	v_mad_i64_i32 v[62:63], s[20:21], v12, s28, v[10:11]
	v_or_b32_e32 v12, 60, v26
	v_mad_i64_i32 v[64:65], s[20:21], v12, s28, v[10:11]
	v_or_b32_e32 v12, 62, v26
	v_mad_i64_i32 v[66:67], s[20:21], v12, s28, v[10:11]
	global_load_dword v38, v[52:53], off nt
	global_load_dword v39, v[54:55], off nt
	global_load_dword v12, v[56:57], off nt
	global_load_dword v13, v[58:59], off nt
	global_load_dword v35, v[60:61], off nt
	global_load_dword v37, v[62:63], off nt
	global_load_dword v10, v[64:65], off nt
	global_load_dword v11, v[66:67], off nt
	s_and_b64 vcc, exec, s[4:5]
	s_cbranch_vccnz .LBB0_33
	v_ashrrev_i32_e32 v27, 31, v26
	s_ashr_i32 s7, s6, 31
	v_lshl_add_u64 v[26:27], v[26:27], 2, s[8:9]
	v_lshl_add_u64 v[52:53], s[6:7], 0, v[2:3]
	v_lshl_add_u64 v[52:53], v[52:53], 2, s[8:9]
	global_load_dword v56, v[26:27], off nt
	global_load_dword v57, v[52:53], off offset:8
	global_load_dword v54, v[52:53], off offset:16
	global_load_dword v55, v[52:53], off offset:24
	s_waitcnt vmcnt(3)
	v_mul_f32_e32 v52, v50, v56
	s_waitcnt vmcnt(2)
	v_mul_f32_e32 v53, v51, v57
	ds_write2_b32 v29, v52, v53 offset1:66
	s_waitcnt vmcnt(0)
	v_pk_mul_f32 v[26:27], v[24:25], v[54:55]
	s_cbranch_execnz .LBB0_13

; __device__ __forceinline__ void tr_item(const float* __restrict__ W, int K, int Nsrc, int col0, int nvalid, const float* __restrict__ gain, bf16_t* WT, int drow0, int k0, LAS float* scr, int lane) {
;     ...
;     for (int i = 0; i < 32; ++i) { const int kk = 2 * i + (lane >> 5), n = lane & 31; v[i] = 0.f; if (n < nvalid) v[i] = W[(size_t)(k0 + kk) * Nsrc + col0 + n]; }
; __device__ __forceinline__ void conv_job(int kind, const float* W, const float* W2, int K, int Nsrc, int Ndst, const float* gain, bf16_t* WT, LAS float* scr, int gw, int NGW, int lane) {
;     const int nb = Ndst / 32, nitems = (K / 64) * nb;
;     for (int it = gw; it < nitems; it += NGW) {
;         const int kb = it / nb, db = it % nb, d0 = db * 32, k0 = kb * 64; const float* src = W; int col0 = d0, nvalid = 32;
.LBB0_43:
	s_ashr_i32 s0, s7, 31
	s_lshr_b32 s0, s0, 26
	s_add_i32 s0, s7, s0
	s_ashr_i32 s8, s0, 6
	s_andn2_b32 s0, s0, 63
	s_lshl_b32 s1, s8, 11
	v_or_b32_e32 v18, s0, v2
	s_sub_i32 s4, s3, s1
	v_or_b32_e32 v32, 10, v18
	v_or_b32_e32 v38, 12, v18
	v_or_b32_e32 v40, 14, v18
	v_or_b32_e32 v50, 24, v18
	v_or_b32_e32 v52, 26, v18
	v_or_b32_e32 v54, 28, v18
	v_or_b32_e32 v56, 30, v18
	v_ashrrev_i32_e32 v19, 31, v18
	v_or_b32_e32 v20, 2, v18
	v_or_b32_e32 v22, 4, v18
	v_or_b32_e32 v24, 6, v18
	v_or_b32_e32 v30, 8, v18
	v_or_b32_e32 v42, 16, v18
	v_or_b32_e32 v44, 18, v18
	v_or_b32_e32 v46, 20, v18
	v_or_b32_e32 v48, 22, v18
	v_or_b32_e32 v58, 32, v18
	v_or_b32_e32 v60, 34, v18
	v_or_b32_e32 v62, 36, v18
	v_or_b32_e32 v64, 38, v18
	v_or_b32_e32 v66, 40, v18
	v_or_b32_e32 v68, 42, v18
	v_or_b32_e32 v70, 44, v18
	v_or_b32_e32 v72, 46, v18
	v_or_b32_e32 v74, 48, v18
	v_or_b32_e32 v76, 50, v18
	v_or_b32_e32 v78, 52, v18
	v_or_b32_e32 v80, 54, v18
	v_or_b32_e32 v82, 56, v18
	v_or_b32_e32 v84, 58, v18
	v_or_b32_e32 v86, 60, v18
	v_or_b32_e32 v88, 62, v18
	s_ashr_i32 s5, s4, 31
	v_ashrrev_i32_e32 v33, 31, v32
	v_ashrrev_i32_e32 v39, 31, v38
	v_ashrrev_i32_e32 v41, 31, v40
	v_ashrrev_i32_e32 v51, 31, v50
	v_ashrrev_i32_e32 v53, 31, v52
	v_ashrrev_i32_e32 v55, 31, v54
	v_ashrrev_i32_e32 v57, 31, v56
	v_lshlrev_b64 v[18:19], 13, v[18:19]
	v_ashrrev_i32_e32 v21, 31, v20
	v_ashrrev_i32_e32 v23, 31, v22
	v_ashrrev_i32_e32 v25, 31, v24
	v_ashrrev_i32_e32 v31, 31, v30
	v_ashrrev_i32_e32 v43, 31, v42
	v_ashrrev_i32_e32 v45, 31, v44
	v_ashrrev_i32_e32 v47, 31, v46
	v_ashrrev_i32_e32 v49, 31, v48
	v_ashrrev_i32_e32 v59, 31, v58
	v_ashrrev_i32_e32 v61, 31, v60
	v_ashrrev_i32_e32 v63, 31, v62
	v_ashrrev_i32_e32 v65, 31, v64
	v_ashrrev_i32_e32 v67, 31, v66
	v_ashrrev_i32_e32 v69, 31, v68
	v_ashrrev_i32_e32 v71, 31, v70
	v_ashrrev_i32_e32 v73, 31, v72
	v_ashrrev_i32_e32 v75, 31, v74
	v_ashrrev_i32_e32 v77, 31, v76
	v_ashrrev_i32_e32 v79, 31, v78
	v_ashrrev_i32_e32 v81, 31, v80
	v_ashrrev_i32_e32 v83, 31, v82
	v_ashrrev_i32_e32 v85, 31, v84
	v_ashrrev_i32_e32 v87, 31, v86
	v_ashrrev_i32_e32 v89, 31, v88
	v_lshlrev_b64 v[32:33], 13, v[32:33]
	v_lshlrev_b64 v[38:39], 13, v[38:39]
	v_lshlrev_b64 v[40:41], 13, v[40:41]
	v_lshlrev_b64 v[50:51], 13, v[50:51]
	v_lshlrev_b64 v[52:53], 13, v[52:53]
	v_lshlrev_b64 v[54:55], 13, v[54:55]
	v_lshlrev_b64 v[56:57], 13, v[56:57]
	v_lshl_add_u64 v[90:91], s[4:5], 2, v[8:9]
	v_lshlrev_b64 v[20:21], 13, v[20:21]
	v_lshlrev_b64 v[22:23], 13, v[22:23]
	v_lshlrev_b64 v[24:25], 13, v[24:25]
	v_lshlrev_b64 v[30:31], 13, v[30:31]
	v_lshlrev_b64 v[42:43], 13, v[42:43]
	v_lshlrev_b64 v[44:45], 13, v[44:45]
	v_lshlrev_b64 v[46:47], 13, v[46:47]
	v_lshlrev_b64 v[48:49], 13, v[48:49]
	v_lshlrev_b64 v[58:59], 13, v[58:59]
	v_lshlrev_b64 v[60:61], 13, v[60:61]
	v_lshlrev_b64 v[62:63], 13, v[62:63]
	v_lshlrev_b64 v[64:65], 13, v[64:65]
	v_lshlrev_b64 v[66:67], 13, v[66:67]
	v_lshlrev_b64 v[68:69], 13, v[68:69]
	v_lshlrev_b64 v[70:71], 13, v[70:71]
	v_lshlrev_b64 v[72:73], 13, v[72:73]
	v_lshlrev_b64 v[74:75], 13, v[74:75]
	v_lshlrev_b64 v[76:77], 13, v[76:77]
	v_lshlrev_b64 v[78:79], 13, v[78:79]
	v_lshlrev_b64 v[80:81], 13, v[80:81]
	v_lshlrev_b64 v[82:83], 13, v[82:83]
	v_lshlrev_b64 v[84:85], 13, v[84:85]
	v_lshlrev_b64 v[86:87], 13, v[86:87]
	v_lshlrev_b64 v[88:89], 13, v[88:89]
	v_lshl_add_u64 v[18:19], v[90:91], 0, v[18:19]
	v_lshl_add_u64 v[32:33], v[90:91], 0, v[32:33]
	v_lshl_add_u64 v[38:39], v[90:91], 0, v[38:39]
	v_lshl_add_u64 v[40:41], v[90:91], 0, v[40:41]
	v_lshl_add_u64 v[50:51], v[90:91], 0, v[50:51]
	v_lshl_add_u64 v[52:53], v[90:91], 0, v[52:53]
	v_lshl_add_u64 v[54:55], v[90:91], 0, v[54:55]
	v_lshl_add_u64 v[56:57], v[90:91], 0, v[56:57]
	v_lshl_add_u64 v[20:21], v[90:91], 0, v[20:21]
	v_lshl_add_u64 v[22:23], v[90:91], 0, v[22:23]
	v_lshl_add_u64 v[24:25], v[90:91], 0, v[24:25]
	v_lshl_add_u64 v[30:31], v[90:91], 0, v[30:31]
	v_lshl_add_u64 v[42:43], v[90:91], 0, v[42:43]
	v_lshl_add_u64 v[44:45], v[90:91], 0, v[44:45]
	v_lshl_add_u64 v[46:47], v[90:91], 0, v[46:47]
	v_lshl_add_u64 v[48:49], v[90:91], 0, v[48:49]
	v_lshl_add_u64 v[58:59], v[90:91], 0, v[58:59]
	v_lshl_add_u64 v[60:61], v[90:91], 0, v[60:61]
	v_lshl_add_u64 v[62:63], v[90:91], 0, v[62:63]
	v_lshl_add_u64 v[64:65], v[90:91], 0, v[64:65]
	v_lshl_add_u64 v[66:67], v[90:91], 0, v[66:67]
	v_lshl_add_u64 v[68:69], v[90:91], 0, v[68:69]
	v_lshl_add_u64 v[70:71], v[90:91], 0, v[70:71]
	v_lshl_add_u64 v[72:73], v[90:91], 0, v[72:73]
	v_lshl_add_u64 v[74:75], v[90:91], 0, v[74:75]
	v_lshl_add_u64 v[76:77], v[90:91], 0, v[76:77]
	v_lshl_add_u64 v[78:79], v[90:91], 0, v[78:79]
	v_lshl_add_u64 v[80:81], v[90:91], 0, v[80:81]
	v_lshl_add_u64 v[82:83], v[90:91], 0, v[82:83]
	v_lshl_add_u64 v[84:85], v[90:91], 0, v[84:85]
	v_lshl_add_u64 v[86:87], v[90:91], 0, v[86:87]
	v_lshl_add_u64 v[88:89], v[90:91], 0, v[88:89]
	global_load_dword v27, v[18:19], off nt
	global_load_dword v29, v[20:21], off nt
	global_load_dword v35, v[22:23], off nt
	global_load_dword v37, v[24:25], off nt
	global_load_dword v90, v[30:31], off nt
	global_load_dword v91, v[32:33], off nt
	global_load_dword v92, v[38:39], off nt
	global_load_dword v93, v[40:41], off nt
	global_load_dword v94, v[42:43], off nt
	global_load_dword v95, v[44:45], off nt
	global_load_dword v96, v[46:47], off nt
	global_load_dword v97, v[48:49], off nt
	global_load_dword v98, v[50:51], off nt
	global_load_dword v99, v[52:53], off nt
	global_load_dword v100, v[54:55], off nt
	global_load_dword v32, v[56:57], off nt
	global_load_dword v33, v[58:59], off nt
	global_load_dword v38, v[60:61], off nt
	global_load_dword v39, v[62:63], off nt
	global_load_dword v40, v[64:65], off nt
	global_load_dword v41, v[66:67], off nt
	global_load_dword v50, v[68:69], off nt
	global_load_dword v51, v[70:71], off nt
	global_load_dword v52, v[72:73], off nt
	global_load_dword v53, v[74:75], off nt
	global_load_dword v54, v[76:77], off nt
	global_load_dword v55, v[78:79], off nt
	global_load_dword v101, v[80:81], off nt
	global_load_dword v102, v[82:83], off nt
	global_load_dword v103, v[84:85], off nt
	global_load_dword v56, v[86:87], off nt
	global_load_dword v57, v[88:89], off nt
	s_mul_i32 s8, s8, 0xff500000
	v_add_u32_e32 v20, s8, v5
	s_ashr_i32 s1, s0, 31
	v_add_u32_e32 v22, 0xb000, v20
	v_add_u32_e32 v24, 0x16000, v20
	v_add_u32_e32 v30, 0x21000, v20
	v_lshl_add_u64 v[18:19], s[0:1], 1, v[6:7]
	v_ashrrev_i32_e32 v23, 31, v22
	v_ashrrev_i32_e32 v25, 31, v24
	v_ashrrev_i32_e32 v31, 31, v30
	s_waitcnt vmcnt(30)
; #define LAS __attribute__((address_space(3)))
; __device__ __forceinline__ unsigned pk2(float lo, float hi) { const f32x2 v = {lo, hi}; return __builtin_bit_cast(unsigned, __builtin_convertvector(v, hbf2)); }
; __device__ __forceinline__ void tr_item(const float* __restrict__ W, int K, int Nsrc, int col0, int nvalid, const float* __restrict__ gain, bf16_t* WT, int drow0, int k0, LAS float* scr, int lane) {
;     ...
;     for (int i = 0; i < 32; ++i) { const int kk = 2 * i + (lane >> 5), n = lane & 31; float x = v[i]; if (gain) x *= gain[k0 + kk]; scr[kk * 33 + n] = x; }
;     const int c = lane & 7;
; #pragma unroll
;     for (int j = 0; j < 4; ++j) { const int n = (lane >> 3) + 8 * j; const LAS float* s = scr + (8 * c) * 33 + n;
;         u32x4 o; o.x = pk2(s[0 * 33], s[1 * 33]); o.y = pk2(s[2 * 33], s[3 * 33]); o.z = pk2(s[4 * 33], s[5 * 33]); o.w = pk2(s[6 * 33], s[7 * 33]);
;         *(u32x4*)(WT + (size_t)(drow0 + n) * K + k0 + 8 * c) = o; }
	ds_write2_b32 v10, v27, v29 offset1:66
	s_waitcnt vmcnt(28)
	ds_write2_b32 v10, v35, v37 offset0:132 offset1:198
	s_waitcnt vmcnt(26)
	ds_write2_b32 v11, v90, v91 offset0:8 offset1:74
	s_waitcnt vmcnt(24)
	ds_write2_b32 v11, v92, v93 offset0:140 offset1:206
	s_waitcnt vmcnt(22)
	ds_write2_b32 v12, v94, v95 offset0:16 offset1:82
	s_waitcnt vmcnt(20)
	ds_write2_b32 v12, v96, v97 offset0:148 offset1:214
	s_waitcnt vmcnt(18)
	ds_write2_b32 v13, v98, v99 offset0:24 offset1:90
	s_waitcnt vmcnt(16)
	ds_write2_b32 v13, v100, v32 offset0:156 offset1:222
	s_waitcnt vmcnt(14)
	ds_write2_b32 v14, v33, v38 offset0:32 offset1:98
	s_waitcnt vmcnt(12)
	ds_write2_b32 v14, v39, v40 offset0:164 offset1:230
	s_waitcnt vmcnt(10)
	ds_write2_b32 v15, v41, v50 offset0:40 offset1:106
	s_waitcnt vmcnt(8)
	ds_write2_b32 v15, v51, v52 offset0:172 offset1:238
	s_waitcnt vmcnt(6)
	ds_write2_b32 v16, v53, v54 offset0:48 offset1:114
	s_waitcnt vmcnt(4)
	ds_write2_b32 v16, v55, v101 offset0:180 offset1:246
	s_waitcnt vmcnt(2)
	ds_write2_b32 v17, v102, v103 offset0:56 offset1:122
	s_waitcnt vmcnt(0)
	ds_write2_b32 v17, v56, v57 offset0:188 offset1:254
	v_lshl_add_u64 v[44:45], v[22:23], 1, v[18:19]
	v_lshl_add_u64 v[46:47], v[24:25], 1, v[18:19]
	v_lshl_add_u64 v[48:49], v[30:31], 1, v[18:19]
	ds_read2_b32 v[22:23], v3 offset0:33 offset1:41
	ds_read2_b32 v[24:25], v3 offset1:8
	ds_read2_b32 v[30:31], v3 offset0:66 offset1:74
	ds_read2_b32 v[32:33], v3 offset0:99 offset1:107
	ds_read2_b32 v[38:39], v3 offset0:132 offset1:140
	ds_read2_b32 v[40:41], v3 offset0:165 offset1:173
	ds_read2_b32 v[50:51], v3 offset0:198 offset1:206
	ds_read2_b32 v[52:53], v3 offset0:231 offset1:239
	ds_read2_b32 v[54:55], v3 offset0:16 offset1:24
	ds_read2_b32 v[56:57], v3 offset0:49 offset1:57
	ds_read2_b32 v[58:59], v3 offset0:82 offset1:90
	ds_read2_b32 v[60:61], v3 offset0:115 offset1:123
	ds_read2_b32 v[62:63], v3 offset0:148 offset1:156
	ds_read2_b32 v[64:65], v3 offset0:181 offset1:189
	ds_read2_b32 v[66:67], v3 offset0:214 offset1:222
	ds_read2_b32 v[68:69], v3 offset0:247 offset1:255
	s_add_i32 s7, s7, s62
	s_add_i32 s3, s3, s6
	v_ashrrev_i32_e32 v21, 31, v20
	v_add_u32_e32 v5, s34, v5
	v_lshl_add_u64 v[42:43], v[20:21], 1, v[18:19]
	s_cmpk_lt_i32 s7, 0x1600
	s_waitcnt lgkmcnt(14)
	v_cvt_pk_bf16_f32 v18, v24, v22
	s_waitcnt lgkmcnt(12)
	v_cvt_pk_bf16_f32 v19, v30, v32
	s_waitcnt lgkmcnt(10)
	v_cvt_pk_bf16_f32 v20, v38, v40
	s_waitcnt lgkmcnt(8)
	v_cvt_pk_bf16_f32 v21, v50, v52
	v_cvt_pk_bf16_f32 v22, v25, v23
	v_cvt_pk_bf16_f32 v23, v31, v33
	v_cvt_pk_bf16_f32 v24, v39, v41
	v_cvt_pk_bf16_f32 v25, v51, v53
	s_waitcnt lgkmcnt(6)
	v_cvt_pk_bf16_f32 v30, v54, v56
	s_waitcnt lgkmcnt(4)
	v_cvt_pk_bf16_f32 v31, v58, v60
	s_waitcnt lgkmcnt(2)
	v_cvt_pk_bf16_f32 v32, v62, v64
	s_waitcnt lgkmcnt(0)
	v_cvt_pk_bf16_f32 v33, v66, v68
	v_cvt_pk_bf16_f32 v38, v55, v57
	v_cvt_pk_bf16_f32 v39, v59, v61
	v_cvt_pk_bf16_f32 v40, v63, v65
	v_cvt_pk_bf16_f32 v41, v67, v69
	global_store_dwordx4 v[42:43], v[18:21], off
	global_store_dwordx4 v[44:45], v[22:25], off
	global_store_dwordx4 v[46:47], v[30:33], off
	global_store_dwordx4 v[48:49], v[38:41], off
	s_cbranch_scc1 .LBB0_43

; __device__ __forceinline__ void tr_item(const float* __restrict__ W, int K, int Nsrc, int col0, int nvalid, const float* __restrict__ gain, bf16_t* WT, int drow0, int k0, LAS float* scr, int lane) {
;     ...
;     for (int i = 0; i < 32; ++i) { const int kk = 2 * i + (lane >> 5), n = lane & 31; v[i] = 0.f; if (n < nvalid) v[i] = W[(size_t)(k0 + kk) * Nsrc + col0 + n]; }
; #pragma unroll
;     for (int i = 0; i < 32; ++i) { const int kk = 2 * i + (lane >> 5), n = lane & 31; float x = v[i]; if (gain) x *= gain[k0 + kk]; scr[kk * 33 + n] = x; }
; __device__ __forceinline__ void conv_job(int kind, const float* W, const float* W2, int K, int Nsrc, int Ndst, const float* gain, bf16_t* WT, LAS float* scr, int gw, int NGW, int lane) {
;     ...
;         else if (kind == 2) { if (d0 < 7168) col0 = d0; else if (d0 < 11264) col0 = d0 + 16; else if (d0 == 11264) { col0 = 7168; nvalid = 16; } else { col0 = 0; nvalid = 0; } }
.LBB0_54:
	s_lshl_b32 s10, s21, 6
	s_ashr_i32 s21, s20, 31
	v_or_b32_e32 v10, s10, v2
	v_lshl_add_u64 v[12:13], s[20:21], 2, v[8:9]
	v_mov_b32_e32 v47, 0
	v_mov_b32_e32 v50, 0
	s_and_saveexec_b64 s[20:21], s[6:7]
	s_cbranch_execz .LBB0_56
	v_mad_i64_i32 v[16:17], s[30:31], v10, s26, v[12:13]
	global_load_dword v50, v[16:17], off nt
.LBB0_56:
	s_or_b64 exec, exec, s[20:21]
	s_and_saveexec_b64 s[20:21], s[6:7]
	s_cbranch_execz .LBB0_58
	v_or_b32_e32 v11, 2, v10
	v_mad_i64_i32 v[16:17], s[30:31], v11, s26, v[12:13]
	global_load_dword v47, v[16:17], off nt
.LBB0_58:
	s_or_b64 exec, exec, s[20:21]
	v_mov_b32_e32 v45, 0
	v_mov_b32_e32 v49, 0
	s_and_saveexec_b64 s[20:21], s[6:7]
	s_cbranch_execz .LBB0_60
	v_or_b32_e32 v11, 4, v10
	v_mad_i64_i32 v[16:17], s[30:31], v11, s26, v[12:13]
	global_load_dword v49, v[16:17], off nt
.LBB0_60:
	s_or_b64 exec, exec, s[20:21]
	s_and_saveexec_b64 s[20:21], s[6:7]
	s_cbranch_execz .LBB0_62
	v_or_b32_e32 v11, 6, v10
	v_mad_i64_i32 v[16:17], s[30:31], v11, s26, v[12:13]
	global_load_dword v45, v[16:17], off nt
.LBB0_62:
	s_or_b64 exec, exec, s[20:21]
	v_mov_b32_e32 v43, 0
	v_mov_b32_e32 v48, 0
	s_and_saveexec_b64 s[20:21], s[6:7]
	s_cbranch_execz .LBB0_64
	v_or_b32_e32 v11, 8, v10
	v_mad_i64_i32 v[16:17], s[30:31], v11, s26, v[12:13]
	global_load_dword v48, v[16:17], off nt
.LBB0_64:
	s_or_b64 exec, exec, s[20:21]
	s_and_saveexec_b64 s[20:21], s[6:7]
	s_cbranch_execz .LBB0_66
	v_or_b32_e32 v11, 10, v10
	v_mad_i64_i32 v[16:17], s[30:31], v11, s26, v[12:13]
	global_load_dword v43, v[16:17], off nt
.LBB0_66:
	s_or_b64 exec, exec, s[20:21]
	v_mov_b32_e32 v41, 0
	v_mov_b32_e32 v46, 0
	s_and_saveexec_b64 s[20:21], s[6:7]
	s_cbranch_execz .LBB0_68
	v_or_b32_e32 v11, 12, v10
	v_mad_i64_i32 v[16:17], s[30:31], v11, s26, v[12:13]
	global_load_dword v46, v[16:17], off nt
.LBB0_68:
	s_or_b64 exec, exec, s[20:21]
	s_and_saveexec_b64 s[20:21], s[6:7]
	s_cbranch_execz .LBB0_70
	v_or_b32_e32 v11, 14, v10
	v_mad_i64_i32 v[16:17], s[30:31], v11, s26, v[12:13]
	global_load_dword v41, v[16:17], off nt
.LBB0_70:
	s_or_b64 exec, exec, s[20:21]
	v_mov_b32_e32 v39, 0
	v_mov_b32_e32 v44, 0
	s_and_saveexec_b64 s[20:21], s[6:7]
	s_cbranch_execz .LBB0_72
	v_or_b32_e32 v11, 16, v10
	v_mad_i64_i32 v[16:17], s[30:31], v11, s26, v[12:13]
	global_load_dword v44, v[16:17], off nt
.LBB0_72:
	s_or_b64 exec, exec, s[20:21]
	s_and_saveexec_b64 s[20:21], s[6:7]
	s_cbranch_execz .LBB0_74
	v_or_b32_e32 v11, 18, v10
	v_mad_i64_i32 v[16:17], s[30:31], v11, s26, v[12:13]
	global_load_dword v39, v[16:17], off nt
.LBB0_74:
	s_or_b64 exec, exec, s[20:21]
	v_mov_b32_e32 v37, 0
	v_mov_b32_e32 v42, 0
	s_and_saveexec_b64 s[20:21], s[6:7]
	s_cbranch_execz .LBB0_76
	v_or_b32_e32 v11, 20, v10
	v_mad_i64_i32 v[16:17], s[30:31], v11, s26, v[12:13]
	global_load_dword v42, v[16:17], off nt
.LBB0_76:
	s_or_b64 exec, exec, s[20:21]
	s_and_saveexec_b64 s[20:21], s[6:7]
	s_cbranch_execz .LBB0_78
	v_or_b32_e32 v11, 22, v10
	v_mad_i64_i32 v[16:17], s[30:31], v11, s26, v[12:13]
	global_load_dword v37, v[16:17], off nt
.LBB0_78:
	s_or_b64 exec, exec, s[20:21]
	v_mov_b32_e32 v33, 0
	v_mov_b32_e32 v40, 0
	s_and_saveexec_b64 s[20:21], s[6:7]
	s_cbranch_execz .LBB0_80
	v_or_b32_e32 v11, 24, v10
	v_mad_i64_i32 v[16:17], s[30:31], v11, s26, v[12:13]
	global_load_dword v40, v[16:17], off nt
.LBB0_80:
	s_or_b64 exec, exec, s[20:21]
	s_and_saveexec_b64 s[20:21], s[6:7]
	s_cbranch_execz .LBB0_82
	v_or_b32_e32 v11, 26, v10
	v_mad_i64_i32 v[16:17], s[30:31], v11, s26, v[12:13]
	global_load_dword v33, v[16:17], off nt
.LBB0_82:
	s_or_b64 exec, exec, s[20:21]
	v_mov_b32_e32 v31, 0
	v_mov_b32_e32 v38, 0
	s_and_saveexec_b64 s[20:21], s[6:7]
	s_cbranch_execz .LBB0_84
	v_or_b32_e32 v11, 28, v10
	v_mad_i64_i32 v[16:17], s[30:31], v11, s26, v[12:13]
	global_load_dword v38, v[16:17], off nt
.LBB0_84:
	s_or_b64 exec, exec, s[20:21]
	s_and_saveexec_b64 s[20:21], s[6:7]
	s_cbranch_execz .LBB0_86
	v_or_b32_e32 v11, 30, v10
	v_mad_i64_i32 v[16:17], s[30:31], v11, s26, v[12:13]
	global_load_dword v31, v[16:17], off nt
.LBB0_86:
	s_or_b64 exec, exec, s[20:21]
	v_mov_b32_e32 v29, 0
	v_mov_b32_e32 v35, 0
	s_and_saveexec_b64 s[20:21], s[6:7]
	s_cbranch_execz .LBB0_88
	v_or_b32_e32 v11, 32, v10
	v_mad_i64_i32 v[16:17], s[30:31], v11, s26, v[12:13]
	global_load_dword v35, v[16:17], off nt
; __device__ __forceinline__ void tr_item(const float* __restrict__ W, int K, int Nsrc, int col0, int nvalid, const float* __restrict__ gain, bf16_t* WT, int drow0, int k0, LAS float* scr, int lane) {
;     ...
;     for (int i = 0; i < 32; ++i) { const int kk = 2 * i + (lane >> 5), n = lane & 31; v[i] = 0.f; if (n < nvalid) v[i] = W[(size_t)(k0 + kk) * Nsrc + col0 + n]; }
; #pragma unroll
;     for (int i = 0; i < 32; ++i) { const int kk = 2 * i + (lane >> 5), n = lane & 31; float x = v[i]; if (gain) x *= gain[k0 + kk]; scr[kk * 33 + n] = x; }
; __device__ __forceinline__ void conv_job(int kind, const float* W, const float* W2, int K, int Nsrc, int Ndst, const float* gain, bf16_t* WT, LAS float* scr, int gw, int NGW, int lane) {
;     ...
;         else if (kind == 2) { if (d0 < 7168) col0 = d0; else if (d0 < 11264) col0 = d0 + 16; else if (d0 == 11264) { col0 = 7168; nvalid = 16; } else { col0 = 0; nvalid = 0; } }
.LBB0_88:
	s_or_b64 exec, exec, s[20:21]
	s_and_saveexec_b64 s[20:21], s[6:7]
	s_cbranch_execz .LBB0_90
	v_or_b32_e32 v11, 34, v10
	v_mad_i64_i32 v[16:17], s[30:31], v11, s26, v[12:13]
	global_load_dword v29, v[16:17], off nt
.LBB0_90:
	s_or_b64 exec, exec, s[20:21]
	v_mov_b32_e32 v25, 0
	v_mov_b32_e32 v32, 0
	s_and_saveexec_b64 s[20:21], s[6:7]
	s_cbranch_execz .LBB0_92
	v_or_b32_e32 v11, 36, v10
	v_mad_i64_i32 v[16:17], s[30:31], v11, s26, v[12:13]
	global_load_dword v32, v[16:17], off nt
.LBB0_92:
	s_or_b64 exec, exec, s[20:21]
	s_and_saveexec_b64 s[20:21], s[6:7]
	s_cbranch_execz .LBB0_94
	v_or_b32_e32 v11, 38, v10
	v_mad_i64_i32 v[16:17], s[30:31], v11, s26, v[12:13]
	global_load_dword v25, v[16:17], off nt
.LBB0_94:
	s_or_b64 exec, exec, s[20:21]
	v_mov_b32_e32 v23, 0
	v_mov_b32_e32 v30, 0
	s_and_saveexec_b64 s[20:21], s[6:7]
	s_cbranch_execz .LBB0_96
	v_or_b32_e32 v11, 40, v10
	v_mad_i64_i32 v[16:17], s[30:31], v11, s26, v[12:13]
	global_load_dword v30, v[16:17], off nt
.LBB0_96:
	s_or_b64 exec, exec, s[20:21]
	s_and_saveexec_b64 s[20:21], s[6:7]
	s_cbranch_execz .LBB0_98
	v_or_b32_e32 v11, 42, v10
	v_mad_i64_i32 v[16:17], s[30:31], v11, s26, v[12:13]
	global_load_dword v23, v[16:17], off nt
.LBB0_98:
	s_or_b64 exec, exec, s[20:21]
	v_mov_b32_e32 v21, 0
	v_mov_b32_e32 v27, 0
	s_and_saveexec_b64 s[20:21], s[6:7]
	s_cbranch_execz .LBB0_100
	v_or_b32_e32 v11, 44, v10
	v_mad_i64_i32 v[16:17], s[30:31], v11, s26, v[12:13]
	global_load_dword v27, v[16:17], off nt
.LBB0_100:
	s_or_b64 exec, exec, s[20:21]
	s_and_saveexec_b64 s[20:21], s[6:7]
	s_cbranch_execz .LBB0_102
	v_or_b32_e32 v11, 46, v10
	v_mad_i64_i32 v[16:17], s[30:31], v11, s26, v[12:13]
	global_load_dword v21, v[16:17], off nt
.LBB0_102:
	s_or_b64 exec, exec, s[20:21]
	v_mov_b32_e32 v18, 0
	v_mov_b32_e32 v24, 0
	s_and_saveexec_b64 s[20:21], s[6:7]
	s_cbranch_execz .LBB0_104
	v_or_b32_e32 v11, 48, v10
	v_mad_i64_i32 v[16:17], s[30:31], v11, s26, v[12:13]
	global_load_dword v24, v[16:17], off nt
.LBB0_104:
	s_or_b64 exec, exec, s[20:21]
	s_and_saveexec_b64 s[20:21], s[6:7]
	s_cbranch_execz .LBB0_106
	v_or_b32_e32 v11, 50, v10
	v_mad_i64_i32 v[16:17], s[30:31], v11, s26, v[12:13]
	global_load_dword v18, v[16:17], off nt
.LBB0_106:
	s_or_b64 exec, exec, s[20:21]
	v_mov_b32_e32 v17, 0
	v_mov_b32_e32 v22, 0
	s_and_saveexec_b64 s[20:21], s[6:7]
	s_cbranch_execz .LBB0_108
	v_or_b32_e32 v11, 52, v10
	v_mad_i64_i32 v[52:53], s[30:31], v11, s26, v[12:13]
	global_load_dword v22, v[52:53], off nt
.LBB0_108:
	s_or_b64 exec, exec, s[20:21]
	s_and_saveexec_b64 s[20:21], s[6:7]
	s_cbranch_execz .LBB0_110
	v_or_b32_e32 v11, 54, v10
	v_mad_i64_i32 v[16:17], s[30:31], v11, s26, v[12:13]
	global_load_dword v17, v[16:17], off nt
.LBB0_110:
	s_or_b64 exec, exec, s[20:21]
	v_mov_b32_e32 v16, 0
	v_mov_b32_e32 v20, 0
	s_and_saveexec_b64 s[20:21], s[6:7]
	s_cbranch_execz .LBB0_112
	v_or_b32_e32 v11, 56, v10
	v_mad_i64_i32 v[52:53], s[30:31], v11, s26, v[12:13]
	global_load_dword v20, v[52:53], off nt
.LBB0_112:
	s_or_b64 exec, exec, s[20:21]
	s_and_saveexec_b64 s[20:21], s[6:7]
	s_cbranch_execz .LBB0_114
	v_or_b32_e32 v11, 58, v10
	v_mad_i64_i32 v[52:53], s[30:31], v11, s26, v[12:13]
	global_load_dword v16, v[52:53], off nt
.LBB0_114:
	s_or_b64 exec, exec, s[20:21]
	v_mov_b32_e32 v15, 0
	v_mov_b32_e32 v19, 0
	s_and_saveexec_b64 s[20:21], s[6:7]
	s_cbranch_execz .LBB0_116
	v_or_b32_e32 v11, 60, v10
	v_mad_i64_i32 v[52:53], s[30:31], v11, s26, v[12:13]
	global_load_dword v19, v[52:53], off nt
.LBB0_116:
	s_or_b64 exec, exec, s[20:21]
	s_and_saveexec_b64 s[20:21], s[6:7]
	s_cbranch_execz .LBB0_118
	v_or_b32_e32 v11, 62, v10
	v_mad_i64_i32 v[12:13], s[6:7], v11, s26, v[12:13]
	global_load_dword v15, v[12:13], off nt
.LBB0_118:
	s_or_b64 exec, exec, s[20:21]
	v_cndmask_b32_e64 v11, 0, 1, s[0:1]
	v_cmp_ne_u32_e64 s[6:7], 1, v11
	s_andn2_b64 vcc, exec, s[0:1]
	s_cbranch_vccnz .LBB0_120
	v_ashrrev_i32_e32 v11, 31, v10
	v_lshl_add_u64 v[10:11], v[10:11], 2, s[8:9]
	global_load_dword v10, v[10:11], off nt
	s_waitcnt vmcnt(0)
	v_mul_f32_e32 v50, v50, v10

; __device__ __forceinline__ void tr_item(const float* __restrict__ W, int K, int Nsrc, int col0, int nvalid, const float* __restrict__ gain, bf16_t* WT, int drow0, int k0, LAS float* scr, int lane) {
;     ...
;     for (int i = 0; i < 32; ++i) { const int kk = 2 * i + (lane >> 5), n = lane & 31; v[i] = 0.f; if (n < nvalid) v[i] = W[(size_t)(k0 + kk) * Nsrc + col0 + n]; }
; __device__ __forceinline__ void conv_job(int kind, const float* W, const float* W2, int K, int Nsrc, int Ndst, const float* gain, bf16_t* WT, LAS float* scr, int gw, int NGW, int lane) {
;     const int nb = Ndst / 32, nitems = (K / 64) * nb;
;     for (int it = gw; it < nitems; it += NGW) {
;         const int kb = it / nb, db = it % nb, d0 = db * 32, k0 = kb * 64; const float* src = W; int col0 = d0, nvalid = 32;
.LBB0_185:
	s_ashr_i32 s4, s10, 31
	s_lshr_b32 s4, s4, 26
	s_add_i32 s4, s10, s4
	s_lshl_b32 s5, s4, 5
	s_andn2_b32 s4, s4, 63
	s_and_b32 s5, s5, 0xfffff800
	v_or_b32_e32 v18, s4, v2
	s_sub_i32 s6, s9, s5
	v_or_b32_e32 v32, 10, v18
	v_or_b32_e32 v38, 12, v18
	v_or_b32_e32 v40, 14, v18
	v_or_b32_e32 v50, 24, v18
	v_or_b32_e32 v52, 26, v18
	v_or_b32_e32 v54, 28, v18
	v_or_b32_e32 v56, 30, v18
	v_ashrrev_i32_e32 v19, 31, v18
	v_or_b32_e32 v20, 2, v18
	v_or_b32_e32 v22, 4, v18
	v_or_b32_e32 v24, 6, v18
	v_or_b32_e32 v30, 8, v18
	v_or_b32_e32 v42, 16, v18
	v_or_b32_e32 v44, 18, v18
	v_or_b32_e32 v46, 20, v18
	v_or_b32_e32 v48, 22, v18
	v_or_b32_e32 v58, 32, v18
	v_or_b32_e32 v60, 34, v18
	v_or_b32_e32 v62, 36, v18
	v_or_b32_e32 v64, 38, v18
	v_or_b32_e32 v66, 40, v18
	v_or_b32_e32 v68, 42, v18
	v_or_b32_e32 v70, 44, v18
	v_or_b32_e32 v72, 46, v18
	v_or_b32_e32 v74, 48, v18
	v_or_b32_e32 v76, 50, v18
	v_or_b32_e32 v78, 52, v18
	v_or_b32_e32 v80, 54, v18
	v_or_b32_e32 v82, 56, v18
	v_or_b32_e32 v84, 58, v18
	v_or_b32_e32 v86, 60, v18
	v_or_b32_e32 v88, 62, v18
	s_ashr_i32 s7, s6, 31
	v_ashrrev_i32_e32 v33, 31, v32
	v_ashrrev_i32_e32 v39, 31, v38
	v_ashrrev_i32_e32 v41, 31, v40
	v_ashrrev_i32_e32 v51, 31, v50
	v_ashrrev_i32_e32 v53, 31, v52
	v_ashrrev_i32_e32 v55, 31, v54
	v_ashrrev_i32_e32 v57, 31, v56
	v_lshlrev_b64 v[18:19], 13, v[18:19]
	v_ashrrev_i32_e32 v21, 31, v20
	v_ashrrev_i32_e32 v23, 31, v22
	v_ashrrev_i32_e32 v25, 31, v24
	v_ashrrev_i32_e32 v31, 31, v30
	v_ashrrev_i32_e32 v43, 31, v42
	v_ashrrev_i32_e32 v45, 31, v44
	v_ashrrev_i32_e32 v47, 31, v46
	v_ashrrev_i32_e32 v49, 31, v48
	v_ashrrev_i32_e32 v59, 31, v58
	v_ashrrev_i32_e32 v61, 31, v60
	v_ashrrev_i32_e32 v63, 31, v62
	v_ashrrev_i32_e32 v65, 31, v64
	v_ashrrev_i32_e32 v67, 31, v66
	v_ashrrev_i32_e32 v69, 31, v68
	v_ashrrev_i32_e32 v71, 31, v70
	v_ashrrev_i32_e32 v73, 31, v72
	v_ashrrev_i32_e32 v75, 31, v74
	v_ashrrev_i32_e32 v77, 31, v76
	v_ashrrev_i32_e32 v79, 31, v78
	v_ashrrev_i32_e32 v81, 31, v80
	v_ashrrev_i32_e32 v83, 31, v82
	v_ashrrev_i32_e32 v85, 31, v84
	v_ashrrev_i32_e32 v87, 31, v86
	v_ashrrev_i32_e32 v89, 31, v88
	v_lshl_add_u64 v[90:91], s[6:7], 2, v[10:11]
	v_lshlrev_b64 v[32:33], 13, v[32:33]
	v_lshlrev_b64 v[38:39], 13, v[38:39]
	v_lshlrev_b64 v[40:41], 13, v[40:41]
	v_lshlrev_b64 v[50:51], 13, v[50:51]
	v_lshlrev_b64 v[52:53], 13, v[52:53]
	v_lshlrev_b64 v[54:55], 13, v[54:55]
	v_lshlrev_b64 v[56:57], 13, v[56:57]
	v_lshlrev_b64 v[20:21], 13, v[20:21]
	v_lshlrev_b64 v[22:23], 13, v[22:23]
	v_lshlrev_b64 v[24:25], 13, v[24:25]
	v_lshlrev_b64 v[30:31], 13, v[30:31]
	v_lshlrev_b64 v[42:43], 13, v[42:43]
	v_lshlrev_b64 v[44:45], 13, v[44:45]
	v_lshlrev_b64 v[46:47], 13, v[46:47]
	v_lshlrev_b64 v[48:49], 13, v[48:49]
	v_lshlrev_b64 v[58:59], 13, v[58:59]
	v_lshlrev_b64 v[60:61], 13, v[60:61]
	v_lshlrev_b64 v[62:63], 13, v[62:63]
	v_lshlrev_b64 v[64:65], 13, v[64:65]
	v_lshlrev_b64 v[66:67], 13, v[66:67]
	v_lshlrev_b64 v[68:69], 13, v[68:69]
	v_lshlrev_b64 v[70:71], 13, v[70:71]
	v_lshlrev_b64 v[72:73], 13, v[72:73]
	v_lshlrev_b64 v[74:75], 13, v[74:75]
	v_lshlrev_b64 v[76:77], 13, v[76:77]
	v_lshlrev_b64 v[78:79], 13, v[78:79]
	v_lshlrev_b64 v[80:81], 13, v[80:81]
	v_lshlrev_b64 v[82:83], 13, v[82:83]
	v_lshlrev_b64 v[84:85], 13, v[84:85]
	v_lshlrev_b64 v[86:87], 13, v[86:87]
	v_lshlrev_b64 v[88:89], 13, v[88:89]
	v_lshl_add_u64 v[18:19], v[90:91], 0, v[18:19]
	v_lshl_add_u64 v[32:33], v[90:91], 0, v[32:33]
	v_lshl_add_u64 v[38:39], v[90:91], 0, v[38:39]
	v_lshl_add_u64 v[40:41], v[90:91], 0, v[40:41]
	v_lshl_add_u64 v[50:51], v[90:91], 0, v[50:51]
	v_lshl_add_u64 v[52:53], v[90:91], 0, v[52:53]
	v_lshl_add_u64 v[54:55], v[90:91], 0, v[54:55]
	v_lshl_add_u64 v[56:57], v[90:91], 0, v[56:57]
	v_lshl_add_u64 v[20:21], v[90:91], 0, v[20:21]
	v_lshl_add_u64 v[22:23], v[90:91], 0, v[22:23]
	v_lshl_add_u64 v[24:25], v[90:91], 0, v[24:25]
	v_lshl_add_u64 v[30:31], v[90:91], 0, v[30:31]
	v_lshl_add_u64 v[42:43], v[90:91], 0, v[42:43]
	v_lshl_add_u64 v[44:45], v[90:91], 0, v[44:45]
	v_lshl_add_u64 v[46:47], v[90:91], 0, v[46:47]
	v_lshl_add_u64 v[48:49], v[90:91], 0, v[48:49]
	v_lshl_add_u64 v[58:59], v[90:91], 0, v[58:59]
	v_lshl_add_u64 v[60:61], v[90:91], 0, v[60:61]
	v_lshl_add_u64 v[62:63], v[90:91], 0, v[62:63]
	v_lshl_add_u64 v[64:65], v[90:91], 0, v[64:65]
	v_lshl_add_u64 v[66:67], v[90:91], 0, v[66:67]
	v_lshl_add_u64 v[68:69], v[90:91], 0, v[68:69]
	v_lshl_add_u64 v[70:71], v[90:91], 0, v[70:71]
	v_lshl_add_u64 v[72:73], v[90:91], 0, v[72:73]
	v_lshl_add_u64 v[74:75], v[90:91], 0, v[74:75]
	v_lshl_add_u64 v[76:77], v[90:91], 0, v[76:77]
	v_lshl_add_u64 v[78:79], v[90:91], 0, v[78:79]
	v_lshl_add_u64 v[80:81], v[90:91], 0, v[80:81]
	v_lshl_add_u64 v[82:83], v[90:91], 0, v[82:83]
	v_lshl_add_u64 v[84:85], v[90:91], 0, v[84:85]
	v_lshl_add_u64 v[86:87], v[90:91], 0, v[86:87]
	v_lshl_add_u64 v[88:89], v[90:91], 0, v[88:89]
	global_load_dword v27, v[18:19], off nt
	global_load_dword v29, v[20:21], off nt
	global_load_dword v35, v[22:23], off nt
	global_load_dword v37, v[24:25], off nt
	global_load_dword v90, v[30:31], off nt
	global_load_dword v91, v[32:33], off nt
	global_load_dword v92, v[38:39], off nt
	global_load_dword v93, v[40:41], off nt
	global_load_dword v94, v[42:43], off nt
	global_load_dword v95, v[44:45], off nt
	global_load_dword v96, v[46:47], off nt
	global_load_dword v97, v[48:49], off nt
	global_load_dword v98, v[50:51], off nt
	global_load_dword v99, v[52:53], off nt
	global_load_dword v100, v[54:55], off nt
	global_load_dword v32, v[56:57], off nt
	global_load_dword v33, v[58:59], off nt
	global_load_dword v38, v[60:61], off nt
	global_load_dword v39, v[62:63], off nt
	global_load_dword v40, v[64:65], off nt
	global_load_dword v41, v[66:67], off nt
	global_load_dword v50, v[68:69], off nt
	global_load_dword v51, v[70:71], off nt
	global_load_dword v52, v[72:73], off nt
	global_load_dword v53, v[74:75], off nt
	global_load_dword v54, v[76:77], off nt
	global_load_dword v55, v[78:79], off nt
	global_load_dword v101, v[80:81], off nt
	global_load_dword v102, v[82:83], off nt
	global_load_dword v103, v[84:85], off nt
	global_load_dword v56, v[86:87], off nt
	global_load_dword v57, v[88:89], off nt
	v_add_u32_e32 v20, s6, v28
	s_ashr_i32 s5, s4, 31
	v_ashrrev_i32_e32 v21, 31, v20
	v_add_u32_e32 v22, 8, v20
	v_add_u32_e32 v24, 16, v20
	v_add_u32_e32 v30, 24, v20
	v_lshl_add_u64 v[18:19], s[4:5], 1, v[8:9]
	v_lshlrev_b64 v[20:21], 11, v[20:21]
	v_ashrrev_i32_e32 v23, 31, v22
	v_ashrrev_i32_e32 v25, 31, v24
	v_ashrrev_i32_e32 v31, 31, v30
	v_lshl_add_u64 v[42:43], v[18:19], 0, v[20:21]
	v_lshlrev_b64 v[20:21], 11, v[22:23]
	v_lshlrev_b64 v[22:23], 11, v[24:25]
	v_lshlrev_b64 v[24:25], 11, v[30:31]
	s_waitcnt vmcnt(30)
; #define LAS __attribute__((address_space(3)))
; __device__ __forceinline__ unsigned pk2(float lo, float hi) { const f32x2 v = {lo, hi}; return __builtin_bit_cast(unsigned, __builtin_convertvector(v, hbf2)); }
; __device__ __forceinline__ void tr_item(const float* __restrict__ W, int K, int Nsrc, int col0, int nvalid, const float* __restrict__ gain, bf16_t* WT, int drow0, int k0, LAS float* scr, int lane) {
;     ...
;     for (int i = 0; i < 32; ++i) { const int kk = 2 * i + (lane >> 5), n = lane & 31; float x = v[i]; if (gain) x *= gain[k0 + kk]; scr[kk * 33 + n] = x; }
;     const int c = lane & 7;
; #pragma unroll
;     for (int j = 0; j < 4; ++j) { const int n = (lane >> 3) + 8 * j; const LAS float* s = scr + (8 * c) * 33 + n;
;         u32x4 o; o.x = pk2(s[0 * 33], s[1 * 33]); o.y = pk2(s[2 * 33], s[3 * 33]); o.z = pk2(s[4 * 33], s[5 * 33]); o.w = pk2(s[6 * 33], s[7 * 33]);
;         *(u32x4*)(WT + (size_t)(drow0 + n) * K + k0 + 8 * c) = o; }
; __device__ __forceinline__ void conv_job(int kind, const float* W, const float* W2, int K, int Nsrc, int Ndst, const float* gain, bf16_t* WT, LAS float* scr, int gw, int NGW, int lane) {
;     const int nb = Ndst / 32, nitems = (K / 64) * nb;
;     for (int it = gw; it < nitems; it += NGW) {
;         const int kb = it / nb, db = it % nb, d0 = db * 32, k0 = kb * 64; const float* src = W; int col0 = d0, nvalid = 32;
	ds_write2_b32 v12, v27, v29 offset1:66
	s_waitcnt vmcnt(28)
	ds_write2_b32 v12, v35, v37 offset0:132 offset1:198
	s_waitcnt vmcnt(26)
	ds_write2_b32 v5, v90, v91 offset0:8 offset1:74
	s_waitcnt vmcnt(24)
	ds_write2_b32 v5, v92, v93 offset0:140 offset1:206
	s_waitcnt vmcnt(22)
	ds_write2_b32 v7, v94, v95 offset0:16 offset1:82
	s_waitcnt vmcnt(20)
	ds_write2_b32 v7, v96, v97 offset0:148 offset1:214
	s_waitcnt vmcnt(18)
	ds_write2_b32 v13, v98, v99 offset0:24 offset1:90
	s_waitcnt vmcnt(16)
	ds_write2_b32 v13, v100, v32 offset0:156 offset1:222
	s_waitcnt vmcnt(14)
	ds_write2_b32 v14, v33, v38 offset0:32 offset1:98
	s_waitcnt vmcnt(12)
	ds_write2_b32 v14, v39, v40 offset0:164 offset1:230
	s_waitcnt vmcnt(10)
	ds_write2_b32 v15, v41, v50 offset0:40 offset1:106
	s_waitcnt vmcnt(8)
	ds_write2_b32 v15, v51, v52 offset0:172 offset1:238
	s_waitcnt vmcnt(6)
	ds_write2_b32 v16, v53, v54 offset0:48 offset1:114
	s_waitcnt vmcnt(4)
	ds_write2_b32 v16, v55, v101 offset0:180 offset1:246
	s_waitcnt vmcnt(2)
	ds_write2_b32 v17, v102, v103 offset0:56 offset1:122
	s_waitcnt vmcnt(0)
	ds_write2_b32 v17, v56, v57 offset0:188 offset1:254
	v_lshl_add_u64 v[46:47], v[18:19], 0, v[22:23]
	v_lshl_add_u64 v[48:49], v[18:19], 0, v[24:25]
	ds_read2_b32 v[22:23], v3 offset0:33 offset1:41
	ds_read2_b32 v[24:25], v3 offset1:8
	ds_read2_b32 v[30:31], v3 offset0:66 offset1:74
	ds_read2_b32 v[32:33], v3 offset0:99 offset1:107
	ds_read2_b32 v[38:39], v3 offset0:132 offset1:140
	ds_read2_b32 v[40:41], v3 offset0:165 offset1:173
	ds_read2_b32 v[50:51], v3 offset0:198 offset1:206
	ds_read2_b32 v[52:53], v3 offset0:231 offset1:239
	ds_read2_b32 v[54:55], v3 offset0:16 offset1:24
	ds_read2_b32 v[56:57], v3 offset0:49 offset1:57
	ds_read2_b32 v[58:59], v3 offset0:82 offset1:90
	ds_read2_b32 v[60:61], v3 offset0:115 offset1:123
	ds_read2_b32 v[62:63], v3 offset0:148 offset1:156
	ds_read2_b32 v[64:65], v3 offset0:181 offset1:189
	ds_read2_b32 v[66:67], v3 offset0:214 offset1:222
	ds_read2_b32 v[68:69], v3 offset0:247 offset1:255
	s_add_i32 s10, s10, s62
	s_add_i32 s9, s9, s8
	s_cmpk_lt_i32 s10, 0x400
	v_lshl_add_u64 v[44:45], v[18:19], 0, v[20:21]
	s_waitcnt lgkmcnt(14)
	v_cvt_pk_bf16_f32 v18, v24, v22
	s_waitcnt lgkmcnt(12)
	v_cvt_pk_bf16_f32 v19, v30, v32
	s_waitcnt lgkmcnt(10)
	v_cvt_pk_bf16_f32 v20, v38, v40
	s_waitcnt lgkmcnt(8)
	v_cvt_pk_bf16_f32 v21, v50, v52
	v_cvt_pk_bf16_f32 v22, v25, v23
	v_cvt_pk_bf16_f32 v23, v31, v33
	v_cvt_pk_bf16_f32 v24, v39, v41
	v_cvt_pk_bf16_f32 v25, v51, v53
	s_waitcnt lgkmcnt(6)
	v_cvt_pk_bf16_f32 v30, v54, v56
	s_waitcnt lgkmcnt(4)
	v_cvt_pk_bf16_f32 v31, v58, v60
	s_waitcnt lgkmcnt(2)
	v_cvt_pk_bf16_f32 v32, v62, v64
	s_waitcnt lgkmcnt(0)
	v_cvt_pk_bf16_f32 v33, v66, v68
	v_cvt_pk_bf16_f32 v38, v55, v57
	v_cvt_pk_bf16_f32 v39, v59, v61
	v_cvt_pk_bf16_f32 v40, v63, v65
	v_cvt_pk_bf16_f32 v41, v67, v69
	global_store_dwordx4 v[42:43], v[18:21], off
	global_store_dwordx4 v[44:45], v[22:25], off
	global_store_dwordx4 v[46:47], v[30:33], off
	global_store_dwordx4 v[48:49], v[38:41], off
	s_cbranch_scc1 .LBB0_185
	s_load_dwordx2 s[4:5], s[18:19], 0x70
	v_lshlrev_b32_e32 v8, 1, v6
	v_mov_b32_e32 v9, 0
	v_lshl_add_u64 v[6:7], s[14:15], 0, v[8:9]
	s_mov_b64 s[6:7], 0x600000
	v_lshlrev_b32_e32 v8, 2, v4
	v_lshl_add_u64 v[6:7], v[6:7], 0, s[6:7]
	s_waitcnt lgkmcnt(0)
	v_lshl_add_u64 v[4:5], s[4:5], 0, v[8:9]
	s_mov_b32 s9, s2
.LBB0_187:
	s_ashr_i32 s4, s9, 31
	s_lshr_b32 s4, s4, 26
	s_add_i32 s4, s9, s4
	s_lshl_b32 s5, s4, 5
	s_andn2_b32 s4, s4, 63
	s_and_b32 s5, s5, 0xfffff800
	v_or_b32_e32 v8, s4, v2
	s_sub_i32 s6, s3, s5
	v_or_b32_e32 v20, 10, v8
	v_or_b32_e32 v22, 12, v8
	v_or_b32_e32 v24, 14, v8
	v_or_b32_e32 v42, 24, v8
	v_or_b32_e32 v44, 26, v8
	v_or_b32_e32 v46, 28, v8
	v_or_b32_e32 v48, 30, v8
	v_ashrrev_i32_e32 v9, 31, v8
	v_or_b32_e32 v10, 2, v8
	v_or_b32_e32 v14, 4, v8
	v_or_b32_e32 v16, 6, v8
	v_or_b32_e32 v18, 8, v8
	v_or_b32_e32 v30, 16, v8
	v_or_b32_e32 v32, 18, v8
	v_or_b32_e32 v38, 20, v8
	v_or_b32_e32 v40, 22, v8
	v_or_b32_e32 v50, 32, v8
	v_or_b32_e32 v52, 34, v8
	v_or_b32_e32 v54, 36, v8
	v_or_b32_e32 v56, 38, v8
	v_or_b32_e32 v58, 40, v8
	v_or_b32_e32 v60, 42, v8
	v_or_b32_e32 v62, 44, v8
	v_or_b32_e32 v64, 46, v8
	v_or_b32_e32 v66, 48, v8
	v_or_b32_e32 v68, 50, v8
	v_or_b32_e32 v70, 52, v8
	v_or_b32_e32 v72, 54, v8
	v_or_b32_e32 v74, 56, v8
	v_or_b32_e32 v76, 58, v8
	v_or_b32_e32 v78, 60, v8
	v_or_b32_e32 v80, 62, v8
	s_ashr_i32 s7, s6, 31
	v_ashrrev_i32_e32 v21, 31, v20
	v_ashrrev_i32_e32 v23, 31, v22
	v_ashrrev_i32_e32 v25, 31, v24
	v_ashrrev_i32_e32 v43, 31, v42
	v_ashrrev_i32_e32 v45, 31, v44
	v_ashrrev_i32_e32 v47, 31, v46
	v_ashrrev_i32_e32 v49, 31, v48
	v_lshlrev_b64 v[8:9], 13, v[8:9]
	v_ashrrev_i32_e32 v11, 31, v10
	v_ashrrev_i32_e32 v15, 31, v14
	v_ashrrev_i32_e32 v17, 31, v16
	v_ashrrev_i32_e32 v19, 31, v18
	v_ashrrev_i32_e32 v31, 31, v30
	v_ashrrev_i32_e32 v33, 31, v32
	v_ashrrev_i32_e32 v39, 31, v38
	v_ashrrev_i32_e32 v41, 31, v40
	v_ashrrev_i32_e32 v51, 31, v50
	v_ashrrev_i32_e32 v53, 31, v52
	v_ashrrev_i32_e32 v55, 31, v54
	v_ashrrev_i32_e32 v57, 31, v56
	v_ashrrev_i32_e32 v59, 31, v58
	v_ashrrev_i32_e32 v61, 31, v60
	v_ashrrev_i32_e32 v63, 31, v62
	v_ashrrev_i32_e32 v65, 31, v64
	v_ashrrev_i32_e32 v67, 31, v66
	v_ashrrev_i32_e32 v69, 31, v68
	v_ashrrev_i32_e32 v71, 31, v70
	v_ashrrev_i32_e32 v73, 31, v72
	v_ashrrev_i32_e32 v75, 31, v74
	v_ashrrev_i32_e32 v77, 31, v76
	v_ashrrev_i32_e32 v79, 31, v78
	v_ashrrev_i32_e32 v81, 31, v80
	v_lshl_add_u64 v[82:83], s[6:7], 2, v[4:5]
	v_lshlrev_b64 v[20:21], 13, v[20:21]
	v_lshlrev_b64 v[22:23], 13, v[22:23]
	v_lshlrev_b64 v[24:25], 13, v[24:25]
	v_lshlrev_b64 v[42:43], 13, v[42:43]
; __device__ __forceinline__ void tr_item(const float* __restrict__ W, int K, int Nsrc, int col0, int nvalid, const float* __restrict__ gain, bf16_t* WT, int drow0, int k0, LAS float* scr, int lane) {
;     ...
;     for (int i = 0; i < 32; ++i) { const int kk = 2 * i + (lane >> 5), n = lane & 31; v[i] = 0.f; if (n < nvalid) v[i] = W[(size_t)(k0 + kk) * Nsrc + col0 + n]; }
	v_lshlrev_b64 v[44:45], 13, v[44:45]
	v_lshlrev_b64 v[46:47], 13, v[46:47]
	v_lshlrev_b64 v[48:49], 13, v[48:49]
	v_lshlrev_b64 v[10:11], 13, v[10:11]
	v_lshlrev_b64 v[14:15], 13, v[14:15]
	v_lshlrev_b64 v[16:17], 13, v[16:17]
	v_lshlrev_b64 v[18:19], 13, v[18:19]
	v_lshlrev_b64 v[30:31], 13, v[30:31]
	v_lshlrev_b64 v[32:33], 13, v[32:33]
	v_lshlrev_b64 v[38:39], 13, v[38:39]
	v_lshlrev_b64 v[40:41], 13, v[40:41]
	v_lshlrev_b64 v[50:51], 13, v[50:51]
	v_lshlrev_b64 v[52:53], 13, v[52:53]
	v_lshlrev_b64 v[54:55], 13, v[54:55]
	v_lshlrev_b64 v[56:57], 13, v[56:57]
	v_lshlrev_b64 v[58:59], 13, v[58:59]
	v_lshlrev_b64 v[60:61], 13, v[60:61]
	v_lshlrev_b64 v[62:63], 13, v[62:63]
	v_lshlrev_b64 v[64:65], 13, v[64:65]
	v_lshlrev_b64 v[66:67], 13, v[66:67]
	v_lshlrev_b64 v[68:69], 13, v[68:69]
	v_lshlrev_b64 v[70:71], 13, v[70:71]
	v_lshlrev_b64 v[72:73], 13, v[72:73]
	v_lshlrev_b64 v[74:75], 13, v[74:75]
	v_lshlrev_b64 v[76:77], 13, v[76:77]
	v_lshlrev_b64 v[78:79], 13, v[78:79]
	v_lshlrev_b64 v[80:81], 13, v[80:81]
	v_lshl_add_u64 v[8:9], v[82:83], 0, v[8:9]
	v_lshl_add_u64 v[20:21], v[82:83], 0, v[20:21]
	v_lshl_add_u64 v[22:23], v[82:83], 0, v[22:23]
	v_lshl_add_u64 v[24:25], v[82:83], 0, v[24:25]
	v_lshl_add_u64 v[42:43], v[82:83], 0, v[42:43]
	v_lshl_add_u64 v[44:45], v[82:83], 0, v[44:45]
	v_lshl_add_u64 v[46:47], v[82:83], 0, v[46:47]
	v_lshl_add_u64 v[48:49], v[82:83], 0, v[48:49]
	v_lshl_add_u64 v[10:11], v[82:83], 0, v[10:11]
	v_lshl_add_u64 v[14:15], v[82:83], 0, v[14:15]
	v_lshl_add_u64 v[16:17], v[82:83], 0, v[16:17]
	v_lshl_add_u64 v[18:19], v[82:83], 0, v[18:19]
	v_lshl_add_u64 v[30:31], v[82:83], 0, v[30:31]
	v_lshl_add_u64 v[32:33], v[82:83], 0, v[32:33]
	v_lshl_add_u64 v[38:39], v[82:83], 0, v[38:39]
	v_lshl_add_u64 v[40:41], v[82:83], 0, v[40:41]
	v_lshl_add_u64 v[50:51], v[82:83], 0, v[50:51]
	v_lshl_add_u64 v[52:53], v[82:83], 0, v[52:53]
	v_lshl_add_u64 v[54:55], v[82:83], 0, v[54:55]
	v_lshl_add_u64 v[56:57], v[82:83], 0, v[56:57]
	v_lshl_add_u64 v[58:59], v[82:83], 0, v[58:59]
	v_lshl_add_u64 v[60:61], v[82:83], 0, v[60:61]
	v_lshl_add_u64 v[62:63], v[82:83], 0, v[62:63]
	v_lshl_add_u64 v[64:65], v[82:83], 0, v[64:65]
	v_lshl_add_u64 v[66:67], v[82:83], 0, v[66:67]
	v_lshl_add_u64 v[68:69], v[82:83], 0, v[68:69]
	v_lshl_add_u64 v[70:71], v[82:83], 0, v[70:71]
	v_lshl_add_u64 v[72:73], v[82:83], 0, v[72:73]
	v_lshl_add_u64 v[74:75], v[82:83], 0, v[74:75]
	v_lshl_add_u64 v[76:77], v[82:83], 0, v[76:77]
	v_lshl_add_u64 v[78:79], v[82:83], 0, v[78:79]
	v_lshl_add_u64 v[80:81], v[82:83], 0, v[80:81]
	global_load_dword v13, v[8:9], off nt
	global_load_dword v27, v[10:11], off nt
	global_load_dword v29, v[14:15], off nt
	global_load_dword v35, v[16:17], off nt
	global_load_dword v37, v[18:19], off nt
	global_load_dword v82, v[20:21], off nt
	global_load_dword v83, v[22:23], off nt
	global_load_dword v84, v[24:25], off nt
	global_load_dword v85, v[30:31], off nt
	global_load_dword v86, v[32:33], off nt
	global_load_dword v87, v[38:39], off nt
	global_load_dword v88, v[40:41], off nt
	global_load_dword v89, v[42:43], off nt
	global_load_dword v90, v[44:45], off nt
	global_load_dword v91, v[46:47], off nt
	global_load_dword v20, v[48:49], off nt
	global_load_dword v21, v[50:51], off nt
	global_load_dword v22, v[52:53], off nt
	global_load_dword v23, v[54:55], off nt
	global_load_dword v24, v[56:57], off nt
	global_load_dword v25, v[58:59], off nt
	global_load_dword v42, v[60:61], off nt
	global_load_dword v43, v[62:63], off nt
	global_load_dword v44, v[64:65], off nt
	global_load_dword v45, v[66:67], off nt
	global_load_dword v46, v[68:69], off nt
	global_load_dword v47, v[70:71], off nt
	global_load_dword v92, v[72:73], off nt
	global_load_dword v93, v[74:75], off nt
	global_load_dword v94, v[76:77], off nt
	global_load_dword v48, v[78:79], off nt
	global_load_dword v49, v[80:81], off nt
	v_add_u32_e32 v10, s6, v28
	s_ashr_i32 s5, s4, 31
	v_ashrrev_i32_e32 v11, 31, v10
	v_add_u32_e32 v14, 8, v10
	v_add_u32_e32 v16, 16, v10
	v_add_u32_e32 v18, 24, v10
	v_lshl_add_u64 v[8:9], s[4:5], 1, v[6:7]
	v_lshlrev_b64 v[10:11], 11, v[10:11]
	v_ashrrev_i32_e32 v15, 31, v14
	v_ashrrev_i32_e32 v17, 31, v16
	v_ashrrev_i32_e32 v19, 31, v18
	v_add_u32_e32 v50, 0x400, v12
	v_add_u32_e32 v51, 0x800, v12
	v_add_u32_e32 v52, 0xc00, v12
	v_add_u32_e32 v53, 0x1000, v12
	v_add_u32_e32 v54, 0x1400, v12
	v_add_u32_e32 v55, 0x1800, v12
	v_add_u32_e32 v56, 0x1c00, v12
	v_lshl_add_u64 v[30:31], v[8:9], 0, v[10:11]
	v_lshlrev_b64 v[10:11], 11, v[14:15]
	v_lshlrev_b64 v[14:15], 11, v[16:17]
	v_lshlrev_b64 v[16:17], 11, v[18:19]
	s_waitcnt vmcnt(30)
; #define LAS __attribute__((address_space(3)))
; __device__ __forceinline__ unsigned pk2(float lo, float hi) { const f32x2 v = {lo, hi}; return __builtin_bit_cast(unsigned, __builtin_convertvector(v, hbf2)); }
; __device__ __forceinline__ void tr_item(const float* __restrict__ W, int K, int Nsrc, int col0, int nvalid, const float* __restrict__ gain, bf16_t* WT, int drow0, int k0, LAS float* scr, int lane) {
;     ...
;     for (int i = 0; i < 32; ++i) { const int kk = 2 * i + (lane >> 5), n = lane & 31; float x = v[i]; if (gain) x *= gain[k0 + kk]; scr[kk * 33 + n] = x; }
;     const int c = lane & 7;
; #pragma unroll
;     for (int j = 0; j < 4; ++j) { const int n = (lane >> 3) + 8 * j; const LAS float* s = scr + (8 * c) * 33 + n;
;         u32x4 o; o.x = pk2(s[0 * 33], s[1 * 33]); o.y = pk2(s[2 * 33], s[3 * 33]); o.z = pk2(s[4 * 33], s[5 * 33]); o.w = pk2(s[6 * 33], s[7 * 33]);
;         *(u32x4*)(WT + (size_t)(drow0 + n) * K + k0 + 8 * c) = o; }
	ds_write2_b32 v12, v13, v27 offset1:66
	s_waitcnt vmcnt(28)
	ds_write2_b32 v12, v29, v35 offset0:132 offset1:198
	s_waitcnt vmcnt(26)
	ds_write2_b32 v50, v37, v82 offset0:8 offset1:74
	s_waitcnt vmcnt(24)
	ds_write2_b32 v50, v83, v84 offset0:140 offset1:206
	s_waitcnt vmcnt(22)
	ds_write2_b32 v51, v85, v86 offset0:16 offset1:82
	s_waitcnt vmcnt(20)
	ds_write2_b32 v51, v87, v88 offset0:148 offset1:214
	s_waitcnt vmcnt(18)
	ds_write2_b32 v52, v89, v90 offset0:24 offset1:90
	s_waitcnt vmcnt(16)
	ds_write2_b32 v52, v91, v20 offset0:156 offset1:222
	s_waitcnt vmcnt(14)
	ds_write2_b32 v53, v21, v22 offset0:32 offset1:98
	s_waitcnt vmcnt(12)
	ds_write2_b32 v53, v23, v24 offset0:164 offset1:230
	s_waitcnt vmcnt(10)
	ds_write2_b32 v54, v25, v42 offset0:40 offset1:106
	s_waitcnt vmcnt(8)
	ds_write2_b32 v54, v43, v44 offset0:172 offset1:238
	s_waitcnt vmcnt(6)
	ds_write2_b32 v55, v45, v46 offset0:48 offset1:114
	s_waitcnt vmcnt(4)
	ds_write2_b32 v55, v47, v92 offset0:180 offset1:246
	s_waitcnt vmcnt(2)
	ds_write2_b32 v56, v93, v94 offset0:56 offset1:122
	s_waitcnt vmcnt(0)
	ds_write2_b32 v56, v48, v49 offset0:188 offset1:254
	v_lshl_add_u64 v[38:39], v[8:9], 0, v[14:15]
	v_lshl_add_u64 v[40:41], v[8:9], 0, v[16:17]
	ds_read2_b32 v[14:15], v3 offset0:33 offset1:41
	ds_read2_b32 v[16:17], v3 offset1:8
	ds_read2_b32 v[18:19], v3 offset0:66 offset1:74
	ds_read2_b32 v[20:21], v3 offset0:99 offset1:107
	ds_read2_b32 v[22:23], v3 offset0:132 offset1:140
	ds_read2_b32 v[24:25], v3 offset0:165 offset1:173
	ds_read2_b32 v[42:43], v3 offset0:198 offset1:206
	ds_read2_b32 v[44:45], v3 offset0:231 offset1:239
	ds_read2_b32 v[46:47], v3 offset0:16 offset1:24
	ds_read2_b32 v[48:49], v3 offset0:49 offset1:57
	ds_read2_b32 v[50:51], v3 offset0:82 offset1:90
	ds_read2_b32 v[52:53], v3 offset0:115 offset1:123
	ds_read2_b32 v[54:55], v3 offset0:148 offset1:156
	ds_read2_b32 v[56:57], v3 offset0:181 offset1:189
	ds_read2_b32 v[58:59], v3 offset0:214 offset1:222
	ds_read2_b32 v[60:61], v3 offset0:247 offset1:255
	s_add_i32 s9, s9, s62
	s_add_i32 s3, s3, s8
	s_cmpk_lt_i32 s9, 0x400
	v_lshl_add_u64 v[32:33], v[8:9], 0, v[10:11]
	s_waitcnt lgkmcnt(14)
	v_cvt_pk_bf16_f32 v8, v16, v14
	s_waitcnt lgkmcnt(12)
	v_cvt_pk_bf16_f32 v9, v18, v20
	s_waitcnt lgkmcnt(10)
	v_cvt_pk_bf16_f32 v10, v22, v24
	s_waitcnt lgkmcnt(8)
	v_cvt_pk_bf16_f32 v11, v42, v44
	v_cvt_pk_bf16_f32 v14, v17, v15
	v_cvt_pk_bf16_f32 v15, v19, v21
	v_cvt_pk_bf16_f32 v16, v23, v25
	v_cvt_pk_bf16_f32 v17, v43, v45
	s_waitcnt lgkmcnt(6)
	v_cvt_pk_bf16_f32 v18, v46, v48
	s_waitcnt lgkmcnt(4)
	v_cvt_pk_bf16_f32 v19, v50, v52
	s_waitcnt lgkmcnt(2)
	v_cvt_pk_bf16_f32 v20, v54, v56
	s_waitcnt lgkmcnt(0)
	v_cvt_pk_bf16_f32 v21, v58, v60
	v_cvt_pk_bf16_f32 v22, v47, v49
	v_cvt_pk_bf16_f32 v23, v51, v53
	v_cvt_pk_bf16_f32 v24, v55, v57
	v_cvt_pk_bf16_f32 v25, v59, v61
	global_store_dwordx4 v[30:31], v[8:11], off
	global_store_dwordx4 v[32:33], v[14:17], off
	global_store_dwordx4 v[38:39], v[18:21], off
	global_store_dwordx4 v[40:41], v[22:25], off
	s_cbranch_scc1 .LBB0_187

; __device__ __forceinline__ void tr_item(const float* __restrict__ W, int K, int Nsrc, int col0, int nvalid, const float* __restrict__ gain, bf16_t* WT, int drow0, int k0, LAS float* scr, int lane) {
;     ...
;     for (int i = 0; i < 32; ++i) { const int kk = 2 * i + (lane >> 5), n = lane & 31; v[i] = 0.f; if (n < nvalid) v[i] = W[(size_t)(k0 + kk) * Nsrc + col0 + n]; }
; __device__ __forceinline__ void conv_job(int kind, const float* W, const float* W2, int K, int Nsrc, int Ndst, const float* gain, bf16_t* WT, LAS float* scr, int gw, int NGW, int lane) {
;     const int nb = Ndst / 32, nitems = (K / 64) * nb;
;     for (int it = gw; it < nitems; it += NGW) {
;         const int kb = it / nb, db = it % nb, d0 = db * 32, k0 = kb * 64; const float* src = W; int col0 = d0, nvalid = 32;
.LBB0_190:
	s_ashr_i32 s4, s9, 31
	s_lshr_b32 s4, s4, 26
	s_add_i32 s4, s9, s4
	s_lshl_b32 s5, s4, 5
	s_andn2_b32 s4, s4, 63
	s_and_b32 s5, s5, 0xfffff800
	v_or_b32_e32 v16, s4, v2
	s_sub_i32 s6, s3, s5
	v_or_b32_e32 v30, 10, v16
	v_or_b32_e32 v32, 12, v16
	v_or_b32_e32 v38, 14, v16
	v_or_b32_e32 v40, 16, v16
	v_or_b32_e32 v48, 24, v16
	v_or_b32_e32 v50, 26, v16
	v_or_b32_e32 v52, 28, v16
	v_or_b32_e32 v54, 30, v16
	v_ashrrev_i32_e32 v17, 31, v16
	v_or_b32_e32 v18, 2, v16
	v_or_b32_e32 v20, 4, v16
	v_or_b32_e32 v22, 6, v16
	v_or_b32_e32 v24, 8, v16
	v_or_b32_e32 v42, 18, v16
	v_or_b32_e32 v44, 20, v16
	v_or_b32_e32 v46, 22, v16
	v_or_b32_e32 v56, 32, v16
	v_or_b32_e32 v58, 34, v16
	v_or_b32_e32 v60, 36, v16
	v_or_b32_e32 v62, 38, v16
	v_or_b32_e32 v64, 40, v16
	v_or_b32_e32 v66, 42, v16
	v_or_b32_e32 v68, 44, v16
	v_or_b32_e32 v70, 46, v16
	v_or_b32_e32 v72, 48, v16
	v_or_b32_e32 v74, 50, v16
	v_or_b32_e32 v76, 52, v16
	v_or_b32_e32 v78, 54, v16
	v_or_b32_e32 v80, 56, v16
	v_or_b32_e32 v82, 58, v16
	v_or_b32_e32 v84, 60, v16
	v_or_b32_e32 v86, 62, v16
	s_ashr_i32 s7, s6, 31
	v_ashrrev_i32_e32 v31, 31, v30
	v_ashrrev_i32_e32 v33, 31, v32
	v_ashrrev_i32_e32 v39, 31, v38
	v_ashrrev_i32_e32 v41, 31, v40
	v_ashrrev_i32_e32 v49, 31, v48
	v_ashrrev_i32_e32 v51, 31, v50
	v_ashrrev_i32_e32 v53, 31, v52
	v_ashrrev_i32_e32 v55, 31, v54
	v_lshlrev_b64 v[16:17], 13, v[16:17]
	v_ashrrev_i32_e32 v19, 31, v18
	v_ashrrev_i32_e32 v21, 31, v20
	v_ashrrev_i32_e32 v23, 31, v22
	v_ashrrev_i32_e32 v25, 31, v24
	v_ashrrev_i32_e32 v43, 31, v42
	v_ashrrev_i32_e32 v45, 31, v44
	v_ashrrev_i32_e32 v47, 31, v46
	v_ashrrev_i32_e32 v57, 31, v56
	v_ashrrev_i32_e32 v59, 31, v58
	v_ashrrev_i32_e32 v61, 31, v60
	v_ashrrev_i32_e32 v63, 31, v62
	v_ashrrev_i32_e32 v65, 31, v64
	v_ashrrev_i32_e32 v67, 31, v66
	v_ashrrev_i32_e32 v69, 31, v68
	v_ashrrev_i32_e32 v71, 31, v70
	v_ashrrev_i32_e32 v73, 31, v72
	v_ashrrev_i32_e32 v75, 31, v74
	v_ashrrev_i32_e32 v77, 31, v76
	v_ashrrev_i32_e32 v79, 31, v78
	v_ashrrev_i32_e32 v81, 31, v80
	v_ashrrev_i32_e32 v83, 31, v82
	v_ashrrev_i32_e32 v85, 31, v84
	v_ashrrev_i32_e32 v87, 31, v86
	v_lshl_add_u64 v[88:89], s[6:7], 2, v[6:7]
	v_lshlrev_b64 v[30:31], 13, v[30:31]
	v_lshlrev_b64 v[32:33], 13, v[32:33]
	v_lshlrev_b64 v[38:39], 13, v[38:39]
	v_lshlrev_b64 v[40:41], 13, v[40:41]
	v_lshlrev_b64 v[48:49], 13, v[48:49]
	v_lshlrev_b64 v[50:51], 13, v[50:51]
	v_lshlrev_b64 v[52:53], 13, v[52:53]
	v_lshlrev_b64 v[54:55], 13, v[54:55]
	v_lshlrev_b64 v[18:19], 13, v[18:19]
	v_lshlrev_b64 v[20:21], 13, v[20:21]
	v_lshlrev_b64 v[22:23], 13, v[22:23]
	v_lshlrev_b64 v[24:25], 13, v[24:25]
	v_lshlrev_b64 v[42:43], 13, v[42:43]
	v_lshlrev_b64 v[44:45], 13, v[44:45]
	v_lshlrev_b64 v[46:47], 13, v[46:47]
	v_lshlrev_b64 v[56:57], 13, v[56:57]
	v_lshlrev_b64 v[58:59], 13, v[58:59]
	v_lshlrev_b64 v[60:61], 13, v[60:61]
	v_lshlrev_b64 v[62:63], 13, v[62:63]
	v_lshlrev_b64 v[64:65], 13, v[64:65]
	v_lshlrev_b64 v[66:67], 13, v[66:67]
	v_lshlrev_b64 v[68:69], 13, v[68:69]
	v_lshlrev_b64 v[70:71], 13, v[70:71]
	v_lshlrev_b64 v[72:73], 13, v[72:73]
	v_lshlrev_b64 v[74:75], 13, v[74:75]
	v_lshlrev_b64 v[76:77], 13, v[76:77]
	v_lshlrev_b64 v[78:79], 13, v[78:79]
	v_lshlrev_b64 v[80:81], 13, v[80:81]
	v_lshlrev_b64 v[82:83], 13, v[82:83]
	v_lshlrev_b64 v[84:85], 13, v[84:85]
	v_lshlrev_b64 v[86:87], 13, v[86:87]
	v_lshl_add_u64 v[16:17], v[88:89], 0, v[16:17]
	v_lshl_add_u64 v[30:31], v[88:89], 0, v[30:31]
	v_lshl_add_u64 v[32:33], v[88:89], 0, v[32:33]
	v_lshl_add_u64 v[38:39], v[88:89], 0, v[38:39]
	v_lshl_add_u64 v[40:41], v[88:89], 0, v[40:41]
	v_lshl_add_u64 v[48:49], v[88:89], 0, v[48:49]
	v_lshl_add_u64 v[50:51], v[88:89], 0, v[50:51]
	v_lshl_add_u64 v[52:53], v[88:89], 0, v[52:53]
	v_lshl_add_u64 v[54:55], v[88:89], 0, v[54:55]
	v_lshl_add_u64 v[18:19], v[88:89], 0, v[18:19]
	v_lshl_add_u64 v[20:21], v[88:89], 0, v[20:21]
	v_lshl_add_u64 v[22:23], v[88:89], 0, v[22:23]
	v_lshl_add_u64 v[24:25], v[88:89], 0, v[24:25]
	v_lshl_add_u64 v[42:43], v[88:89], 0, v[42:43]
	v_lshl_add_u64 v[44:45], v[88:89], 0, v[44:45]
	v_lshl_add_u64 v[46:47], v[88:89], 0, v[46:47]
	v_lshl_add_u64 v[56:57], v[88:89], 0, v[56:57]
	v_lshl_add_u64 v[58:59], v[88:89], 0, v[58:59]
	v_lshl_add_u64 v[60:61], v[88:89], 0, v[60:61]
	v_lshl_add_u64 v[62:63], v[88:89], 0, v[62:63]
	v_lshl_add_u64 v[64:65], v[88:89], 0, v[64:65]
	v_lshl_add_u64 v[66:67], v[88:89], 0, v[66:67]
	v_lshl_add_u64 v[68:69], v[88:89], 0, v[68:69]
	v_lshl_add_u64 v[70:71], v[88:89], 0, v[70:71]
	v_lshl_add_u64 v[72:73], v[88:89], 0, v[72:73]
	v_lshl_add_u64 v[74:75], v[88:89], 0, v[74:75]
	v_lshl_add_u64 v[76:77], v[88:89], 0, v[76:77]
	v_lshl_add_u64 v[78:79], v[88:89], 0, v[78:79]
	v_lshl_add_u64 v[80:81], v[88:89], 0, v[80:81]
	v_lshl_add_u64 v[82:83], v[88:89], 0, v[82:83]
	v_lshl_add_u64 v[84:85], v[88:89], 0, v[84:85]
	v_lshl_add_u64 v[86:87], v[88:89], 0, v[86:87]
	global_load_dword v27, v[16:17], off nt
	global_load_dword v29, v[18:19], off nt
	global_load_dword v35, v[20:21], off nt
	global_load_dword v37, v[22:23], off nt
	global_load_dword v88, v[24:25], off nt
	global_load_dword v89, v[30:31], off nt
	global_load_dword v90, v[32:33], off nt
	global_load_dword v91, v[38:39], off nt
	global_load_dword v92, v[40:41], off nt
	global_load_dword v93, v[42:43], off nt
	global_load_dword v94, v[44:45], off nt
	global_load_dword v95, v[46:47], off nt
	global_load_dword v96, v[48:49], off nt
	global_load_dword v97, v[50:51], off nt
	global_load_dword v98, v[52:53], off nt
	global_load_dword v30, v[54:55], off nt
	global_load_dword v31, v[56:57], off nt
	global_load_dword v32, v[58:59], off nt
	global_load_dword v33, v[60:61], off nt
	global_load_dword v38, v[62:63], off nt
	global_load_dword v39, v[64:65], off nt
	global_load_dword v40, v[66:67], off nt
	global_load_dword v41, v[68:69], off nt
	global_load_dword v48, v[70:71], off nt
	global_load_dword v49, v[72:73], off nt
	global_load_dword v50, v[74:75], off nt
	global_load_dword v51, v[76:77], off nt
	global_load_dword v52, v[78:79], off nt
	global_load_dword v53, v[80:81], off nt
	global_load_dword v99, v[82:83], off nt
	global_load_dword v54, v[84:85], off nt
	global_load_dword v55, v[86:87], off nt
	v_add_u32_e32 v18, s6, v28
	s_ashr_i32 s5, s4, 31
	v_ashrrev_i32_e32 v19, 31, v18
	v_add_u32_e32 v20, 8, v18
	v_add_u32_e32 v22, 16, v18
	v_add_u32_e32 v24, 24, v18
	v_lshl_add_u64 v[16:17], s[4:5], 1, v[4:5]
	v_lshlrev_b64 v[18:19], 12, v[18:19]
	v_ashrrev_i32_e32 v21, 31, v20
	v_ashrrev_i32_e32 v23, 31, v22
	v_ashrrev_i32_e32 v25, 31, v24
	v_lshl_add_u64 v[42:43], v[16:17], 0, v[18:19]
	v_lshlrev_b64 v[18:19], 12, v[20:21]
	v_lshlrev_b64 v[20:21], 12, v[22:23]
	v_lshlrev_b64 v[22:23], 12, v[24:25]
	s_waitcnt vmcnt(30)
; #define LAS __attribute__((address_space(3)))
; __device__ __forceinline__ unsigned pk2(float lo, float hi) { const f32x2 v = {lo, hi}; return __builtin_bit_cast(unsigned, __builtin_convertvector(v, hbf2)); }
; __device__ __forceinline__ void tr_item(const float* __restrict__ W, int K, int Nsrc, int col0, int nvalid, const float* __restrict__ gain, bf16_t* WT, int drow0, int k0, LAS float* scr, int lane) {
;     ...
;     for (int i = 0; i < 32; ++i) { const int kk = 2 * i + (lane >> 5), n = lane & 31; float x = v[i]; if (gain) x *= gain[k0 + kk]; scr[kk * 33 + n] = x; }
;     const int c = lane & 7;
; #pragma unroll
;     for (int j = 0; j < 4; ++j) { const int n = (lane >> 3) + 8 * j; const LAS float* s = scr + (8 * c) * 33 + n;
;         u32x4 o; o.x = pk2(s[0 * 33], s[1 * 33]); o.y = pk2(s[2 * 33], s[3 * 33]); o.z = pk2(s[4 * 33], s[5 * 33]); o.w = pk2(s[6 * 33], s[7 * 33]);
;         *(u32x4*)(WT + (size_t)(drow0 + n) * K + k0 + 8 * c) = o; }
	ds_write2_b32 v8, v27, v29 offset1:66
	s_waitcnt vmcnt(28)
	ds_write2_b32 v8, v35, v37 offset0:132 offset1:198
	s_waitcnt vmcnt(26)
	ds_write2_b32 v9, v88, v89 offset0:8 offset1:74
	s_waitcnt vmcnt(24)
	ds_write2_b32 v9, v90, v91 offset0:140 offset1:206
	s_waitcnt vmcnt(22)
	ds_write2_b32 v10, v92, v93 offset0:16 offset1:82
	s_waitcnt vmcnt(20)
	ds_write2_b32 v10, v94, v95 offset0:148 offset1:214
	s_waitcnt vmcnt(18)
	ds_write2_b32 v11, v96, v97 offset0:24 offset1:90
	s_waitcnt vmcnt(16)
	ds_write2_b32 v11, v98, v30 offset0:156 offset1:222
	s_waitcnt vmcnt(14)
	ds_write2_b32 v12, v31, v32 offset0:32 offset1:98
	s_waitcnt vmcnt(12)
	ds_write2_b32 v12, v33, v38 offset0:164 offset1:230
	s_waitcnt vmcnt(10)
	ds_write2_b32 v13, v39, v40 offset0:40 offset1:106
	s_waitcnt vmcnt(8)
	ds_write2_b32 v13, v41, v48 offset0:172 offset1:238
	s_waitcnt vmcnt(6)
	ds_write2_b32 v14, v49, v50 offset0:48 offset1:114
	s_waitcnt vmcnt(4)
	ds_write2_b32 v14, v51, v52 offset0:180 offset1:246
	s_waitcnt vmcnt(2)
	ds_write2_b32 v15, v53, v99 offset0:56 offset1:122
	s_waitcnt vmcnt(0)
	ds_write2_b32 v15, v54, v55 offset0:188 offset1:254
	v_lshl_add_u64 v[44:45], v[16:17], 0, v[20:21]
	v_lshl_add_u64 v[46:47], v[16:17], 0, v[22:23]
	ds_read2_b32 v[20:21], v3 offset0:33 offset1:41
	ds_read2_b32 v[22:23], v3 offset1:8
	ds_read2_b32 v[30:31], v3 offset0:66 offset1:74
	ds_read2_b32 v[32:33], v3 offset0:99 offset1:107
	ds_read2_b32 v[38:39], v3 offset0:132 offset1:140
	ds_read2_b32 v[40:41], v3 offset0:165 offset1:173
	ds_read2_b32 v[48:49], v3 offset0:198 offset1:206
	ds_read2_b32 v[50:51], v3 offset0:231 offset1:239
	ds_read2_b32 v[52:53], v3 offset0:16 offset1:24
	ds_read2_b32 v[54:55], v3 offset0:49 offset1:57
	ds_read2_b32 v[56:57], v3 offset0:82 offset1:90
	ds_read2_b32 v[58:59], v3 offset0:115 offset1:123
	ds_read2_b32 v[60:61], v3 offset0:148 offset1:156
	ds_read2_b32 v[62:63], v3 offset0:181 offset1:189
	ds_read2_b32 v[64:65], v3 offset0:214 offset1:222
	ds_read2_b32 v[66:67], v3 offset0:247 offset1:255
	s_add_i32 s9, s9, s62
	s_add_i32 s3, s3, s8
	s_cmpk_lt_i32 s9, 0x800
	v_lshl_add_u64 v[24:25], v[16:17], 0, v[18:19]
	s_waitcnt lgkmcnt(14)
	v_cvt_pk_bf16_f32 v16, v22, v20
	s_waitcnt lgkmcnt(12)
	v_cvt_pk_bf16_f32 v17, v30, v32
	s_waitcnt lgkmcnt(10)
	v_cvt_pk_bf16_f32 v18, v38, v40
	s_waitcnt lgkmcnt(8)
	v_cvt_pk_bf16_f32 v19, v48, v50
	v_cvt_pk_bf16_f32 v20, v23, v21
	v_cvt_pk_bf16_f32 v21, v31, v33
	v_cvt_pk_bf16_f32 v22, v39, v41
	v_cvt_pk_bf16_f32 v23, v49, v51
	s_waitcnt lgkmcnt(6)
	v_cvt_pk_bf16_f32 v30, v52, v54
	s_waitcnt lgkmcnt(4)
	v_cvt_pk_bf16_f32 v31, v56, v58
	s_waitcnt lgkmcnt(2)
	v_cvt_pk_bf16_f32 v32, v60, v62
	s_waitcnt lgkmcnt(0)
	v_cvt_pk_bf16_f32 v33, v64, v66
	v_cvt_pk_bf16_f32 v38, v53, v55
	v_cvt_pk_bf16_f32 v39, v57, v59
	v_cvt_pk_bf16_f32 v40, v61, v63
	v_cvt_pk_bf16_f32 v41, v65, v67
	global_store_dwordx4 v[42:43], v[16:19], off
	global_store_dwordx4 v[24:25], v[20:23], off
	global_store_dwordx4 v[44:45], v[30:33], off
	global_store_dwordx4 v[46:47], v[38:41], off
	s_cbranch_scc1 .LBB0_190

; __device__ __forceinline__ void tr_item(const float* __restrict__ W, int K, int Nsrc, int col0, int nvalid, const float* __restrict__ gain, bf16_t* WT, int drow0, int k0, LAS float* scr, int lane) {
;     ...
;     for (int i = 0; i < 32; ++i) { const int kk = 2 * i + (lane >> 5), n = lane & 31; v[i] = 0.f; if (n < nvalid) v[i] = W[(size_t)(k0 + kk) * Nsrc + col0 + n]; }
; #pragma unroll
;     for (int i = 0; i < 32; ++i) { const int kk = 2 * i + (lane >> 5), n = lane & 31; float x = v[i]; if (gain) x *= gain[k0 + kk]; scr[kk * 33 + n] = x; }
; __device__ __forceinline__ void conv_job(int kind, const float* W, const float* W2, int K, int Nsrc, int Ndst, const float* gain, bf16_t* WT, LAS float* scr, int gw, int NGW, int lane) {
;     ...
;         const int kb = it / nb, db = it % nb, d0 = db * 32, k0 = kb * 64; const float* src = W; int col0 = d0, nvalid = 32;
;         if (kind == 1) { const int t = d0 >> 8; int r = d0 & 255; if (r >= 128) { src = W2; r -= 128; } col0 = t * 128 + r; }
.LBB0_195:
	s_ashr_i32 s10, s26, 31
	s_lshr_b32 s10, s10, 28
	s_add_i32 s10, s26, s10
	s_ashr_i32 s10, s10, 4
	s_lshl_b32 s27, s10, 9
	s_lshl_b32 s10, s10, 6
	v_or_b32_e32 v22, s10, v2
	s_sub_i32 s20, s3, s27
	v_or_b32_e32 v18, 8, v22
	s_ashr_i32 s21, s20, 31
	v_ashrrev_i32_e32 v19, 31, v18
	v_lshl_add_u64 v[8:9], s[20:21], 2, v[6:7]
	v_lshlrev_b64 v[18:19], 11, v[18:19]
	v_lshl_add_u64 v[20:21], v[8:9], 0, v[18:19]
	v_or_b32_e32 v18, 10, v22
	v_ashrrev_i32_e32 v19, 31, v18
	v_lshlrev_b64 v[18:19], 11, v[18:19]
	v_lshl_add_u64 v[38:39], v[8:9], 0, v[18:19]
	v_or_b32_e32 v18, 12, v22
	v_ashrrev_i32_e32 v19, 31, v18
	v_or_b32_e32 v14, 4, v22
	v_lshlrev_b64 v[18:19], 11, v[18:19]
	v_ashrrev_i32_e32 v23, 31, v22
	v_or_b32_e32 v12, 2, v22
	v_ashrrev_i32_e32 v15, 31, v14
	v_or_b32_e32 v16, 6, v22
	v_lshl_add_u64 v[40:41], v[8:9], 0, v[18:19]
	v_or_b32_e32 v18, 14, v22
	v_lshlrev_b64 v[10:11], 11, v[22:23]
	v_ashrrev_i32_e32 v13, 31, v12
	v_lshlrev_b64 v[14:15], 11, v[14:15]
	v_ashrrev_i32_e32 v17, 31, v16
	v_ashrrev_i32_e32 v19, 31, v18
	v_lshl_add_u64 v[10:11], v[8:9], 0, v[10:11]
	v_lshlrev_b64 v[12:13], 11, v[12:13]
	v_lshl_add_u64 v[14:15], v[8:9], 0, v[14:15]
	v_lshlrev_b64 v[16:17], 11, v[16:17]
	v_lshlrev_b64 v[18:19], 11, v[18:19]
	v_lshl_add_u64 v[12:13], v[8:9], 0, v[12:13]
	v_lshl_add_u64 v[16:17], v[8:9], 0, v[16:17]
	v_lshl_add_u64 v[42:43], v[8:9], 0, v[18:19]
	global_load_dword v50, v[10:11], off nt
	global_load_dword v51, v[12:13], off nt
	global_load_dword v24, v[14:15], off nt
	global_load_dword v25, v[16:17], off nt
	global_load_dword v46, v[20:21], off nt
	global_load_dword v47, v[38:39], off nt
	global_load_dword v18, v[40:41], off nt
	global_load_dword v19, v[42:43], off nt
	v_or_b32_e32 v14, 20, v22
	v_ashrrev_i32_e32 v15, 31, v14
	v_lshlrev_b64 v[14:15], 11, v[14:15]
	v_lshl_add_u64 v[16:17], v[8:9], 0, v[14:15]
	v_or_b32_e32 v14, 22, v22
	v_ashrrev_i32_e32 v15, 31, v14
	v_lshlrev_b64 v[14:15], 11, v[14:15]
	v_lshl_add_u64 v[38:39], v[8:9], 0, v[14:15]
	v_or_b32_e32 v14, 24, v22
	v_ashrrev_i32_e32 v15, 31, v14
	v_lshlrev_b64 v[14:15], 11, v[14:15]
	v_lshl_add_u64 v[40:41], v[8:9], 0, v[14:15]
	v_or_b32_e32 v14, 26, v22
	v_ashrrev_i32_e32 v15, 31, v14
	v_lshlrev_b64 v[14:15], 11, v[14:15]
	v_lshl_add_u64 v[44:45], v[8:9], 0, v[14:15]
	v_or_b32_e32 v14, 28, v22
	v_ashrrev_i32_e32 v15, 31, v14
	v_or_b32_e32 v10, 16, v22
	v_lshlrev_b64 v[14:15], 11, v[14:15]
	v_ashrrev_i32_e32 v11, 31, v10
	v_or_b32_e32 v12, 18, v22
	v_lshl_add_u64 v[52:53], v[8:9], 0, v[14:15]
	v_or_b32_e32 v14, 30, v22
	v_lshlrev_b64 v[10:11], 11, v[10:11]
	v_ashrrev_i32_e32 v13, 31, v12
	v_ashrrev_i32_e32 v15, 31, v14
	v_lshl_add_u64 v[10:11], v[8:9], 0, v[10:11]
	v_lshlrev_b64 v[12:13], 11, v[12:13]
	v_lshlrev_b64 v[14:15], 11, v[14:15]
	v_lshl_add_u64 v[12:13], v[8:9], 0, v[12:13]
	v_lshl_add_u64 v[54:55], v[8:9], 0, v[14:15]
	global_load_dword v48, v[10:11], off nt
	global_load_dword v49, v[12:13], off nt
	global_load_dword v20, v[16:17], off nt
	global_load_dword v21, v[38:39], off nt
	global_load_dword v42, v[40:41], off nt
	global_load_dword v43, v[44:45], off nt
	global_load_dword v14, v[52:53], off nt
	global_load_dword v15, v[54:55], off nt
	v_or_b32_e32 v10, 32, v22
	v_ashrrev_i32_e32 v11, 31, v10
	v_lshlrev_b64 v[10:11], 11, v[10:11]
	v_lshl_add_u64 v[12:13], v[8:9], 0, v[10:11]
	v_or_b32_e32 v10, 34, v22
	v_ashrrev_i32_e32 v11, 31, v10
	v_lshlrev_b64 v[10:11], 11, v[10:11]
	v_lshl_add_u64 v[40:41], v[8:9], 0, v[10:11]
	v_or_b32_e32 v10, 36, v22
	v_ashrrev_i32_e32 v11, 31, v10
	v_lshlrev_b64 v[10:11], 11, v[10:11]
	v_lshl_add_u64 v[52:53], v[8:9], 0, v[10:11]
	v_or_b32_e32 v10, 38, v22
	v_ashrrev_i32_e32 v11, 31, v10
	v_lshlrev_b64 v[10:11], 11, v[10:11]
	v_lshl_add_u64 v[54:55], v[8:9], 0, v[10:11]
	v_or_b32_e32 v10, 40, v22
	v_ashrrev_i32_e32 v11, 31, v10
	v_lshlrev_b64 v[10:11], 11, v[10:11]
	v_lshl_add_u64 v[56:57], v[8:9], 0, v[10:11]
	v_or_b32_e32 v10, 42, v22
	v_ashrrev_i32_e32 v11, 31, v10
	v_lshlrev_b64 v[10:11], 11, v[10:11]
	v_lshl_add_u64 v[58:59], v[8:9], 0, v[10:11]
	v_or_b32_e32 v10, 44, v22
	v_ashrrev_i32_e32 v11, 31, v10
	v_lshlrev_b64 v[10:11], 11, v[10:11]
	v_lshl_add_u64 v[60:61], v[8:9], 0, v[10:11]
	v_or_b32_e32 v10, 46, v22
	v_ashrrev_i32_e32 v11, 31, v10
	v_lshlrev_b64 v[10:11], 11, v[10:11]
	v_lshl_add_u64 v[62:63], v[8:9], 0, v[10:11]
	global_load_dword v44, v[12:13], off nt
	global_load_dword v45, v[40:41], off nt
	global_load_dword v16, v[52:53], off nt
	global_load_dword v17, v[54:55], off nt
	global_load_dword v38, v[56:57], off nt
	global_load_dword v39, v[58:59], off nt
	global_load_dword v10, v[60:61], off nt
	global_load_dword v11, v[62:63], off nt
	v_or_b32_e32 v12, 48, v22
	v_ashrrev_i32_e32 v13, 31, v12
	v_lshlrev_b64 v[12:13], 11, v[12:13]
	v_lshl_add_u64 v[52:53], v[8:9], 0, v[12:13]
	v_or_b32_e32 v12, 50, v22
	v_ashrrev_i32_e32 v13, 31, v12
	v_lshlrev_b64 v[12:13], 11, v[12:13]
	v_lshl_add_u64 v[54:55], v[8:9], 0, v[12:13]
	v_or_b32_e32 v12, 52, v22
	v_ashrrev_i32_e32 v13, 31, v12
	v_lshlrev_b64 v[12:13], 11, v[12:13]
	v_lshl_add_u64 v[56:57], v[8:9], 0, v[12:13]
	v_or_b32_e32 v12, 54, v22
	v_ashrrev_i32_e32 v13, 31, v12
	v_lshlrev_b64 v[12:13], 11, v[12:13]
	v_lshl_add_u64 v[58:59], v[8:9], 0, v[12:13]
	v_or_b32_e32 v12, 56, v22
	v_ashrrev_i32_e32 v13, 31, v12
	v_lshlrev_b64 v[12:13], 11, v[12:13]
	v_lshl_add_u64 v[60:61], v[8:9], 0, v[12:13]
	v_or_b32_e32 v12, 58, v22
	v_ashrrev_i32_e32 v13, 31, v12
	v_lshlrev_b64 v[12:13], 11, v[12:13]
	v_lshl_add_u64 v[62:63], v[8:9], 0, v[12:13]
	v_or_b32_e32 v12, 60, v22
	v_ashrrev_i32_e32 v13, 31, v12
	v_lshlrev_b64 v[12:13], 11, v[12:13]
	v_lshl_add_u64 v[64:65], v[8:9], 0, v[12:13]
	v_or_b32_e32 v12, 62, v22
	v_ashrrev_i32_e32 v13, 31, v12
	v_lshlrev_b64 v[12:13], 11, v[12:13]
	v_lshl_add_u64 v[66:67], v[8:9], 0, v[12:13]
	global_load_dword v40, v[52:53], off nt
	global_load_dword v41, v[54:55], off nt
	global_load_dword v12, v[56:57], off nt
	global_load_dword v13, v[58:59], off nt
	global_load_dword v35, v[60:61], off nt
	global_load_dword v37, v[62:63], off nt
	global_load_dword v8, v[64:65], off nt
	global_load_dword v9, v[66:67], off nt
	s_and_b64 vcc, exec, s[4:5]
	s_cbranch_vccnz .LBB0_218
	s_ashr_i32 s11, s10, 31
	v_lshl_add_u64 v[22:23], v[22:23], 2, s[6:7]
	v_lshl_add_u64 v[52:53], s[10:11], 0, v[2:3]
	v_lshl_add_u64 v[52:53], v[52:53], 2, s[6:7]
	global_load_dword v56, v[22:23], off nt
	global_load_dword v57, v[52:53], off offset:8
	global_load_dword v54, v[52:53], off offset:16
	global_load_dword v55, v[52:53], off offset:24
	s_waitcnt vmcnt(3)
	v_mul_f32_e32 v52, v50, v56
	s_waitcnt vmcnt(2)
	v_mul_f32_e32 v53, v51, v57
	ds_write2_b32 v31, v52, v53 offset1:66
	s_waitcnt vmcnt(0)
	v_pk_mul_f32 v[22:23], v[24:25], v[54:55]
	s_cbranch_execnz .LBB0_198

; __device__ __forceinline__ void tr_item(const float* __restrict__ W, int K, int Nsrc, int col0, int nvalid, const float* __restrict__ gain, bf16_t* WT, int drow0, int k0, LAS float* scr, int lane) {
;     ...
;     for (int i = 0; i < 32; ++i) { const int kk = 2 * i + (lane >> 5), n = lane & 31; v[i] = 0.f; if (n < nvalid) v[i] = W[(size_t)(k0 + kk) * Nsrc + col0 + n]; }
; #pragma unroll
;     for (int i = 0; i < 32; ++i) { const int kk = 2 * i + (lane >> 5), n = lane & 31; float x = v[i]; if (gain) x *= gain[k0 + kk]; scr[kk * 33 + n] = x; }
; __device__ __forceinline__ void conv_job(int kind, const float* W, const float* W2, int K, int Nsrc, int Ndst, const float* gain, bf16_t* WT, LAS float* scr, int gw, int NGW, int lane) {
;     ...
;         const int kb = it / nb, db = it % nb, d0 = db * 32, k0 = kb * 64; const float* src = W; int col0 = d0, nvalid = 32;
;         if (kind == 1) { const int t = d0 >> 8; int r = d0 & 255; if (r >= 128) { src = W2; r -= 128; } col0 = t * 128 + r; }
.LBB0_230:
	s_ashr_i32 s10, s26, 31
	s_lshr_b32 s10, s10, 27
	s_add_i32 s10, s26, s10
	s_ashr_i32 s10, s10, 5
	s_lshl_b32 s27, s10, 10
	s_lshl_b32 s10, s10, 6
	v_or_b32_e32 v22, s10, v2
	s_sub_i32 s20, s3, s27
	v_or_b32_e32 v18, 8, v22
	s_ashr_i32 s21, s20, 31
	v_ashrrev_i32_e32 v19, 31, v18
	v_lshl_add_u64 v[8:9], s[20:21], 2, v[6:7]
	v_lshlrev_b64 v[18:19], 12, v[18:19]
	v_lshl_add_u64 v[20:21], v[8:9], 0, v[18:19]
	v_or_b32_e32 v18, 10, v22
	v_ashrrev_i32_e32 v19, 31, v18
	v_lshlrev_b64 v[18:19], 12, v[18:19]
	v_lshl_add_u64 v[38:39], v[8:9], 0, v[18:19]
	v_or_b32_e32 v18, 12, v22
	v_ashrrev_i32_e32 v19, 31, v18
	v_or_b32_e32 v14, 4, v22
	v_lshlrev_b64 v[18:19], 12, v[18:19]
	v_ashrrev_i32_e32 v23, 31, v22
	v_or_b32_e32 v12, 2, v22
	v_ashrrev_i32_e32 v15, 31, v14
	v_or_b32_e32 v16, 6, v22
	v_lshl_add_u64 v[40:41], v[8:9], 0, v[18:19]
	v_or_b32_e32 v18, 14, v22
	v_lshlrev_b64 v[10:11], 12, v[22:23]
	v_ashrrev_i32_e32 v13, 31, v12
	v_lshlrev_b64 v[14:15], 12, v[14:15]
	v_ashrrev_i32_e32 v17, 31, v16
	v_ashrrev_i32_e32 v19, 31, v18
	v_lshl_add_u64 v[10:11], v[8:9], 0, v[10:11]
	v_lshlrev_b64 v[12:13], 12, v[12:13]
	v_lshl_add_u64 v[14:15], v[8:9], 0, v[14:15]
	v_lshlrev_b64 v[16:17], 12, v[16:17]
	v_lshlrev_b64 v[18:19], 12, v[18:19]
	v_lshl_add_u64 v[12:13], v[8:9], 0, v[12:13]
	v_lshl_add_u64 v[16:17], v[8:9], 0, v[16:17]
	v_lshl_add_u64 v[42:43], v[8:9], 0, v[18:19]
	global_load_dword v50, v[10:11], off nt
	global_load_dword v51, v[12:13], off nt
	global_load_dword v24, v[14:15], off nt
	global_load_dword v25, v[16:17], off nt
	global_load_dword v46, v[20:21], off nt
	global_load_dword v47, v[38:39], off nt
	global_load_dword v18, v[40:41], off nt
	global_load_dword v19, v[42:43], off nt
	v_or_b32_e32 v14, 20, v22
	v_ashrrev_i32_e32 v15, 31, v14
	v_lshlrev_b64 v[14:15], 12, v[14:15]
	v_lshl_add_u64 v[16:17], v[8:9], 0, v[14:15]
	v_or_b32_e32 v14, 22, v22
	v_ashrrev_i32_e32 v15, 31, v14
	v_lshlrev_b64 v[14:15], 12, v[14:15]
	v_lshl_add_u64 v[38:39], v[8:9], 0, v[14:15]
	v_or_b32_e32 v14, 24, v22
	v_ashrrev_i32_e32 v15, 31, v14
	v_lshlrev_b64 v[14:15], 12, v[14:15]
	v_lshl_add_u64 v[40:41], v[8:9], 0, v[14:15]
	v_or_b32_e32 v14, 26, v22
	v_ashrrev_i32_e32 v15, 31, v14
	v_lshlrev_b64 v[14:15], 12, v[14:15]
	v_lshl_add_u64 v[44:45], v[8:9], 0, v[14:15]
	v_or_b32_e32 v14, 28, v22
	v_ashrrev_i32_e32 v15, 31, v14
	v_or_b32_e32 v10, 16, v22
	v_lshlrev_b64 v[14:15], 12, v[14:15]
	v_ashrrev_i32_e32 v11, 31, v10
	v_or_b32_e32 v12, 18, v22
	v_lshl_add_u64 v[52:53], v[8:9], 0, v[14:15]
	v_or_b32_e32 v14, 30, v22
	v_lshlrev_b64 v[10:11], 12, v[10:11]
	v_ashrrev_i32_e32 v13, 31, v12
	v_ashrrev_i32_e32 v15, 31, v14
	v_lshl_add_u64 v[10:11], v[8:9], 0, v[10:11]
	v_lshlrev_b64 v[12:13], 12, v[12:13]
	v_lshlrev_b64 v[14:15], 12, v[14:15]
	v_lshl_add_u64 v[12:13], v[8:9], 0, v[12:13]
	v_lshl_add_u64 v[54:55], v[8:9], 0, v[14:15]
	global_load_dword v48, v[10:11], off nt
	global_load_dword v49, v[12:13], off nt
	global_load_dword v20, v[16:17], off nt
	global_load_dword v21, v[38:39], off nt
	global_load_dword v42, v[40:41], off nt
	global_load_dword v43, v[44:45], off nt
	global_load_dword v14, v[52:53], off nt
	global_load_dword v15, v[54:55], off nt
	v_or_b32_e32 v10, 32, v22
	v_ashrrev_i32_e32 v11, 31, v10
	v_lshlrev_b64 v[10:11], 12, v[10:11]
	v_lshl_add_u64 v[12:13], v[8:9], 0, v[10:11]
	v_or_b32_e32 v10, 34, v22
	v_ashrrev_i32_e32 v11, 31, v10
	v_lshlrev_b64 v[10:11], 12, v[10:11]
	v_lshl_add_u64 v[40:41], v[8:9], 0, v[10:11]
	v_or_b32_e32 v10, 36, v22
	v_ashrrev_i32_e32 v11, 31, v10
	v_lshlrev_b64 v[10:11], 12, v[10:11]
	v_lshl_add_u64 v[52:53], v[8:9], 0, v[10:11]
	v_or_b32_e32 v10, 38, v22
	v_ashrrev_i32_e32 v11, 31, v10
	v_lshlrev_b64 v[10:11], 12, v[10:11]
	v_lshl_add_u64 v[54:55], v[8:9], 0, v[10:11]
	v_or_b32_e32 v10, 40, v22
	v_ashrrev_i32_e32 v11, 31, v10
	v_lshlrev_b64 v[10:11], 12, v[10:11]
	v_lshl_add_u64 v[56:57], v[8:9], 0, v[10:11]
	v_or_b32_e32 v10, 42, v22
	v_ashrrev_i32_e32 v11, 31, v10
	v_lshlrev_b64 v[10:11], 12, v[10:11]
	v_lshl_add_u64 v[58:59], v[8:9], 0, v[10:11]
	v_or_b32_e32 v10, 44, v22
	v_ashrrev_i32_e32 v11, 31, v10
	v_lshlrev_b64 v[10:11], 12, v[10:11]
	v_lshl_add_u64 v[60:61], v[8:9], 0, v[10:11]
	v_or_b32_e32 v10, 46, v22
	v_ashrrev_i32_e32 v11, 31, v10
	v_lshlrev_b64 v[10:11], 12, v[10:11]
	v_lshl_add_u64 v[62:63], v[8:9], 0, v[10:11]
	global_load_dword v44, v[12:13], off nt
	global_load_dword v45, v[40:41], off nt
	global_load_dword v16, v[52:53], off nt
	global_load_dword v17, v[54:55], off nt
	global_load_dword v38, v[56:57], off nt
	global_load_dword v39, v[58:59], off nt
	global_load_dword v10, v[60:61], off nt
	global_load_dword v11, v[62:63], off nt
	v_or_b32_e32 v12, 48, v22
	v_ashrrev_i32_e32 v13, 31, v12
	v_lshlrev_b64 v[12:13], 12, v[12:13]
	v_lshl_add_u64 v[52:53], v[8:9], 0, v[12:13]
	v_or_b32_e32 v12, 50, v22
	v_ashrrev_i32_e32 v13, 31, v12
	v_lshlrev_b64 v[12:13], 12, v[12:13]
	v_lshl_add_u64 v[54:55], v[8:9], 0, v[12:13]
	v_or_b32_e32 v12, 52, v22
	v_ashrrev_i32_e32 v13, 31, v12
	v_lshlrev_b64 v[12:13], 12, v[12:13]
	v_lshl_add_u64 v[56:57], v[8:9], 0, v[12:13]
	v_or_b32_e32 v12, 54, v22
	v_ashrrev_i32_e32 v13, 31, v12
	v_lshlrev_b64 v[12:13], 12, v[12:13]
	v_lshl_add_u64 v[58:59], v[8:9], 0, v[12:13]
	v_or_b32_e32 v12, 56, v22
	v_ashrrev_i32_e32 v13, 31, v12
	v_lshlrev_b64 v[12:13], 12, v[12:13]
	v_lshl_add_u64 v[60:61], v[8:9], 0, v[12:13]
	v_or_b32_e32 v12, 58, v22
	v_ashrrev_i32_e32 v13, 31, v12
	v_lshlrev_b64 v[12:13], 12, v[12:13]
	v_lshl_add_u64 v[62:63], v[8:9], 0, v[12:13]
	v_or_b32_e32 v12, 60, v22
	v_ashrrev_i32_e32 v13, 31, v12
	v_lshlrev_b64 v[12:13], 12, v[12:13]
	v_lshl_add_u64 v[64:65], v[8:9], 0, v[12:13]
	v_or_b32_e32 v12, 62, v22
	v_ashrrev_i32_e32 v13, 31, v12
	v_lshlrev_b64 v[12:13], 12, v[12:13]
	v_lshl_add_u64 v[66:67], v[8:9], 0, v[12:13]
	global_load_dword v40, v[52:53], off nt
	global_load_dword v41, v[54:55], off nt
	global_load_dword v12, v[56:57], off nt
	global_load_dword v13, v[58:59], off nt
	global_load_dword v35, v[60:61], off nt
	global_load_dword v37, v[62:63], off nt
	global_load_dword v8, v[64:65], off nt
	global_load_dword v9, v[66:67], off nt
	s_and_b64 vcc, exec, s[6:7]
	s_cbranch_vccnz .LBB0_253
	s_ashr_i32 s11, s10, 31
	v_lshl_add_u64 v[22:23], v[22:23], 2, s[0:1]
	v_lshl_add_u64 v[52:53], s[10:11], 0, v[2:3]
	v_lshl_add_u64 v[52:53], v[52:53], 2, s[0:1]
	global_load_dword v56, v[22:23], off nt
	global_load_dword v57, v[52:53], off offset:8
	global_load_dword v54, v[52:53], off offset:16
	global_load_dword v55, v[52:53], off offset:24
	s_waitcnt vmcnt(3)
	v_mul_f32_e32 v52, v50, v56
	s_waitcnt vmcnt(2)
	v_mul_f32_e32 v53, v51, v57
	ds_write2_b32 v31, v52, v53 offset1:66
	s_waitcnt vmcnt(0)
	v_pk_mul_f32 v[22:23], v[24:25], v[54:55]
	s_cbranch_execnz .LBB0_233

; __device__ __forceinline__ void tr_item(const float* __restrict__ W, int K, int Nsrc, int col0, int nvalid, const float* __restrict__ gain, bf16_t* WT, int drow0, int k0, LAS float* scr, int lane) {
;     ...
;     for (int i = 0; i < 32; ++i) { const int kk = 2 * i + (lane >> 5), n = lane & 31; v[i] = 0.f; if (n < nvalid) v[i] = W[(size_t)(k0 + kk) * Nsrc + col0 + n]; }
; __device__ __forceinline__ void conv_job(int kind, const float* W, const float* W2, int K, int Nsrc, int Ndst, const float* gain, bf16_t* WT, LAS float* scr, int gw, int NGW, int lane) {
;     const int nb = Ndst / 32, nitems = (K / 64) * nb;
;     for (int it = gw; it < nitems; it += NGW) {
;         const int kb = it / nb, db = it % nb, d0 = db * 32, k0 = kb * 64; const float* src = W; int col0 = d0, nvalid = 32;
.LBB0_263:
	s_ashr_i32 s0, s9, 31
	s_lshr_b32 s0, s0, 26
	s_add_i32 s0, s9, s0
	s_lshl_b32 s1, s0, 5
	s_andn2_b32 s0, s0, 63
	s_and_b32 s1, s1, 0xfffff800
	v_or_b32_e32 v16, s0, v2
	s_sub_i32 s6, s3, s1
	v_or_b32_e32 v26, 10, v16
	v_or_b32_e32 v30, 12, v16
	v_or_b32_e32 v32, 14, v16
	v_or_b32_e32 v46, 24, v16
	v_or_b32_e32 v48, 26, v16
	v_or_b32_e32 v50, 28, v16
	v_or_b32_e32 v52, 30, v16
	v_ashrrev_i32_e32 v17, 31, v16
	v_or_b32_e32 v18, 2, v16
	v_or_b32_e32 v20, 4, v16
	v_or_b32_e32 v22, 6, v16
	v_or_b32_e32 v24, 8, v16
	v_or_b32_e32 v38, 16, v16
	v_or_b32_e32 v40, 18, v16
	v_or_b32_e32 v42, 20, v16
	v_or_b32_e32 v44, 22, v16
	v_or_b32_e32 v54, 32, v16
	v_or_b32_e32 v56, 34, v16
	v_or_b32_e32 v58, 36, v16
	v_or_b32_e32 v60, 38, v16
	v_or_b32_e32 v62, 40, v16
	v_or_b32_e32 v64, 42, v16
	v_or_b32_e32 v66, 44, v16
	v_or_b32_e32 v68, 46, v16
	v_or_b32_e32 v70, 48, v16
	v_or_b32_e32 v72, 50, v16
	v_or_b32_e32 v74, 52, v16
	v_or_b32_e32 v76, 54, v16
	v_or_b32_e32 v78, 56, v16
	v_or_b32_e32 v80, 58, v16
	v_or_b32_e32 v82, 60, v16
	v_or_b32_e32 v84, 62, v16
	s_ashr_i32 s7, s6, 31
	v_ashrrev_i32_e32 v27, 31, v26
	v_ashrrev_i32_e32 v31, 31, v30
	v_ashrrev_i32_e32 v33, 31, v32
	v_ashrrev_i32_e32 v47, 31, v46
	v_ashrrev_i32_e32 v49, 31, v48
	v_ashrrev_i32_e32 v51, 31, v50
	v_ashrrev_i32_e32 v53, 31, v52
	v_lshlrev_b64 v[16:17], 13, v[16:17]
	v_ashrrev_i32_e32 v19, 31, v18
	v_ashrrev_i32_e32 v21, 31, v20
	v_ashrrev_i32_e32 v23, 31, v22
	v_ashrrev_i32_e32 v25, 31, v24
	v_ashrrev_i32_e32 v39, 31, v38
	v_ashrrev_i32_e32 v41, 31, v40
	v_ashrrev_i32_e32 v43, 31, v42
	v_ashrrev_i32_e32 v45, 31, v44
	v_ashrrev_i32_e32 v55, 31, v54
	v_ashrrev_i32_e32 v57, 31, v56
	v_ashrrev_i32_e32 v59, 31, v58
	v_ashrrev_i32_e32 v61, 31, v60
	v_ashrrev_i32_e32 v63, 31, v62
	v_ashrrev_i32_e32 v65, 31, v64
	v_ashrrev_i32_e32 v67, 31, v66
	v_ashrrev_i32_e32 v69, 31, v68
	v_ashrrev_i32_e32 v71, 31, v70
	v_ashrrev_i32_e32 v73, 31, v72
	v_ashrrev_i32_e32 v75, 31, v74
	v_ashrrev_i32_e32 v77, 31, v76
	v_ashrrev_i32_e32 v79, 31, v78
	v_ashrrev_i32_e32 v81, 31, v80
	v_ashrrev_i32_e32 v83, 31, v82
	v_ashrrev_i32_e32 v85, 31, v84
	v_lshl_add_u64 v[86:87], s[6:7], 2, v[6:7]
	v_lshlrev_b64 v[26:27], 13, v[26:27]
	v_lshlrev_b64 v[30:31], 13, v[30:31]
	v_lshlrev_b64 v[32:33], 13, v[32:33]
	v_lshlrev_b64 v[46:47], 13, v[46:47]
	v_lshlrev_b64 v[48:49], 13, v[48:49]
	v_lshlrev_b64 v[50:51], 13, v[50:51]
	v_lshlrev_b64 v[52:53], 13, v[52:53]
	v_lshlrev_b64 v[18:19], 13, v[18:19]
	v_lshlrev_b64 v[20:21], 13, v[20:21]
	v_lshlrev_b64 v[22:23], 13, v[22:23]
	v_lshlrev_b64 v[24:25], 13, v[24:25]
	v_lshlrev_b64 v[38:39], 13, v[38:39]
	v_lshlrev_b64 v[40:41], 13, v[40:41]
	v_lshlrev_b64 v[42:43], 13, v[42:43]
	v_lshlrev_b64 v[44:45], 13, v[44:45]
	v_lshlrev_b64 v[54:55], 13, v[54:55]
	v_lshlrev_b64 v[56:57], 13, v[56:57]
	v_lshlrev_b64 v[58:59], 13, v[58:59]
	v_lshlrev_b64 v[60:61], 13, v[60:61]
	v_lshlrev_b64 v[62:63], 13, v[62:63]
	v_lshlrev_b64 v[64:65], 13, v[64:65]
	v_lshlrev_b64 v[66:67], 13, v[66:67]
	v_lshlrev_b64 v[68:69], 13, v[68:69]
	v_lshlrev_b64 v[70:71], 13, v[70:71]
	v_lshlrev_b64 v[72:73], 13, v[72:73]
	v_lshlrev_b64 v[74:75], 13, v[74:75]
	v_lshlrev_b64 v[76:77], 13, v[76:77]
	v_lshlrev_b64 v[78:79], 13, v[78:79]
	v_lshlrev_b64 v[80:81], 13, v[80:81]
	v_lshlrev_b64 v[82:83], 13, v[82:83]
	v_lshlrev_b64 v[84:85], 13, v[84:85]
	v_lshl_add_u64 v[16:17], v[86:87], 0, v[16:17]
	v_lshl_add_u64 v[26:27], v[86:87], 0, v[26:27]
	v_lshl_add_u64 v[30:31], v[86:87], 0, v[30:31]
	v_lshl_add_u64 v[32:33], v[86:87], 0, v[32:33]
	v_lshl_add_u64 v[46:47], v[86:87], 0, v[46:47]
	v_lshl_add_u64 v[48:49], v[86:87], 0, v[48:49]
	v_lshl_add_u64 v[50:51], v[86:87], 0, v[50:51]
	v_lshl_add_u64 v[52:53], v[86:87], 0, v[52:53]
	v_lshl_add_u64 v[18:19], v[86:87], 0, v[18:19]
	v_lshl_add_u64 v[20:21], v[86:87], 0, v[20:21]
	v_lshl_add_u64 v[22:23], v[86:87], 0, v[22:23]
	v_lshl_add_u64 v[24:25], v[86:87], 0, v[24:25]
	v_lshl_add_u64 v[38:39], v[86:87], 0, v[38:39]
	v_lshl_add_u64 v[40:41], v[86:87], 0, v[40:41]
	v_lshl_add_u64 v[42:43], v[86:87], 0, v[42:43]
	v_lshl_add_u64 v[44:45], v[86:87], 0, v[44:45]
	v_lshl_add_u64 v[54:55], v[86:87], 0, v[54:55]
	v_lshl_add_u64 v[56:57], v[86:87], 0, v[56:57]
	v_lshl_add_u64 v[58:59], v[86:87], 0, v[58:59]
	v_lshl_add_u64 v[60:61], v[86:87], 0, v[60:61]
	v_lshl_add_u64 v[62:63], v[86:87], 0, v[62:63]
	v_lshl_add_u64 v[64:65], v[86:87], 0, v[64:65]
	v_lshl_add_u64 v[66:67], v[86:87], 0, v[66:67]
	v_lshl_add_u64 v[68:69], v[86:87], 0, v[68:69]
	v_lshl_add_u64 v[70:71], v[86:87], 0, v[70:71]
	v_lshl_add_u64 v[72:73], v[86:87], 0, v[72:73]
	v_lshl_add_u64 v[74:75], v[86:87], 0, v[74:75]
	v_lshl_add_u64 v[76:77], v[86:87], 0, v[76:77]
	v_lshl_add_u64 v[78:79], v[86:87], 0, v[78:79]
	v_lshl_add_u64 v[80:81], v[86:87], 0, v[80:81]
	v_lshl_add_u64 v[82:83], v[86:87], 0, v[82:83]
	v_lshl_add_u64 v[84:85], v[86:87], 0, v[84:85]
	global_load_dword v29, v[16:17], off nt
	global_load_dword v35, v[18:19], off nt
	global_load_dword v37, v[20:21], off nt
	global_load_dword v86, v[22:23], off nt
	global_load_dword v87, v[24:25], off nt
	global_load_dword v88, v[26:27], off nt
	global_load_dword v89, v[30:31], off nt
	global_load_dword v90, v[32:33], off nt
	global_load_dword v91, v[38:39], off nt
	global_load_dword v92, v[40:41], off nt
	global_load_dword v93, v[42:43], off nt
	global_load_dword v94, v[44:45], off nt
	global_load_dword v95, v[46:47], off nt
	global_load_dword v96, v[48:49], off nt
	global_load_dword v97, v[50:51], off nt
	global_load_dword v26, v[52:53], off nt
	global_load_dword v27, v[54:55], off nt
	global_load_dword v30, v[56:57], off nt
	global_load_dword v31, v[58:59], off nt
	global_load_dword v32, v[60:61], off nt
	global_load_dword v33, v[62:63], off nt
	global_load_dword v46, v[64:65], off nt
	global_load_dword v47, v[66:67], off nt
	global_load_dword v48, v[68:69], off nt
	global_load_dword v49, v[70:71], off nt
	global_load_dword v50, v[72:73], off nt
	global_load_dword v51, v[74:75], off nt
	global_load_dword v98, v[76:77], off nt
	global_load_dword v99, v[78:79], off nt
	global_load_dword v100, v[80:81], off nt
	global_load_dword v52, v[82:83], off nt
	global_load_dword v53, v[84:85], off nt
	v_add_u32_e32 v18, s6, v28
	s_ashr_i32 s1, s0, 31
	v_ashrrev_i32_e32 v19, 31, v18
	v_add_u32_e32 v20, 8, v18
	v_add_u32_e32 v22, 16, v18
	v_add_u32_e32 v24, 24, v18
	v_lshl_add_u64 v[16:17], s[0:1], 1, v[4:5]
	v_lshlrev_b64 v[18:19], 10, v[18:19]
	v_ashrrev_i32_e32 v21, 31, v20
	v_ashrrev_i32_e32 v23, 31, v22
	v_ashrrev_i32_e32 v25, 31, v24
	v_lshl_add_u64 v[38:39], v[16:17], 0, v[18:19]
	v_lshlrev_b64 v[18:19], 10, v[20:21]
	v_lshlrev_b64 v[20:21], 10, v[22:23]
	v_lshlrev_b64 v[22:23], 10, v[24:25]
	s_waitcnt vmcnt(30)
; #define LAS __attribute__((address_space(3)))
; __device__ __forceinline__ unsigned pk2(float lo, float hi) { const f32x2 v = {lo, hi}; return __builtin_bit_cast(unsigned, __builtin_convertvector(v, hbf2)); }
; __device__ __forceinline__ void tr_item(const float* __restrict__ W, int K, int Nsrc, int col0, int nvalid, const float* __restrict__ gain, bf16_t* WT, int drow0, int k0, LAS float* scr, int lane) {
;     ...
;     for (int i = 0; i < 32; ++i) { const int kk = 2 * i + (lane >> 5), n = lane & 31; float x = v[i]; if (gain) x *= gain[k0 + kk]; scr[kk * 33 + n] = x; }
;     const int c = lane & 7;
; #pragma unroll
;     for (int j = 0; j < 4; ++j) { const int n = (lane >> 3) + 8 * j; const LAS float* s = scr + (8 * c) * 33 + n;
;         u32x4 o; o.x = pk2(s[0 * 33], s[1 * 33]); o.y = pk2(s[2 * 33], s[3 * 33]); o.z = pk2(s[4 * 33], s[5 * 33]); o.w = pk2(s[6 * 33], s[7 * 33]);
;         *(u32x4*)(WT + (size_t)(drow0 + n) * K + k0 + 8 * c) = o; }
	ds_write2_b32 v8, v29, v35 offset1:66
	s_waitcnt vmcnt(28)
	ds_write2_b32 v8, v37, v86 offset0:132 offset1:198
	s_waitcnt vmcnt(26)
	ds_write2_b32 v9, v87, v88 offset0:8 offset1:74
	s_waitcnt vmcnt(24)
	ds_write2_b32 v9, v89, v90 offset0:140 offset1:206
	s_waitcnt vmcnt(22)
	ds_write2_b32 v10, v91, v92 offset0:16 offset1:82
	s_waitcnt vmcnt(20)
	ds_write2_b32 v10, v93, v94 offset0:148 offset1:214
	s_waitcnt vmcnt(18)
	ds_write2_b32 v11, v95, v96 offset0:24 offset1:90
	s_waitcnt vmcnt(16)
	ds_write2_b32 v11, v97, v26 offset0:156 offset1:222
	s_waitcnt vmcnt(14)
	ds_write2_b32 v12, v27, v30 offset0:32 offset1:98
	s_waitcnt vmcnt(12)
	ds_write2_b32 v12, v31, v32 offset0:164 offset1:230
	s_waitcnt vmcnt(10)
	ds_write2_b32 v13, v33, v46 offset0:40 offset1:106
	s_waitcnt vmcnt(8)
	ds_write2_b32 v13, v47, v48 offset0:172 offset1:238
	s_waitcnt vmcnt(6)
	ds_write2_b32 v14, v49, v50 offset0:48 offset1:114
	s_waitcnt vmcnt(4)
	ds_write2_b32 v14, v51, v98 offset0:180 offset1:246
	s_waitcnt vmcnt(2)
	ds_write2_b32 v15, v99, v100 offset0:56 offset1:122
	s_waitcnt vmcnt(0)
	ds_write2_b32 v15, v52, v53 offset0:188 offset1:254
	v_lshl_add_u64 v[42:43], v[16:17], 0, v[20:21]
	v_lshl_add_u64 v[44:45], v[16:17], 0, v[22:23]
	ds_read2_b32 v[20:21], v3 offset0:33 offset1:41
	ds_read2_b32 v[22:23], v3 offset1:8
	ds_read2_b32 v[24:25], v3 offset0:66 offset1:74
	ds_read2_b32 v[26:27], v3 offset0:99 offset1:107
	ds_read2_b32 v[30:31], v3 offset0:132 offset1:140
	ds_read2_b32 v[32:33], v3 offset0:165 offset1:173
	ds_read2_b32 v[46:47], v3 offset0:198 offset1:206
	ds_read2_b32 v[48:49], v3 offset0:231 offset1:239
	ds_read2_b32 v[50:51], v3 offset0:16 offset1:24
	ds_read2_b32 v[52:53], v3 offset0:49 offset1:57
	ds_read2_b32 v[54:55], v3 offset0:82 offset1:90
	ds_read2_b32 v[56:57], v3 offset0:115 offset1:123
	ds_read2_b32 v[58:59], v3 offset0:148 offset1:156
	ds_read2_b32 v[60:61], v3 offset0:181 offset1:189
	ds_read2_b32 v[62:63], v3 offset0:214 offset1:222
	ds_read2_b32 v[64:65], v3 offset0:247 offset1:255
	s_add_i32 s9, s9, s62
	s_add_i32 s3, s3, s8
	s_cmpk_lt_i32 s9, 0x200
	v_lshl_add_u64 v[40:41], v[16:17], 0, v[18:19]
	s_waitcnt lgkmcnt(14)
	v_cvt_pk_bf16_f32 v16, v22, v20
	s_waitcnt lgkmcnt(12)
	v_cvt_pk_bf16_f32 v17, v24, v26
	s_waitcnt lgkmcnt(10)
	v_cvt_pk_bf16_f32 v18, v30, v32
	s_waitcnt lgkmcnt(8)
	v_cvt_pk_bf16_f32 v19, v46, v48
	v_cvt_pk_bf16_f32 v20, v23, v21
	v_cvt_pk_bf16_f32 v21, v25, v27
	v_cvt_pk_bf16_f32 v22, v31, v33
	v_cvt_pk_bf16_f32 v23, v47, v49
	s_waitcnt lgkmcnt(6)
	v_cvt_pk_bf16_f32 v24, v50, v52
	s_waitcnt lgkmcnt(4)
	v_cvt_pk_bf16_f32 v25, v54, v56
	s_waitcnt lgkmcnt(2)
	v_cvt_pk_bf16_f32 v26, v58, v60
	s_waitcnt lgkmcnt(0)
	v_cvt_pk_bf16_f32 v27, v62, v64
	v_cvt_pk_bf16_f32 v30, v51, v53
	v_cvt_pk_bf16_f32 v31, v55, v57
	v_cvt_pk_bf16_f32 v32, v59, v61
	v_cvt_pk_bf16_f32 v33, v63, v65
	global_store_dwordx4 v[38:39], v[16:19], off
	global_store_dwordx4 v[40:41], v[20:23], off
	global_store_dwordx4 v[42:43], v[24:27], off
	global_store_dwordx4 v[44:45], v[30:33], off
	s_cbranch_scc1 .LBB0_263

; __device__ __forceinline__ u64 ssq_fix(float v) { return (u64)(v * 4294967296.f); }
; __device__ __forceinline__ void rows_to_bf16(const float* X, bf16_t* XB, float* ssqf, u64* ssqx, int nrows, int gw, int NGW, int lane) {
;     for (int row = gw; row < nrows; row += NGW) {
;         const f32x4* p = (const f32x4*)(X + (size_t)row * DM) + lane; f32x4 v[8]; float ss = 0.f;
; #pragma unroll
;         for (int j = 0; j < 8; ++j) { v[j] = p[64 * j]; ss += (v[j].x * v[j].x + v[j].y * v[j].y) + (v[j].z * v[j].z + v[j].w * v[j].w); }
;         ss = wave_sum(ss); if (lane == 0) { if (ssqf) ssqf[row] = ss; else ssqx[row] = ssq_fix(ss); }
.LBB0_267:
	global_load_dwordx4 v[2:5], v[40:41], off offset:-4096 nt
	global_load_dwordx4 v[6:9], v[40:41], off offset:-3072 nt
	global_load_dwordx4 v[10:13], v[40:41], off offset:-2048 nt
	global_load_dwordx4 v[14:17], v[40:41], off offset:-1024 nt
	global_load_dwordx4 v[18:21], v[40:41], off nt
	global_load_dwordx4 v[22:25], v[40:41], off offset:1024 nt
	global_load_dwordx4 v[26:29], v[40:41], off offset:2048 nt
	global_load_dwordx4 v[30:33], v[40:41], off offset:3072 nt
	s_waitcnt vmcnt(7)
	v_mul_f32_e32 v37, v3, v3
	s_waitcnt lgkmcnt(0)
	v_mul_f32_e32 v49, v5, v5
	s_waitcnt vmcnt(6)
	v_mul_f32_e32 v50, v7, v7
	v_mul_f32_e32 v51, v9, v9
	s_waitcnt vmcnt(5)
	v_mul_f32_e32 v52, v11, v11
	v_mul_f32_e32 v53, v13, v13
	v_fmac_f32_e32 v37, v2, v2
	v_fmac_f32_e32 v49, v4, v4
	v_fmac_f32_e32 v50, v6, v6
	v_fmac_f32_e32 v51, v8, v8
	s_waitcnt vmcnt(4)
	v_mul_f32_e32 v54, v15, v15
	v_mul_f32_e32 v55, v17, v17
	v_fmac_f32_e32 v52, v10, v10
	v_fmac_f32_e32 v53, v12, v12
	v_add_f32_e32 v37, v37, v49
	v_add_f32_e32 v49, v50, v51
	s_waitcnt vmcnt(3)
	v_mul_f32_e32 v56, v19, v19
	v_mul_f32_e32 v57, v21, v21
	v_fmac_f32_e32 v54, v14, v14
	v_fmac_f32_e32 v55, v16, v16
	v_add_f32_e32 v50, v52, v53
	v_add_f32_e32 v37, v37, v49
	s_waitcnt vmcnt(2)
	v_mul_f32_e32 v58, v23, v23
	v_mul_f32_e32 v59, v25, v25
	v_fmac_f32_e32 v56, v18, v18
	v_fmac_f32_e32 v57, v20, v20
	v_add_f32_e32 v51, v54, v55
	v_add_f32_e32 v37, v37, v50
	s_waitcnt vmcnt(1)
	v_mul_f32_e32 v60, v27, v27
	v_mul_f32_e32 v61, v29, v29
	v_fmac_f32_e32 v58, v22, v22
	v_fmac_f32_e32 v59, v24, v24
	v_add_f32_e32 v52, v56, v57
	v_add_f32_e32 v37, v37, v51
	s_waitcnt vmcnt(0)
	v_mul_f32_e32 v62, v31, v31
	v_mul_f32_e32 v63, v33, v33
	v_fmac_f32_e32 v60, v26, v26
	v_fmac_f32_e32 v61, v28, v28
	v_add_f32_e32 v53, v58, v59
	v_add_f32_e32 v37, v37, v52
	v_fmac_f32_e32 v62, v30, v30
	v_fmac_f32_e32 v63, v32, v32
	v_add_f32_e32 v54, v60, v61
	v_add_f32_e32 v37, v37, v53
	v_add_f32_e32 v37, v37, v54
	v_add_f32_e32 v49, v62, v63
	v_add_f32_e32 v37, v37, v49
	ds_bpermute_b32 v49, v35, v37
	s_waitcnt lgkmcnt(0)
	v_add_f32_e32 v37, v37, v49
	ds_bpermute_b32 v49, v44, v37
	s_waitcnt lgkmcnt(0)
	v_add_f32_e32 v37, v37, v49
	ds_bpermute_b32 v49, v45, v37
	s_waitcnt lgkmcnt(0)
	v_add_f32_e32 v37, v37, v49
	ds_bpermute_b32 v49, v46, v37
	s_waitcnt lgkmcnt(0)
	v_add_f32_e32 v37, v37, v49
	ds_bpermute_b32 v49, v47, v37
	s_waitcnt lgkmcnt(0)
	v_add_f32_e32 v37, v37, v49
	ds_bpermute_b32 v49, v48, v37
	s_and_saveexec_b64 s[20:21], vcc
	s_cbranch_execz .LBB0_266
	s_waitcnt lgkmcnt(0)
	v_add_f32_e32 v37, v37, v49
	v_mul_f32_e32 v37, 0x4f800000, v37
	v_trunc_f32_e32 v37, v37
	v_mul_f32_e32 v49, 0x2f800000, v37
	v_floor_f32_e32 v49, v49
	v_fmac_f32_e32 v37, 0xcf800000, v49
	v_cvt_u32_f32_e32 v50, v37
	v_cvt_u32_f32_e32 v51, v49
	global_store_dwordx2 v39, v[50:51], s[0:1]
	s_branch .LBB0_266

; __device__ __forceinline__ u64 ssq_fix(float v) { return (u64)(v * 4294967296.f); }
; __device__ __forceinline__ void rows_to_bf16(const float* X, bf16_t* XB, float* ssqf, u64* ssqx, int nrows, int gw, int NGW, int lane) {
;     for (int row = gw; row < nrows; row += NGW) {
;         const f32x4* p = (const f32x4*)(X + (size_t)row * DM) + lane; f32x4 v[8]; float ss = 0.f;
; #pragma unroll
;         for (int j = 0; j < 8; ++j) { v[j] = p[64 * j]; ss += (v[j].x * v[j].x + v[j].y * v[j].y) + (v[j].z * v[j].z + v[j].w * v[j].w); }
;         ss = wave_sum(ss); if (lane == 0) { if (ssqf) ssqf[row] = ss; else ssqx[row] = ssq_fix(ss); }
.LBB0_272:
	global_load_dwordx4 v[2:5], v[40:41], off offset:-4096 nt
	global_load_dwordx4 v[6:9], v[40:41], off offset:-3072 nt
	global_load_dwordx4 v[10:13], v[40:41], off offset:-2048 nt
	global_load_dwordx4 v[14:17], v[40:41], off offset:-1024 nt
	global_load_dwordx4 v[18:21], v[40:41], off nt
	global_load_dwordx4 v[22:25], v[40:41], off offset:1024 nt
	global_load_dwordx4 v[26:29], v[40:41], off offset:2048 nt
	global_load_dwordx4 v[30:33], v[40:41], off offset:3072 nt
	s_waitcnt vmcnt(7)
	v_mul_f32_e32 v1, v3, v3
	s_waitcnt lgkmcnt(0)
	v_mul_f32_e32 v38, v5, v5
	s_waitcnt vmcnt(6)
	v_mul_f32_e32 v47, v7, v7
	v_mul_f32_e32 v48, v9, v9
	s_waitcnt vmcnt(5)
	v_mul_f32_e32 v49, v11, v11
	v_mul_f32_e32 v50, v13, v13
	v_fmac_f32_e32 v1, v2, v2
	v_fmac_f32_e32 v38, v4, v4
	v_fmac_f32_e32 v47, v6, v6
	v_fmac_f32_e32 v48, v8, v8
	s_waitcnt vmcnt(4)
	v_mul_f32_e32 v51, v15, v15
	v_mul_f32_e32 v52, v17, v17
	v_fmac_f32_e32 v49, v10, v10
	v_fmac_f32_e32 v50, v12, v12
	v_add_f32_e32 v1, v1, v38
	v_add_f32_e32 v38, v47, v48
	s_waitcnt vmcnt(3)
	v_mul_f32_e32 v53, v19, v19
	v_mul_f32_e32 v54, v21, v21
	v_fmac_f32_e32 v51, v14, v14
	v_fmac_f32_e32 v52, v16, v16
	v_add_f32_e32 v47, v49, v50
	v_add_f32_e32 v1, v1, v38
	s_waitcnt vmcnt(2)
	v_mul_f32_e32 v55, v23, v23
	v_mul_f32_e32 v56, v25, v25
	v_fmac_f32_e32 v53, v18, v18
	v_fmac_f32_e32 v54, v20, v20
	v_add_f32_e32 v48, v51, v52
	v_add_f32_e32 v1, v1, v47
	s_waitcnt vmcnt(1)
	v_mul_f32_e32 v57, v27, v27
	v_mul_f32_e32 v58, v29, v29
	v_fmac_f32_e32 v55, v22, v22
	v_fmac_f32_e32 v56, v24, v24
	v_add_f32_e32 v49, v53, v54
	v_add_f32_e32 v1, v1, v48
	s_waitcnt vmcnt(0)
	v_mul_f32_e32 v59, v31, v31
	v_mul_f32_e32 v60, v33, v33
	v_fmac_f32_e32 v57, v26, v26
	v_fmac_f32_e32 v58, v28, v28
	v_add_f32_e32 v50, v55, v56
	v_add_f32_e32 v1, v1, v49
	v_fmac_f32_e32 v59, v30, v30
	v_fmac_f32_e32 v60, v32, v32
	v_add_f32_e32 v51, v57, v58
	v_add_f32_e32 v1, v1, v50
	v_add_f32_e32 v1, v1, v51
	v_add_f32_e32 v38, v59, v60
	v_add_f32_e32 v1, v1, v38
	ds_bpermute_b32 v38, v35, v1
	s_waitcnt lgkmcnt(0)
	v_add_f32_e32 v1, v1, v38
	ds_bpermute_b32 v38, v42, v1
	s_waitcnt lgkmcnt(0)
	v_add_f32_e32 v1, v1, v38
	ds_bpermute_b32 v38, v43, v1
	s_waitcnt lgkmcnt(0)
	v_add_f32_e32 v1, v1, v38
	ds_bpermute_b32 v38, v44, v1
	s_waitcnt lgkmcnt(0)
	v_add_f32_e32 v1, v1, v38
	ds_bpermute_b32 v38, v45, v1
	s_waitcnt lgkmcnt(0)
	v_add_f32_e32 v1, v1, v38
	ds_bpermute_b32 v38, v46, v1
	s_and_saveexec_b64 s[10:11], vcc
	s_cbranch_execz .LBB0_271
	s_waitcnt lgkmcnt(0)
	v_add_f32_e32 v1, v1, v38
	global_store_dword v39, v1, s[0:1]
	s_branch .LBB0_271

; __device__ __forceinline__ unsigned pk2(float lo, float hi) { const f32x2 v = {lo, hi}; return __builtin_bit_cast(unsigned, __builtin_convertvector(v, hbf2)); }
;     __device__ __forceinline__ void operator()(const f32x4 (&acc)[2][2][4][2], const Unit& u, int wr, int wc, int fr, int fq, LAS f32x4* rsc, bool reuse) const {
;     ...
;                 const bool is_ba = (baf != nullptr) && (u.pn * BM == C_BA);
;                 const bool is_gdn = (halo != nullptr) && (u.pn * BM >= C_GDN) && (u.pn * BM < C_Z);
; #pragma unroll
;                 for (int ai = 0; ai < 2; ++ai)
; #pragma unroll
;                     for (int m = 0; m < 4; ++m) {
;                         const int row = row0 + ai * HALF + m * 16; const float r = rs[ai][m];
; #pragma unroll
;                         for (int bj = 0; bj < 2; ++bj) {
;                             const int col = u.pn * BM + bj * HALF + cl;
;                             const f32x4 v0 = acc[ai][bj][m][0] * r, v1 = acc[ai][bj][m][1] * r;
;                             u32x4 w; w.x = pk2(v0[0], v0[1]); w.y = pk2(v0[2], v0[3]); w.z = pk2(v1[0], v1[1]); w.w = pk2(v1[2], v1[3]);
;                             if (is_ba) { if (bj == 0 && cl < 16) { *(f32x4*)(baf + (size_t)row * 16 + cl) = v0; *(f32x4*)(baf + (size_t)row * 16 + cl + 4) = v1; } }
;                             else *(u32x4*)(outb + (size_t)row * ldo + col) = w;
.LBB0_592:
	s_cmp_eq_u64 s[18:19], 0
	s_cselect_b64 s[0:1], -1, 0
	s_cmp_lg_u32 s73, 44
	s_cselect_b64 s[20:21], -1, 0
	s_or_b64 s[0:1], s[0:1], s[20:21]
	v_lshl_or_b32 v160, s73, 8, v204
	v_pk_mul_f32 v[142:143], v[130:131], v[136:137] op_sel_hi:[1,0]
	v_pk_mul_f32 v[140:141], v[128:129], v[136:137] op_sel_hi:[1,0]
	v_pk_mul_f32 v[146:147], v[122:123], v[136:137] op_sel_hi:[1,0]
	v_pk_mul_f32 v[144:145], v[120:121], v[136:137] op_sel_hi:[1,0]
	s_mov_b64 s[20:21], -1
	s_and_b64 vcc, exec, s[0:1]
	v_ashrrev_i32_e32 v161, 31, v160
	s_cbranch_vccz .LBB0_648
	v_mad_i64_i32 v[162:163], s[20:21], s72, v210, 0
	v_lshl_add_u64 v[162:163], v[162:163], 1, s[14:15]
	v_cvt_pk_bf16_f32 v148, v140, v141
	v_cvt_pk_bf16_f32 v149, v142, v143
	v_cvt_pk_bf16_f32 v150, v144, v145
	v_cvt_pk_bf16_f32 v151, v146, v147
	v_lshl_add_u64 v[162:163], v[160:161], 1, v[162:163]
	flat_store_dwordx4 v[162:163], v[148:151] nt
	s_cbranch_execz .LBB0_649

; __device__ __forceinline__ unsigned pk2(float lo, float hi) { const f32x2 v = {lo, hi}; return __builtin_bit_cast(unsigned, __builtin_convertvector(v, hbf2)); }
;     __device__ __forceinline__ void operator()(const f32x4 (&acc)[2][2][4][2], const Unit& u, int wr, int wc, int fr, int fq, LAS f32x4* rsc, bool reuse) const {
;     ...
;                     for (int m = 0; m < 4; ++m) {
;                         const int row = row0 + ai * HALF + m * 16; const float r = rs[ai][m];
; #pragma unroll
;                         for (int bj = 0; bj < 2; ++bj) {
;                             const int col = u.pn * BM + bj * HALF + cl;
;                             const f32x4 v0 = acc[ai][bj][m][0] * r, v1 = acc[ai][bj][m][1] * r;
;                             u32x4 w; w.x = pk2(v0[0], v0[1]); w.y = pk2(v0[2], v0[3]); w.z = pk2(v1[0], v1[1]); w.w = pk2(v1[2], v1[3]);
;                             if (is_ba) { if (bj == 0 && cl < 16) { *(f32x4*)(baf + (size_t)row * 16 + cl) = v0; *(f32x4*)(baf + (size_t)row * 16 + cl + 4) = v1; } }
;                             else *(u32x4*)(outb + (size_t)row * ldo + col) = w;
.LBB0_595:
	v_mov_b32_e32 v137, v136
	v_mov_b32_e32 v142, v136
	v_mov_b32_e32 v143, v136
	v_pk_mul_f32 v[144:145], v[126:127], v[142:143]
	v_pk_mul_f32 v[140:141], v[124:125], v[136:137]
	s_nop 0
	v_cvt_pk_bf16_f32 v140, v140, v141
	v_cvt_pk_bf16_f32 v141, v144, v145
	v_pk_mul_f32 v[144:145], v[118:119], v[142:143]
	v_pk_mul_f32 v[142:143], v[116:117], v[136:137]
	s_nop 0
	v_cvt_pk_bf16_f32 v142, v142, v143
	v_cvt_pk_bf16_f32 v143, v144, v145
	v_mad_i64_i32 v[144:145], s[0:1], s72, v210, 0
	v_lshl_add_u64 v[144:145], v[144:145], 1, s[14:15]
	v_lshl_add_u64 v[144:145], v[160:161], 1, v[144:145]
	flat_store_dwordx4 v[144:145], v[140:143] offset:256 nt
.LBB0_596:
	v_or_b32_e32 v148, 16, v210
	v_ashrrev_i32_e32 v149, 31, v148
	v_pk_mul_f32 v[142:143], v[114:115], v[158:159] op_sel_hi:[1,0]
	v_pk_mul_f32 v[140:141], v[112:113], v[158:159] op_sel_hi:[1,0]
	v_pk_mul_f32 v[146:147], v[106:107], v[158:159] op_sel_hi:[1,0]
	v_pk_mul_f32 v[144:145], v[104:105], v[158:159] op_sel_hi:[1,0]
	s_and_b64 vcc, exec, s[48:49]
	s_mov_b64 s[0:1], -1
	s_cbranch_vccnz .LBB0_652
	v_mad_i64_i32 v[150:151], s[0:1], s72, v148, 0
	v_lshl_add_u64 v[150:151], v[150:151], 1, s[14:15]
	v_cvt_pk_bf16_f32 v162, v140, v141
	v_cvt_pk_bf16_f32 v163, v142, v143
	v_cvt_pk_bf16_f32 v164, v144, v145
	v_cvt_pk_bf16_f32 v165, v146, v147
	v_lshl_add_u64 v[150:151], v[160:161], 1, v[150:151]
	flat_store_dwordx4 v[150:151], v[162:165] nt
	s_cbranch_execz .LBB0_653

; __device__ __forceinline__ unsigned pk2(float lo, float hi) { const f32x2 v = {lo, hi}; return __builtin_bit_cast(unsigned, __builtin_convertvector(v, hbf2)); }
;     __device__ __forceinline__ void operator()(const f32x4 (&acc)[2][2][4][2], const Unit& u, int wr, int wc, int fr, int fq, LAS f32x4* rsc, bool reuse) const {
;     ...
;                     for (int m = 0; m < 4; ++m) {
;                         const int row = row0 + ai * HALF + m * 16; const float r = rs[ai][m];
; #pragma unroll
;                         for (int bj = 0; bj < 2; ++bj) {
;                             const int col = u.pn * BM + bj * HALF + cl;
;                             const f32x4 v0 = acc[ai][bj][m][0] * r, v1 = acc[ai][bj][m][1] * r;
;                             u32x4 w; w.x = pk2(v0[0], v0[1]); w.y = pk2(v0[2], v0[3]); w.z = pk2(v1[0], v1[1]); w.w = pk2(v1[2], v1[3]);
;                             if (is_ba) { if (bj == 0 && cl < 16) { *(f32x4*)(baf + (size_t)row * 16 + cl) = v0; *(f32x4*)(baf + (size_t)row * 16 + cl + 4) = v1; } }
;                             else *(u32x4*)(outb + (size_t)row * ldo + col) = w;
.LBB0_599:
	v_mov_b32_e32 v159, v158
	v_mov_b32_e32 v142, v158
	v_mov_b32_e32 v143, v158
	v_pk_mul_f32 v[144:145], v[110:111], v[142:143]
	v_pk_mul_f32 v[140:141], v[108:109], v[158:159]
	s_nop 0
	v_cvt_pk_bf16_f32 v140, v140, v141
	v_cvt_pk_bf16_f32 v141, v144, v145
	v_pk_mul_f32 v[144:145], v[102:103], v[142:143]
	v_pk_mul_f32 v[142:143], v[100:101], v[158:159]
	s_nop 0
	v_cvt_pk_bf16_f32 v142, v142, v143
	v_cvt_pk_bf16_f32 v143, v144, v145
	v_mad_i64_i32 v[144:145], s[0:1], s72, v148, 0
	v_lshl_add_u64 v[144:145], v[144:145], 1, s[14:15]
	v_lshl_add_u64 v[144:145], v[160:161], 1, v[144:145]
	flat_store_dwordx4 v[144:145], v[140:143] offset:256 nt
.LBB0_600:
	v_or_b32_e32 v148, 32, v210
	v_ashrrev_i32_e32 v149, 31, v148
	v_pk_mul_f32 v[142:143], v[98:99], v[138:139] op_sel_hi:[1,0]
	v_pk_mul_f32 v[140:141], v[96:97], v[138:139] op_sel_hi:[1,0]
	v_pk_mul_f32 v[146:147], v[90:91], v[138:139] op_sel_hi:[1,0]
	v_pk_mul_f32 v[144:145], v[88:89], v[138:139] op_sel_hi:[1,0]
	s_and_b64 vcc, exec, s[48:49]
	s_mov_b64 s[0:1], -1
	s_cbranch_vccnz .LBB0_656
	v_mad_i64_i32 v[150:151], s[0:1], s72, v148, 0
	v_lshl_add_u64 v[150:151], v[150:151], 1, s[14:15]
	v_cvt_pk_bf16_f32 v162, v140, v141
	v_cvt_pk_bf16_f32 v163, v142, v143
	v_cvt_pk_bf16_f32 v164, v144, v145
	v_cvt_pk_bf16_f32 v165, v146, v147
	v_lshl_add_u64 v[150:151], v[160:161], 1, v[150:151]
	flat_store_dwordx4 v[150:151], v[162:165] nt
	s_cbranch_execz .LBB0_657

; __device__ __forceinline__ unsigned pk2(float lo, float hi) { const f32x2 v = {lo, hi}; return __builtin_bit_cast(unsigned, __builtin_convertvector(v, hbf2)); }
;     __device__ __forceinline__ void operator()(const f32x4 (&acc)[2][2][4][2], const Unit& u, int wr, int wc, int fr, int fq, LAS f32x4* rsc, bool reuse) const {
;     ...
;                     for (int m = 0; m < 4; ++m) {
;                         const int row = row0 + ai * HALF + m * 16; const float r = rs[ai][m];
; #pragma unroll
;                         for (int bj = 0; bj < 2; ++bj) {
;                             const int col = u.pn * BM + bj * HALF + cl;
;                             const f32x4 v0 = acc[ai][bj][m][0] * r, v1 = acc[ai][bj][m][1] * r;
;                             u32x4 w; w.x = pk2(v0[0], v0[1]); w.y = pk2(v0[2], v0[3]); w.z = pk2(v1[0], v1[1]); w.w = pk2(v1[2], v1[3]);
;                             if (is_ba) { if (bj == 0 && cl < 16) { *(f32x4*)(baf + (size_t)row * 16 + cl) = v0; *(f32x4*)(baf + (size_t)row * 16 + cl + 4) = v1; } }
;                             else *(u32x4*)(outb + (size_t)row * ldo + col) = w;
.LBB0_603:
	v_mov_b32_e32 v142, v138
	v_mov_b32_e32 v143, v138
	v_mov_b32_e32 v139, v138
	v_pk_mul_f32 v[144:145], v[94:95], v[138:139]
	v_pk_mul_f32 v[140:141], v[92:93], v[142:143]
	v_pk_mul_f32 v[142:143], v[84:85], v[142:143]
	v_cvt_pk_bf16_f32 v140, v140, v141
	v_cvt_pk_bf16_f32 v141, v144, v145
	v_pk_mul_f32 v[144:145], v[86:87], v[138:139]
	v_cvt_pk_bf16_f32 v142, v142, v143
	v_cvt_pk_bf16_f32 v143, v144, v145
	v_mad_i64_i32 v[144:145], s[0:1], s72, v148, 0
	v_lshl_add_u64 v[144:145], v[144:145], 1, s[14:15]
	v_lshl_add_u64 v[144:145], v[160:161], 1, v[144:145]
	flat_store_dwordx4 v[144:145], v[140:143] offset:256 nt
.LBB0_604:
	v_or_b32_e32 v162, 48, v210
	v_pk_mul_f32 v[146:147], v[82:83], v[156:157] op_sel_hi:[1,0]
	v_pk_mul_f32 v[144:145], v[80:81], v[156:157] op_sel_hi:[1,0]
	v_pk_mul_f32 v[150:151], v[74:75], v[156:157] op_sel_hi:[1,0]
	v_pk_mul_f32 v[148:149], v[72:73], v[156:157] op_sel_hi:[1,0]
	v_ashrrev_i32_e32 v163, 31, v162
	v_cvt_pk_bf16_f32 v140, v144, v145
	v_cvt_pk_bf16_f32 v141, v146, v147
	v_cvt_pk_bf16_f32 v142, v148, v149
	v_cvt_pk_bf16_f32 v143, v150, v151
	s_and_b64 vcc, exec, s[48:49]
	s_mov_b64 s[0:1], -1
	s_cbranch_vccnz .LBB0_606
	v_mad_i64_i32 v[164:165], s[0:1], s72, v162, 0
	v_lshl_add_u64 v[164:165], v[164:165], 1, s[14:15]
	v_lshl_add_u64 v[164:165], v[160:161], 1, v[164:165]
	s_mov_b64 s[0:1], 0
	flat_store_dwordx4 v[164:165], v[140:143] nt

; __device__ __forceinline__ unsigned pk2(float lo, float hi) { const f32x2 v = {lo, hi}; return __builtin_bit_cast(unsigned, __builtin_convertvector(v, hbf2)); }
;     __device__ __forceinline__ void operator()(const f32x4 (&acc)[2][2][4][2], const Unit& u, int wr, int wc, int fr, int fq, LAS f32x4* rsc, bool reuse) const {
;     ...
;                     for (int m = 0; m < 4; ++m) {
;                         const int row = row0 + ai * HALF + m * 16; const float r = rs[ai][m];
; #pragma unroll
;                         for (int bj = 0; bj < 2; ++bj) {
;                             const int col = u.pn * BM + bj * HALF + cl;
;                             const f32x4 v0 = acc[ai][bj][m][0] * r, v1 = acc[ai][bj][m][1] * r;
;                             u32x4 w; w.x = pk2(v0[0], v0[1]); w.y = pk2(v0[2], v0[3]); w.z = pk2(v1[0], v1[1]); w.w = pk2(v1[2], v1[3]);
;                             if (is_ba) { if (bj == 0 && cl < 16) { *(f32x4*)(baf + (size_t)row * 16 + cl) = v0; *(f32x4*)(baf + (size_t)row * 16 + cl + 4) = v1; } }
;                             else *(u32x4*)(outb + (size_t)row * ldo + col) = w;
.LBB0_612:
	s_or_b64 exec, exec, s[20:21]
	v_mov_b32_e32 v157, v156
	v_mov_b32_e32 v140, v156
	v_mov_b32_e32 v141, v156
	v_pk_mul_f32 v[142:143], v[78:79], v[140:141]
	v_pk_mul_f32 v[146:147], v[76:77], v[156:157]
	v_pk_mul_f32 v[148:149], v[70:71], v[140:141]
	v_pk_mul_f32 v[150:151], v[68:69], v[156:157]
	v_cvt_pk_bf16_f32 v140, v146, v147
	v_cvt_pk_bf16_f32 v141, v142, v143
	v_cvt_pk_bf16_f32 v142, v150, v151
	s_and_b64 vcc, exec, s[48:49]
	v_cvt_pk_bf16_f32 v143, v148, v149
	s_cbranch_vccnz .LBB0_614
	v_mad_i64_i32 v[146:147], s[20:21], s72, v162, 0
	v_lshl_add_u64 v[146:147], v[146:147], 1, s[14:15]
	v_lshl_add_u64 v[146:147], v[160:161], 1, v[146:147]
	flat_store_dwordx4 v[146:147], v[140:143] offset:256 nt

; __device__ __forceinline__ unsigned pk2(float lo, float hi) { const f32x2 v = {lo, hi}; return __builtin_bit_cast(unsigned, __builtin_convertvector(v, hbf2)); }
;     __device__ __forceinline__ void operator()(const f32x4 (&acc)[2][2][4][2], const Unit& u, int wr, int wc, int fr, int fq, LAS f32x4* rsc, bool reuse) const {
;     ...
;                     for (int m = 0; m < 4; ++m) {
;                         const int row = row0 + ai * HALF + m * 16; const float r = rs[ai][m];
; #pragma unroll
;                         for (int bj = 0; bj < 2; ++bj) {
;                             const int col = u.pn * BM + bj * HALF + cl;
;                             const f32x4 v0 = acc[ai][bj][m][0] * r, v1 = acc[ai][bj][m][1] * r;
;                             u32x4 w; w.x = pk2(v0[0], v0[1]); w.y = pk2(v0[2], v0[3]); w.z = pk2(v1[0], v1[1]); w.w = pk2(v1[2], v1[3]);
;                             if (is_ba) { if (bj == 0 && cl < 16) { *(f32x4*)(baf + (size_t)row * 16 + cl) = v0; *(f32x4*)(baf + (size_t)row * 16 + cl + 4) = v1; } }
;                             else *(u32x4*)(outb + (size_t)row * ldo + col) = w;
.LBB0_616:
	s_or_b64 exec, exec, s[20:21]
	v_add_u32_e32 v162, 0x80, v210
	v_ashrrev_i32_e32 v163, 31, v162
	s_waitcnt lgkmcnt(0)
	v_pk_mul_f32 v[142:143], v[66:67], v[132:133] op_sel_hi:[1,0]
	v_pk_mul_f32 v[140:141], v[64:65], v[132:133] op_sel_hi:[1,0]
	v_pk_mul_f32 v[146:147], v[58:59], v[132:133] op_sel_hi:[1,0]
	v_pk_mul_f32 v[144:145], v[56:57], v[132:133] op_sel_hi:[1,0]
	s_and_b64 vcc, exec, s[48:49]
	s_mov_b64 s[20:21], -1
	s_cbranch_vccnz .LBB0_660
	v_mad_i64_i32 v[164:165], s[20:21], s72, v162, 0
	v_lshl_add_u64 v[164:165], v[164:165], 1, s[14:15]
	v_cvt_pk_bf16_f32 v148, v140, v141
	v_cvt_pk_bf16_f32 v149, v142, v143
	v_cvt_pk_bf16_f32 v150, v144, v145
	v_cvt_pk_bf16_f32 v151, v146, v147
	v_lshl_add_u64 v[164:165], v[160:161], 1, v[164:165]
	flat_store_dwordx4 v[164:165], v[148:151] nt
	s_cbranch_execz .LBB0_661

; __device__ __forceinline__ unsigned pk2(float lo, float hi) { const f32x2 v = {lo, hi}; return __builtin_bit_cast(unsigned, __builtin_convertvector(v, hbf2)); }
;     __device__ __forceinline__ void operator()(const f32x4 (&acc)[2][2][4][2], const Unit& u, int wr, int wc, int fr, int fq, LAS f32x4* rsc, bool reuse) const {
;     ...
;                     for (int m = 0; m < 4; ++m) {
;                         const int row = row0 + ai * HALF + m * 16; const float r = rs[ai][m];
; #pragma unroll
;                         for (int bj = 0; bj < 2; ++bj) {
;                             const int col = u.pn * BM + bj * HALF + cl;
;                             const f32x4 v0 = acc[ai][bj][m][0] * r, v1 = acc[ai][bj][m][1] * r;
;                             u32x4 w; w.x = pk2(v0[0], v0[1]); w.y = pk2(v0[2], v0[3]); w.z = pk2(v1[0], v1[1]); w.w = pk2(v1[2], v1[3]);
;                             if (is_ba) { if (bj == 0 && cl < 16) { *(f32x4*)(baf + (size_t)row * 16 + cl) = v0; *(f32x4*)(baf + (size_t)row * 16 + cl + 4) = v1; } }
;                             else *(u32x4*)(outb + (size_t)row * ldo + col) = w;
.LBB0_619:
	v_mov_b32_e32 v133, v132
	v_mov_b32_e32 v142, v132
	v_mov_b32_e32 v143, v132
	v_pk_mul_f32 v[144:145], v[62:63], v[142:143]
	v_pk_mul_f32 v[140:141], v[60:61], v[132:133]
	s_nop 0
	v_cvt_pk_bf16_f32 v140, v140, v141
	v_cvt_pk_bf16_f32 v141, v144, v145
	v_pk_mul_f32 v[144:145], v[54:55], v[142:143]
	v_pk_mul_f32 v[142:143], v[52:53], v[132:133]
	s_nop 0
	v_cvt_pk_bf16_f32 v142, v142, v143
	v_cvt_pk_bf16_f32 v143, v144, v145
	v_mad_i64_i32 v[144:145], s[20:21], s72, v162, 0
	v_lshl_add_u64 v[144:145], v[144:145], 1, s[14:15]
	v_lshl_add_u64 v[144:145], v[160:161], 1, v[144:145]
	flat_store_dwordx4 v[144:145], v[140:143] offset:256 nt
.LBB0_620:
	v_add_u32_e32 v148, 0x90, v210
	v_ashrrev_i32_e32 v149, 31, v148
	v_pk_mul_f32 v[142:143], v[50:51], v[154:155] op_sel_hi:[1,0]
	v_pk_mul_f32 v[140:141], v[48:49], v[154:155] op_sel_hi:[1,0]
	v_pk_mul_f32 v[146:147], v[42:43], v[154:155] op_sel_hi:[1,0]
	v_pk_mul_f32 v[144:145], v[40:41], v[154:155] op_sel_hi:[1,0]
	s_and_b64 vcc, exec, s[48:49]
	s_mov_b64 s[20:21], -1
	s_cbranch_vccnz .LBB0_664
	v_mad_i64_i32 v[150:151], s[20:21], s72, v148, 0
	v_lshl_add_u64 v[150:151], v[150:151], 1, s[14:15]
	v_cvt_pk_bf16_f32 v164, v140, v141
	v_cvt_pk_bf16_f32 v165, v142, v143
	v_cvt_pk_bf16_f32 v166, v144, v145
	v_cvt_pk_bf16_f32 v167, v146, v147
	v_lshl_add_u64 v[150:151], v[160:161], 1, v[150:151]
	flat_store_dwordx4 v[150:151], v[164:167] nt
	s_cbranch_execz .LBB0_665

; __device__ __forceinline__ unsigned pk2(float lo, float hi) { const f32x2 v = {lo, hi}; return __builtin_bit_cast(unsigned, __builtin_convertvector(v, hbf2)); }
;     __device__ __forceinline__ void operator()(const f32x4 (&acc)[2][2][4][2], const Unit& u, int wr, int wc, int fr, int fq, LAS f32x4* rsc, bool reuse) const {
;     ...
;                     for (int m = 0; m < 4; ++m) {
;                         const int row = row0 + ai * HALF + m * 16; const float r = rs[ai][m];
; #pragma unroll
;                         for (int bj = 0; bj < 2; ++bj) {
;                             const int col = u.pn * BM + bj * HALF + cl;
;                             const f32x4 v0 = acc[ai][bj][m][0] * r, v1 = acc[ai][bj][m][1] * r;
;                             u32x4 w; w.x = pk2(v0[0], v0[1]); w.y = pk2(v0[2], v0[3]); w.z = pk2(v1[0], v1[1]); w.w = pk2(v1[2], v1[3]);
;                             if (is_ba) { if (bj == 0 && cl < 16) { *(f32x4*)(baf + (size_t)row * 16 + cl) = v0; *(f32x4*)(baf + (size_t)row * 16 + cl + 4) = v1; } }
;                             else *(u32x4*)(outb + (size_t)row * ldo + col) = w;
.LBB0_623:
	v_mov_b32_e32 v155, v154
	v_mov_b32_e32 v142, v154
	v_mov_b32_e32 v143, v154
	v_pk_mul_f32 v[144:145], v[46:47], v[142:143]
	v_pk_mul_f32 v[140:141], v[44:45], v[154:155]
	s_nop 0
	v_cvt_pk_bf16_f32 v140, v140, v141
	v_cvt_pk_bf16_f32 v141, v144, v145
	v_pk_mul_f32 v[144:145], v[38:39], v[142:143]
	v_pk_mul_f32 v[142:143], v[36:37], v[154:155]
	s_nop 0
	v_cvt_pk_bf16_f32 v142, v142, v143
	v_cvt_pk_bf16_f32 v143, v144, v145
	v_mad_i64_i32 v[144:145], s[20:21], s72, v148, 0
	v_lshl_add_u64 v[144:145], v[144:145], 1, s[14:15]
	v_lshl_add_u64 v[144:145], v[160:161], 1, v[144:145]
	flat_store_dwordx4 v[144:145], v[140:143] offset:256 nt
.LBB0_624:
	v_add_u32_e32 v148, 0xa0, v210
	v_ashrrev_i32_e32 v149, 31, v148
	v_pk_mul_f32 v[142:143], v[34:35], v[134:135] op_sel_hi:[1,0]
	v_pk_mul_f32 v[140:141], v[32:33], v[134:135] op_sel_hi:[1,0]
	v_pk_mul_f32 v[146:147], v[26:27], v[134:135] op_sel_hi:[1,0]
	v_pk_mul_f32 v[144:145], v[24:25], v[134:135] op_sel_hi:[1,0]
	s_and_b64 vcc, exec, s[48:49]
	s_mov_b64 s[20:21], -1
	s_cbranch_vccnz .LBB0_668
	v_mad_i64_i32 v[150:151], s[20:21], s72, v148, 0
	v_lshl_add_u64 v[150:151], v[150:151], 1, s[14:15]
	v_cvt_pk_bf16_f32 v164, v140, v141
	v_cvt_pk_bf16_f32 v165, v142, v143
	v_cvt_pk_bf16_f32 v166, v144, v145
	v_cvt_pk_bf16_f32 v167, v146, v147
	v_lshl_add_u64 v[150:151], v[160:161], 1, v[150:151]
	flat_store_dwordx4 v[150:151], v[164:167] nt
	s_cbranch_execz .LBB0_669

; __device__ __forceinline__ unsigned pk2(float lo, float hi) { const f32x2 v = {lo, hi}; return __builtin_bit_cast(unsigned, __builtin_convertvector(v, hbf2)); }
;     __device__ __forceinline__ void operator()(const f32x4 (&acc)[2][2][4][2], const Unit& u, int wr, int wc, int fr, int fq, LAS f32x4* rsc, bool reuse) const {
;     ...
;                     for (int m = 0; m < 4; ++m) {
;                         const int row = row0 + ai * HALF + m * 16; const float r = rs[ai][m];
; #pragma unroll
;                         for (int bj = 0; bj < 2; ++bj) {
;                             const int col = u.pn * BM + bj * HALF + cl;
;                             const f32x4 v0 = acc[ai][bj][m][0] * r, v1 = acc[ai][bj][m][1] * r;
;                             u32x4 w; w.x = pk2(v0[0], v0[1]); w.y = pk2(v0[2], v0[3]); w.z = pk2(v1[0], v1[1]); w.w = pk2(v1[2], v1[3]);
;                             if (is_ba) { if (bj == 0 && cl < 16) { *(f32x4*)(baf + (size_t)row * 16 + cl) = v0; *(f32x4*)(baf + (size_t)row * 16 + cl + 4) = v1; } }
;                             else *(u32x4*)(outb + (size_t)row * ldo + col) = w;
.LBB0_627:
	v_mov_b32_e32 v142, v134
	v_mov_b32_e32 v143, v134
	v_mov_b32_e32 v135, v134
	v_pk_mul_f32 v[144:145], v[30:31], v[134:135]
	v_pk_mul_f32 v[140:141], v[28:29], v[142:143]
	v_pk_mul_f32 v[142:143], v[20:21], v[142:143]
	v_cvt_pk_bf16_f32 v140, v140, v141
	v_cvt_pk_bf16_f32 v141, v144, v145
	v_pk_mul_f32 v[144:145], v[22:23], v[134:135]
	v_cvt_pk_bf16_f32 v142, v142, v143
	v_cvt_pk_bf16_f32 v143, v144, v145
	v_mad_i64_i32 v[144:145], s[20:21], s72, v148, 0
	v_lshl_add_u64 v[144:145], v[144:145], 1, s[14:15]
	v_lshl_add_u64 v[144:145], v[160:161], 1, v[144:145]
	flat_store_dwordx4 v[144:145], v[140:143] offset:256 nt
.LBB0_628:
	v_add_u32_e32 v164, 0xb0, v210
	v_pk_mul_f32 v[146:147], v[18:19], v[152:153] op_sel_hi:[1,0]
	v_pk_mul_f32 v[144:145], v[16:17], v[152:153] op_sel_hi:[1,0]
	v_pk_mul_f32 v[150:151], v[10:11], v[152:153] op_sel_hi:[1,0]
	v_pk_mul_f32 v[148:149], v[8:9], v[152:153] op_sel_hi:[1,0]
	v_ashrrev_i32_e32 v165, 31, v164
	v_cvt_pk_bf16_f32 v140, v144, v145
	v_cvt_pk_bf16_f32 v141, v146, v147
	v_cvt_pk_bf16_f32 v142, v148, v149
	v_cvt_pk_bf16_f32 v143, v150, v151
	s_and_b64 vcc, exec, s[48:49]
	s_mov_b64 s[20:21], -1
	s_cbranch_vccnz .LBB0_630
	v_mad_i64_i32 v[166:167], s[20:21], s72, v164, 0
	v_lshl_add_u64 v[166:167], v[166:167], 1, s[14:15]
	v_lshl_add_u64 v[166:167], v[160:161], 1, v[166:167]
	s_mov_b64 s[20:21], 0
	flat_store_dwordx4 v[166:167], v[140:143] nt

; __device__ __forceinline__ unsigned pk2(float lo, float hi) { const f32x2 v = {lo, hi}; return __builtin_bit_cast(unsigned, __builtin_convertvector(v, hbf2)); }
;     __device__ __forceinline__ void operator()(const f32x4 (&acc)[2][2][4][2], const Unit& u, int wr, int wc, int fr, int fq, LAS f32x4* rsc, bool reuse) const {
;     ...
;                     for (int m = 0; m < 4; ++m) {
;                         const int row = row0 + ai * HALF + m * 16; const float r = rs[ai][m];
; #pragma unroll
;                         for (int bj = 0; bj < 2; ++bj) {
;                             const int col = u.pn * BM + bj * HALF + cl;
;                             const f32x4 v0 = acc[ai][bj][m][0] * r, v1 = acc[ai][bj][m][1] * r;
;                             u32x4 w; w.x = pk2(v0[0], v0[1]); w.y = pk2(v0[2], v0[3]); w.z = pk2(v1[0], v1[1]); w.w = pk2(v1[2], v1[3]);
;                             if (is_ba) { if (bj == 0 && cl < 16) { *(f32x4*)(baf + (size_t)row * 16 + cl) = v0; *(f32x4*)(baf + (size_t)row * 16 + cl + 4) = v1; } }
;                             else *(u32x4*)(outb + (size_t)row * ldo + col) = w;
.LBB0_636:
	s_or_b64 exec, exec, s[16:17]
	v_mov_b32_e32 v153, v152
	v_mov_b32_e32 v140, v152
	v_mov_b32_e32 v141, v152
	v_pk_mul_f32 v[142:143], v[14:15], v[140:141]
	v_pk_mul_f32 v[146:147], v[12:13], v[152:153]
	v_pk_mul_f32 v[148:149], v[6:7], v[140:141]
	v_pk_mul_f32 v[150:151], v[4:5], v[152:153]
	v_cvt_pk_bf16_f32 v140, v146, v147
	v_cvt_pk_bf16_f32 v141, v142, v143
	v_cvt_pk_bf16_f32 v142, v150, v151
	s_and_b64 vcc, exec, s[48:49]
	v_cvt_pk_bf16_f32 v143, v148, v149
	s_cbranch_vccnz .LBB0_638
	v_mad_i64_i32 v[146:147], s[16:17], s72, v164, 0
	v_lshl_add_u64 v[146:147], v[146:147], 1, s[14:15]
	v_lshl_add_u64 v[146:147], v[160:161], 1, v[146:147]
	flat_store_dwordx4 v[146:147], v[140:143] offset:256 nt

; __device__ __forceinline__ unsigned pk2(float lo, float hi) { const f32x2 v = {lo, hi}; return __builtin_bit_cast(unsigned, __builtin_convertvector(v, hbf2)); }
; __device__ __forceinline__ float sigmoidf_(float x) { return __builtin_amdgcn_rcpf(1.f + __builtin_amdgcn_exp2f(-1.4426950408889634f * x)); }
;     __device__ __forceinline__ void operator()(const f32x4 (&acc)[2][2][4][2], const Unit& u, int wr, int wc, int fr, int fq, LAS f32x4* rsc, bool reuse) const {
;     ...
;             if (mode == E_GU) {
; #pragma unroll
;                 for (int ai = 0; ai < 2; ++ai)
; #pragma unroll
;                     for (int m = 0; m < 4; ++m) {
;                         const int row = row0 + ai * HALF + m * 16; const float r = rs[ai][m];
;                         float o[8];
; #pragma unroll
;                         for (int n = 0; n < 2; ++n)
; #pragma unroll
;                             for (int e = 0; e < 4; ++e) { const float g = acc[ai][0][m][n][e] * r, up = acc[ai][1][m][n][e] * r; o[n * 4 + e] = g * sigmoidf_(g) * up; }
;                         u32x4 w; w.x = pk2(o[0], o[1]); w.y = pk2(o[2], o[3]); w.z = pk2(o[4], o[5]); w.w = pk2(o[6], o[7]);
;                         *(u32x4*)(outb + (size_t)row * ldo + u.pn * 128 + cl) = w;
;                     }
.LBB0_641:
	v_pk_mul_f32 v[128:129], v[128:129], v[136:137] op_sel_hi:[1,0]
	v_pk_mul_f32 v[124:125], v[124:125], v[136:137] op_sel_hi:[1,0]
	v_mul_f32_e32 v2, 0xbfb8aa3b, v128
	v_exp_f32_e32 v2, v2
	v_pk_mul_f32 v[120:121], v[120:121], v[136:137] op_sel_hi:[1,0]
	v_pk_mul_f32 v[126:127], v[126:127], v[136:137] op_sel_hi:[1,0]
	v_pk_mul_f32 v[116:117], v[116:117], v[136:137] op_sel_hi:[1,0]
	v_add_f32_e32 v2, 1.0, v2
	v_rcp_f32_e32 v140, v2
	v_mul_f32_e32 v2, 0xbfb8aa3b, v129
	v_exp_f32_e32 v2, v2
	s_lshl_b32 s0, s73, 7
	v_pk_mul_f32 v[118:119], v[118:119], v[136:137] op_sel_hi:[1,0]
	s_ashr_i32 s1, s0, 31
	v_add_f32_e32 v2, 1.0, v2
	v_rcp_f32_e32 v141, v2
	s_lshl_b64 s[0:1], s[0:1], 1
	v_pk_mul_f32 v[112:113], v[112:113], v[158:159] op_sel_hi:[1,0]
	v_pk_mul_f32 v[108:109], v[108:109], v[158:159] op_sel_hi:[1,0]
	v_pk_mul_f32 v[128:129], v[128:129], v[140:141]
	v_pk_mul_f32 v[110:111], v[110:111], v[158:159] op_sel_hi:[1,0]
	v_pk_mul_f32 v[124:125], v[124:125], v[128:129]
	v_pk_mul_f32 v[128:129], v[130:131], v[136:137] op_sel_hi:[1,0]
	v_pk_mul_f32 v[104:105], v[104:105], v[158:159] op_sel_hi:[1,0]
	v_mul_f32_e32 v2, 0xbfb8aa3b, v128
	v_exp_f32_e32 v2, v2
	v_pk_mul_f32 v[100:101], v[100:101], v[158:159] op_sel_hi:[1,0]
	v_pk_mul_f32 v[102:103], v[102:103], v[158:159] op_sel_hi:[1,0]
	v_pk_mul_f32 v[96:97], v[96:97], v[138:139] op_sel_hi:[1,0]
	v_add_f32_e32 v2, 1.0, v2
	v_rcp_f32_e32 v130, v2
	v_mul_f32_e32 v2, 0xbfb8aa3b, v129
	v_exp_f32_e32 v2, v2
	v_pk_mul_f32 v[92:93], v[92:93], v[138:139] op_sel_hi:[1,0]
	v_pk_mul_f32 v[94:95], v[94:95], v[138:139] op_sel_hi:[1,0]
	v_pk_mul_f32 v[88:89], v[88:89], v[138:139] op_sel_hi:[1,0]
	v_add_f32_e32 v2, 1.0, v2
	v_rcp_f32_e32 v131, v2
	v_mul_f32_e32 v2, 0xbfb8aa3b, v120
	v_exp_f32_e32 v2, v2
	v_pk_mul_f32 v[84:85], v[84:85], v[138:139] op_sel_hi:[1,0]
	v_pk_mul_f32 v[128:129], v[128:129], v[130:131]
	v_pk_mul_f32 v[86:87], v[86:87], v[138:139] op_sel_hi:[1,0]
	v_add_f32_e32 v2, 1.0, v2
	v_pk_mul_f32 v[126:127], v[126:127], v[128:129]
	v_rcp_f32_e32 v128, v2
	v_mul_f32_e32 v2, 0xbfb8aa3b, v121
	v_exp_f32_e32 v2, v2
	v_pk_mul_f32 v[80:81], v[80:81], v[156:157] op_sel_hi:[1,0]
	v_pk_mul_f32 v[76:77], v[76:77], v[156:157] op_sel_hi:[1,0]
	v_pk_mul_f32 v[78:79], v[78:79], v[156:157] op_sel_hi:[1,0]
	v_add_f32_e32 v2, 1.0, v2
	v_rcp_f32_e32 v129, v2
	v_pk_mul_f32 v[72:73], v[72:73], v[156:157] op_sel_hi:[1,0]
	v_pk_mul_f32 v[68:69], v[68:69], v[156:157] op_sel_hi:[1,0]
	v_pk_mul_f32 v[70:71], v[70:71], v[156:157] op_sel_hi:[1,0]
	v_pk_mul_f32 v[120:121], v[120:121], v[128:129]
	s_waitcnt lgkmcnt(0)
	v_pk_mul_f32 v[64:65], v[64:65], v[132:133] op_sel_hi:[1,0]
	v_pk_mul_f32 v[120:121], v[116:117], v[120:121]
	v_pk_mul_f32 v[116:117], v[122:123], v[136:137] op_sel_hi:[1,0]
	v_pk_mul_f32 v[60:61], v[60:61], v[132:133] op_sel_hi:[1,0]
	v_mul_f32_e32 v2, 0xbfb8aa3b, v116
	v_exp_f32_e32 v2, v2
	v_pk_mul_f32 v[62:63], v[62:63], v[132:133] op_sel_hi:[1,0]
	v_pk_mul_f32 v[56:57], v[56:57], v[132:133] op_sel_hi:[1,0]
	v_pk_mul_f32 v[52:53], v[52:53], v[132:133] op_sel_hi:[1,0]
	v_add_f32_e32 v2, 1.0, v2
	v_rcp_f32_e32 v122, v2
	v_mul_f32_e32 v2, 0xbfb8aa3b, v117
	v_exp_f32_e32 v2, v2
	v_pk_mul_f32 v[54:55], v[54:55], v[132:133] op_sel_hi:[1,0]
	v_pk_mul_f32 v[48:49], v[48:49], v[154:155] op_sel_hi:[1,0]
	v_pk_mul_f32 v[44:45], v[44:45], v[154:155] op_sel_hi:[1,0]
	v_add_f32_e32 v2, 1.0, v2
	v_rcp_f32_e32 v123, v2
	v_lshlrev_b32_e32 v2, 1, v204
	v_pk_mul_f32 v[46:47], v[46:47], v[154:155] op_sel_hi:[1,0]
	v_pk_mul_f32 v[40:41], v[40:41], v[154:155] op_sel_hi:[1,0]
	v_pk_mul_f32 v[116:117], v[116:117], v[122:123]
	v_pk_mul_f32 v[36:37], v[36:37], v[154:155] op_sel_hi:[1,0]
	v_pk_mul_f32 v[122:123], v[118:119], v[116:117]
	v_cvt_pk_bf16_f32 v118, v120, v121
	v_mad_i64_i32 v[120:121], s[16:17], s72, v210, 0
	v_lshl_add_u64 v[120:121], v[120:121], 1, s[14:15]
	v_lshl_add_u64 v[120:121], v[120:121], 0, s[0:1]
	v_cvt_pk_bf16_f32 v116, v124, v125
	v_cvt_pk_bf16_f32 v117, v126, v127
	v_cvt_pk_bf16_f32 v119, v122, v123
	v_lshl_add_u64 v[120:121], v[120:121], 0, v[2:3]
	flat_store_dwordx4 v[120:121], v[116:119] sc1
	v_pk_mul_f32 v[38:39], v[38:39], v[154:155] op_sel_hi:[1,0]
	v_pk_mul_f32 v[32:33], v[32:33], v[134:135] op_sel_hi:[1,0]
	v_mul_f32_e32 v116, 0xbfb8aa3b, v112
	v_mul_f32_e32 v117, 0xbfb8aa3b, v113
	v_exp_f32_e32 v116, v116
	v_exp_f32_e32 v117, v117
	v_pk_mul_f32 v[28:29], v[28:29], v[134:135] op_sel_hi:[1,0]
	v_pk_mul_f32 v[30:31], v[30:31], v[134:135] op_sel_hi:[1,0]
	v_add_f32_e32 v116, 1.0, v116
	v_add_f32_e32 v117, 1.0, v117
	v_rcp_f32_e32 v116, v116
	v_rcp_f32_e32 v117, v117
	v_pk_mul_f32 v[24:25], v[24:25], v[134:135] op_sel_hi:[1,0]
	v_pk_mul_f32 v[20:21], v[20:21], v[134:135] op_sel_hi:[1,0]
	v_pk_mul_f32 v[22:23], v[22:23], v[134:135] op_sel_hi:[1,0]
	v_pk_mul_f32 v[112:113], v[112:113], v[116:117]
	v_pk_mul_f32 v[16:17], v[16:17], v[152:153] op_sel_hi:[1,0]
	v_pk_mul_f32 v[108:109], v[108:109], v[112:113]
	v_pk_mul_f32 v[112:113], v[114:115], v[158:159] op_sel_hi:[1,0]
	v_pk_mul_f32 v[12:13], v[12:13], v[152:153] op_sel_hi:[1,0]
	v_mul_f32_e32 v114, 0xbfb8aa3b, v112
	v_mul_f32_e32 v115, 0xbfb8aa3b, v113
	v_exp_f32_e32 v114, v114
	v_exp_f32_e32 v115, v115
	v_pk_mul_f32 v[14:15], v[14:15], v[152:153] op_sel_hi:[1,0]
	v_pk_mul_f32 v[8:9], v[8:9], v[152:153] op_sel_hi:[1,0]
	v_add_f32_e32 v114, 1.0, v114
	v_add_f32_e32 v115, 1.0, v115
	v_rcp_f32_e32 v114, v114
	v_rcp_f32_e32 v115, v115
	v_pk_mul_f32 v[4:5], v[4:5], v[152:153] op_sel_hi:[1,0]
	v_pk_mul_f32 v[6:7], v[6:7], v[152:153] op_sel_hi:[1,0]
	v_pk_mul_f32 v[112:113], v[112:113], v[114:115]
	s_nop 0
	v_pk_mul_f32 v[110:111], v[110:111], v[112:113]
; __device__ __forceinline__ unsigned pk2(float lo, float hi) { const f32x2 v = {lo, hi}; return __builtin_bit_cast(unsigned, __builtin_convertvector(v, hbf2)); }
; __device__ __forceinline__ float sigmoidf_(float x) { return __builtin_amdgcn_rcpf(1.f + __builtin_amdgcn_exp2f(-1.4426950408889634f * x)); }
;     __device__ __forceinline__ void operator()(const f32x4 (&acc)[2][2][4][2], const Unit& u, int wr, int wc, int fr, int fq, LAS f32x4* rsc, bool reuse) const {
;     ...
;             if (mode == E_GU) {
; #pragma unroll
;                 for (int ai = 0; ai < 2; ++ai)
; #pragma unroll
;                     for (int m = 0; m < 4; ++m) {
;                         const int row = row0 + ai * HALF + m * 16; const float r = rs[ai][m];
;                         float o[8];
; #pragma unroll
;                         for (int n = 0; n < 2; ++n)
; #pragma unroll
;                             for (int e = 0; e < 4; ++e) { const float g = acc[ai][0][m][n][e] * r, up = acc[ai][1][m][n][e] * r; o[n * 4 + e] = g * sigmoidf_(g) * up; }
;                         u32x4 w; w.x = pk2(o[0], o[1]); w.y = pk2(o[2], o[3]); w.z = pk2(o[4], o[5]); w.w = pk2(o[6], o[7]);
;                         *(u32x4*)(outb + (size_t)row * ldo + u.pn * 128 + cl) = w;
;                     }
	v_mul_f32_e32 v112, 0xbfb8aa3b, v104
	v_mul_f32_e32 v113, 0xbfb8aa3b, v105
	v_exp_f32_e32 v112, v112
	v_exp_f32_e32 v113, v113
	v_add_f32_e32 v112, 1.0, v112
	v_add_f32_e32 v113, 1.0, v113
	v_rcp_f32_e32 v112, v112
	v_rcp_f32_e32 v113, v113
	s_nop 0
	v_pk_mul_f32 v[104:105], v[104:105], v[112:113]
	s_nop 0
	v_pk_mul_f32 v[104:105], v[100:101], v[104:105]
	v_pk_mul_f32 v[100:101], v[106:107], v[158:159] op_sel_hi:[1,0]
	v_or_b32_e32 v112, 16, v210
	v_mul_f32_e32 v106, 0xbfb8aa3b, v100
	v_mul_f32_e32 v107, 0xbfb8aa3b, v101
	v_exp_f32_e32 v106, v106
	v_exp_f32_e32 v107, v107
	v_add_f32_e32 v106, 1.0, v106
	v_add_f32_e32 v107, 1.0, v107
	v_rcp_f32_e32 v106, v106
	v_rcp_f32_e32 v107, v107
	s_nop 0
	v_pk_mul_f32 v[100:101], v[100:101], v[106:107]
	s_nop 0
	v_pk_mul_f32 v[106:107], v[102:103], v[100:101]
	v_cvt_pk_bf16_f32 v102, v104, v105
	v_mad_i64_i32 v[104:105], s[16:17], s72, v112, 0
	v_lshl_add_u64 v[104:105], v[104:105], 1, s[14:15]
	v_lshl_add_u64 v[104:105], v[104:105], 0, s[0:1]
	v_cvt_pk_bf16_f32 v100, v108, v109
	v_cvt_pk_bf16_f32 v101, v110, v111
	v_cvt_pk_bf16_f32 v103, v106, v107
	v_lshl_add_u64 v[104:105], v[104:105], 0, v[2:3]
	flat_store_dwordx4 v[104:105], v[100:103] sc1
	s_nop 1
	v_mul_f32_e32 v100, 0xbfb8aa3b, v96
	v_mul_f32_e32 v101, 0xbfb8aa3b, v97
	v_exp_f32_e32 v100, v100
	v_exp_f32_e32 v101, v101
	v_add_f32_e32 v100, 1.0, v100
	v_add_f32_e32 v101, 1.0, v101
	v_rcp_f32_e32 v100, v100
	v_rcp_f32_e32 v101, v101
	s_nop 0
	v_pk_mul_f32 v[96:97], v[96:97], v[100:101]
	s_nop 0
	v_pk_mul_f32 v[92:93], v[92:93], v[96:97]
	v_pk_mul_f32 v[96:97], v[98:99], v[138:139] op_sel_hi:[1,0]
	s_nop 0
	v_mul_f32_e32 v98, 0xbfb8aa3b, v96
	v_mul_f32_e32 v99, 0xbfb8aa3b, v97
	v_exp_f32_e32 v98, v98
	v_exp_f32_e32 v99, v99
	v_add_f32_e32 v98, 1.0, v98
	v_add_f32_e32 v99, 1.0, v99
	v_rcp_f32_e32 v98, v98
	v_rcp_f32_e32 v99, v99
	s_nop 0
	v_pk_mul_f32 v[96:97], v[96:97], v[98:99]
	s_nop 0
	v_pk_mul_f32 v[94:95], v[94:95], v[96:97]
	v_mul_f32_e32 v96, 0xbfb8aa3b, v88
	v_mul_f32_e32 v97, 0xbfb8aa3b, v89
	v_exp_f32_e32 v96, v96
	v_exp_f32_e32 v97, v97
	v_add_f32_e32 v96, 1.0, v96
	v_add_f32_e32 v97, 1.0, v97
	v_rcp_f32_e32 v96, v96
	v_rcp_f32_e32 v97, v97
	s_nop 0
	v_pk_mul_f32 v[88:89], v[88:89], v[96:97]
	s_nop 0
	v_pk_mul_f32 v[88:89], v[84:85], v[88:89]
	v_pk_mul_f32 v[84:85], v[90:91], v[138:139] op_sel_hi:[1,0]
	v_or_b32_e32 v96, 32, v210
	v_mul_f32_e32 v90, 0xbfb8aa3b, v84
	v_mul_f32_e32 v91, 0xbfb8aa3b, v85
	v_exp_f32_e32 v90, v90
	v_exp_f32_e32 v91, v91
	v_add_f32_e32 v90, 1.0, v90
	v_add_f32_e32 v91, 1.0, v91
	v_rcp_f32_e32 v90, v90
	v_rcp_f32_e32 v91, v91
	s_nop 0
	v_pk_mul_f32 v[84:85], v[84:85], v[90:91]
	s_nop 0
	v_pk_mul_f32 v[90:91], v[86:87], v[84:85]
	v_cvt_pk_bf16_f32 v86, v88, v89
	v_mad_i64_i32 v[88:89], s[16:17], s72, v96, 0
	v_lshl_add_u64 v[88:89], v[88:89], 1, s[14:15]
	v_lshl_add_u64 v[88:89], v[88:89], 0, s[0:1]
	v_cvt_pk_bf16_f32 v84, v92, v93
	v_cvt_pk_bf16_f32 v85, v94, v95
	v_cvt_pk_bf16_f32 v87, v90, v91
	v_lshl_add_u64 v[88:89], v[88:89], 0, v[2:3]
	flat_store_dwordx4 v[88:89], v[84:87] sc1
	s_nop 1
	v_mul_f32_e32 v84, 0xbfb8aa3b, v80
	v_mul_f32_e32 v85, 0xbfb8aa3b, v81
	v_exp_f32_e32 v84, v84
	v_exp_f32_e32 v85, v85
	v_add_f32_e32 v84, 1.0, v84
	v_add_f32_e32 v85, 1.0, v85
	v_rcp_f32_e32 v84, v84
	v_rcp_f32_e32 v85, v85
	s_nop 0
	v_pk_mul_f32 v[80:81], v[80:81], v[84:85]
	s_nop 0
	v_pk_mul_f32 v[76:77], v[76:77], v[80:81]
	v_pk_mul_f32 v[80:81], v[82:83], v[156:157] op_sel_hi:[1,0]
	s_nop 0
	v_mul_f32_e32 v82, 0xbfb8aa3b, v80
	v_mul_f32_e32 v83, 0xbfb8aa3b, v81
	v_exp_f32_e32 v82, v82
	v_exp_f32_e32 v83, v83
	v_add_f32_e32 v82, 1.0, v82
	v_add_f32_e32 v83, 1.0, v83
	v_rcp_f32_e32 v82, v82
	v_rcp_f32_e32 v83, v83
	s_nop 0
	v_pk_mul_f32 v[80:81], v[80:81], v[82:83]
	s_nop 0
	v_pk_mul_f32 v[78:79], v[78:79], v[80:81]
	v_mul_f32_e32 v80, 0xbfb8aa3b, v72
	v_mul_f32_e32 v81, 0xbfb8aa3b, v73
	v_exp_f32_e32 v80, v80
	v_exp_f32_e32 v81, v81
	v_add_f32_e32 v80, 1.0, v80
	v_add_f32_e32 v81, 1.0, v81
	v_rcp_f32_e32 v80, v80
	v_rcp_f32_e32 v81, v81
	s_nop 0
	v_pk_mul_f32 v[72:73], v[72:73], v[80:81]
	s_nop 0
	v_pk_mul_f32 v[72:73], v[68:69], v[72:73]
	v_pk_mul_f32 v[68:69], v[74:75], v[156:157] op_sel_hi:[1,0]
	v_or_b32_e32 v80, 48, v210
	v_mul_f32_e32 v74, 0xbfb8aa3b, v68
	v_mul_f32_e32 v75, 0xbfb8aa3b, v69
	v_exp_f32_e32 v74, v74
	v_exp_f32_e32 v75, v75
	v_add_f32_e32 v74, 1.0, v74
	v_add_f32_e32 v75, 1.0, v75
	v_rcp_f32_e32 v74, v74
	v_rcp_f32_e32 v75, v75
	s_nop 0
	v_pk_mul_f32 v[68:69], v[68:69], v[74:75]
	s_nop 0
	v_pk_mul_f32 v[74:75], v[70:71], v[68:69]
	v_cvt_pk_bf16_f32 v70, v72, v73
	v_mad_i64_i32 v[72:73], s[16:17], s72, v80, 0
	v_lshl_add_u64 v[72:73], v[72:73], 1, s[14:15]
	v_lshl_add_u64 v[72:73], v[72:73], 0, s[0:1]
	v_cvt_pk_bf16_f32 v68, v76, v77
	v_cvt_pk_bf16_f32 v69, v78, v79
	v_cvt_pk_bf16_f32 v71, v74, v75
	v_lshl_add_u64 v[72:73], v[72:73], 0, v[2:3]
	flat_store_dwordx4 v[72:73], v[68:71] sc1
	s_nop 1
	v_mul_f32_e32 v68, 0xbfb8aa3b, v64
	v_mul_f32_e32 v69, 0xbfb8aa3b, v65
	v_exp_f32_e32 v68, v68
	v_exp_f32_e32 v69, v69
	v_add_u32_e32 v70, 0x80, v210
	v_add_f32_e32 v68, 1.0, v68
	v_add_f32_e32 v69, 1.0, v69
	v_rcp_f32_e32 v68, v68
	v_rcp_f32_e32 v69, v69
	s_nop 0
	v_pk_mul_f32 v[64:65], v[64:65], v[68:69]
	s_nop 0
	v_pk_mul_f32 v[60:61], v[60:61], v[64:65]
	v_pk_mul_f32 v[64:65], v[66:67], v[132:133] op_sel_hi:[1,0]
	s_nop 0
	v_mul_f32_e32 v66, 0xbfb8aa3b, v64
	v_mul_f32_e32 v67, 0xbfb8aa3b, v65
	v_exp_f32_e32 v66, v66
	v_exp_f32_e32 v67, v67
	v_add_f32_e32 v66, 1.0, v66
	v_add_f32_e32 v67, 1.0, v67
	v_rcp_f32_e32 v66, v66
	v_rcp_f32_e32 v67, v67
	s_nop 0
	v_pk_mul_f32 v[64:65], v[64:65], v[66:67]
; __device__ __forceinline__ unsigned pk2(float lo, float hi) { const f32x2 v = {lo, hi}; return __builtin_bit_cast(unsigned, __builtin_convertvector(v, hbf2)); }
; __device__ __forceinline__ float sigmoidf_(float x) { return __builtin_amdgcn_rcpf(1.f + __builtin_amdgcn_exp2f(-1.4426950408889634f * x)); }
;     __device__ __forceinline__ void operator()(const f32x4 (&acc)[2][2][4][2], const Unit& u, int wr, int wc, int fr, int fq, LAS f32x4* rsc, bool reuse) const {
;     ...
;             if (mode == E_GU) {
; #pragma unroll
;                 for (int ai = 0; ai < 2; ++ai)
; #pragma unroll
;                     for (int m = 0; m < 4; ++m) {
;                         const int row = row0 + ai * HALF + m * 16; const float r = rs[ai][m];
;                         float o[8];
; #pragma unroll
;                         for (int n = 0; n < 2; ++n)
; #pragma unroll
;                             for (int e = 0; e < 4; ++e) { const float g = acc[ai][0][m][n][e] * r, up = acc[ai][1][m][n][e] * r; o[n * 4 + e] = g * sigmoidf_(g) * up; }
;                         u32x4 w; w.x = pk2(o[0], o[1]); w.y = pk2(o[2], o[3]); w.z = pk2(o[4], o[5]); w.w = pk2(o[6], o[7]);
;                         *(u32x4*)(outb + (size_t)row * ldo + u.pn * 128 + cl) = w;
;                     }
	s_nop 0
	v_pk_mul_f32 v[62:63], v[62:63], v[64:65]
	v_mul_f32_e32 v64, 0xbfb8aa3b, v56
	v_mul_f32_e32 v65, 0xbfb8aa3b, v57
	v_exp_f32_e32 v64, v64
	v_exp_f32_e32 v65, v65
	v_add_f32_e32 v64, 1.0, v64
	v_add_f32_e32 v65, 1.0, v65
	v_rcp_f32_e32 v64, v64
	v_rcp_f32_e32 v65, v65
	s_nop 0
	v_pk_mul_f32 v[56:57], v[56:57], v[64:65]
	s_nop 0
	v_pk_mul_f32 v[56:57], v[52:53], v[56:57]
	v_pk_mul_f32 v[52:53], v[58:59], v[132:133] op_sel_hi:[1,0]
	s_nop 0
	v_mul_f32_e32 v58, 0xbfb8aa3b, v52
	v_mul_f32_e32 v59, 0xbfb8aa3b, v53
	v_exp_f32_e32 v58, v58
	v_exp_f32_e32 v59, v59
	v_add_f32_e32 v58, 1.0, v58
	v_add_f32_e32 v59, 1.0, v59
	v_rcp_f32_e32 v58, v58
	v_rcp_f32_e32 v59, v59
	s_nop 0
	v_pk_mul_f32 v[52:53], v[52:53], v[58:59]
	s_nop 0
	v_pk_mul_f32 v[58:59], v[54:55], v[52:53]
	v_cvt_pk_bf16_f32 v54, v56, v57
	v_mad_i64_i32 v[56:57], s[16:17], s72, v70, 0
	v_lshl_add_u64 v[56:57], v[56:57], 1, s[14:15]
	v_lshl_add_u64 v[56:57], v[56:57], 0, s[0:1]
	v_cvt_pk_bf16_f32 v52, v60, v61
	v_cvt_pk_bf16_f32 v53, v62, v63
	v_cvt_pk_bf16_f32 v55, v58, v59
	v_lshl_add_u64 v[56:57], v[56:57], 0, v[2:3]
	flat_store_dwordx4 v[56:57], v[52:55] sc1
	s_nop 1
	v_mul_f32_e32 v52, 0xbfb8aa3b, v48
	v_mul_f32_e32 v53, 0xbfb8aa3b, v49
	v_exp_f32_e32 v52, v52
	v_exp_f32_e32 v53, v53
	v_add_f32_e32 v52, 1.0, v52
	v_add_f32_e32 v53, 1.0, v53
	v_rcp_f32_e32 v52, v52
	v_rcp_f32_e32 v53, v53
	s_nop 0
	v_pk_mul_f32 v[48:49], v[48:49], v[52:53]
	s_nop 0
	v_pk_mul_f32 v[44:45], v[44:45], v[48:49]
	v_pk_mul_f32 v[48:49], v[50:51], v[154:155] op_sel_hi:[1,0]
	s_nop 0
	v_mul_f32_e32 v50, 0xbfb8aa3b, v48
	v_mul_f32_e32 v51, 0xbfb8aa3b, v49
	v_exp_f32_e32 v50, v50
	v_exp_f32_e32 v51, v51
	v_add_f32_e32 v50, 1.0, v50
	v_add_f32_e32 v51, 1.0, v51
	v_rcp_f32_e32 v50, v50
	v_rcp_f32_e32 v51, v51
	s_nop 0
	v_pk_mul_f32 v[48:49], v[48:49], v[50:51]
	s_nop 0
	v_pk_mul_f32 v[46:47], v[46:47], v[48:49]
	v_mul_f32_e32 v48, 0xbfb8aa3b, v40
	v_mul_f32_e32 v49, 0xbfb8aa3b, v41
	v_exp_f32_e32 v48, v48
	v_exp_f32_e32 v49, v49
	v_add_f32_e32 v48, 1.0, v48
	v_add_f32_e32 v49, 1.0, v49
	v_rcp_f32_e32 v48, v48
	v_rcp_f32_e32 v49, v49
	s_nop 0
	v_pk_mul_f32 v[40:41], v[40:41], v[48:49]
	s_nop 0
	v_pk_mul_f32 v[40:41], v[36:37], v[40:41]
	v_pk_mul_f32 v[36:37], v[42:43], v[154:155] op_sel_hi:[1,0]
	v_add_u32_e32 v48, 0x90, v210
	v_mul_f32_e32 v42, 0xbfb8aa3b, v36
	v_mul_f32_e32 v43, 0xbfb8aa3b, v37
	v_exp_f32_e32 v42, v42
	v_exp_f32_e32 v43, v43
	v_add_f32_e32 v42, 1.0, v42
	v_add_f32_e32 v43, 1.0, v43
	v_rcp_f32_e32 v42, v42
	v_rcp_f32_e32 v43, v43
	s_nop 0
	v_pk_mul_f32 v[36:37], v[36:37], v[42:43]
	s_nop 0
	v_pk_mul_f32 v[42:43], v[38:39], v[36:37]
	v_cvt_pk_bf16_f32 v38, v40, v41
	v_mad_i64_i32 v[40:41], s[16:17], s72, v48, 0
	v_lshl_add_u64 v[40:41], v[40:41], 1, s[14:15]
	v_lshl_add_u64 v[40:41], v[40:41], 0, s[0:1]
	v_cvt_pk_bf16_f32 v36, v44, v45
	v_cvt_pk_bf16_f32 v37, v46, v47
	v_cvt_pk_bf16_f32 v39, v42, v43
	v_lshl_add_u64 v[40:41], v[40:41], 0, v[2:3]
	flat_store_dwordx4 v[40:41], v[36:39] sc1
	s_nop 1
	v_mul_f32_e32 v36, 0xbfb8aa3b, v32
	v_mul_f32_e32 v37, 0xbfb8aa3b, v33
	v_exp_f32_e32 v36, v36
	v_exp_f32_e32 v37, v37
	v_add_f32_e32 v36, 1.0, v36
	v_add_f32_e32 v37, 1.0, v37
	v_rcp_f32_e32 v36, v36
	v_rcp_f32_e32 v37, v37
	s_nop 0
	v_pk_mul_f32 v[32:33], v[32:33], v[36:37]
	s_nop 0
	v_pk_mul_f32 v[28:29], v[28:29], v[32:33]
	v_pk_mul_f32 v[32:33], v[34:35], v[134:135] op_sel_hi:[1,0]
	s_nop 0
	v_mul_f32_e32 v34, 0xbfb8aa3b, v32
	v_mul_f32_e32 v35, 0xbfb8aa3b, v33
	v_exp_f32_e32 v34, v34
	v_exp_f32_e32 v35, v35
	v_add_f32_e32 v34, 1.0, v34
	v_add_f32_e32 v35, 1.0, v35
	v_rcp_f32_e32 v34, v34
	v_rcp_f32_e32 v35, v35
	s_nop 0
	v_pk_mul_f32 v[32:33], v[32:33], v[34:35]
	s_nop 0
	v_pk_mul_f32 v[30:31], v[30:31], v[32:33]
	v_mul_f32_e32 v32, 0xbfb8aa3b, v24
	v_mul_f32_e32 v33, 0xbfb8aa3b, v25
	v_exp_f32_e32 v32, v32
	v_exp_f32_e32 v33, v33
	v_add_f32_e32 v32, 1.0, v32
	v_add_f32_e32 v33, 1.0, v33
	v_rcp_f32_e32 v32, v32
	v_rcp_f32_e32 v33, v33
	s_nop 0
	v_pk_mul_f32 v[24:25], v[24:25], v[32:33]
	s_nop 0
	v_pk_mul_f32 v[24:25], v[20:21], v[24:25]
	v_pk_mul_f32 v[20:21], v[26:27], v[134:135] op_sel_hi:[1,0]
	v_add_u32_e32 v32, 0xa0, v210
	v_mul_f32_e32 v26, 0xbfb8aa3b, v20
	v_mul_f32_e32 v27, 0xbfb8aa3b, v21
	v_exp_f32_e32 v26, v26
	v_exp_f32_e32 v27, v27
	v_add_f32_e32 v26, 1.0, v26
	v_add_f32_e32 v27, 1.0, v27
	v_rcp_f32_e32 v26, v26
	v_rcp_f32_e32 v27, v27
	s_nop 0
	v_pk_mul_f32 v[20:21], v[20:21], v[26:27]
	s_nop 0
	v_pk_mul_f32 v[26:27], v[22:23], v[20:21]
	v_cvt_pk_bf16_f32 v22, v24, v25
	v_mad_i64_i32 v[24:25], s[16:17], s72, v32, 0
	v_lshl_add_u64 v[24:25], v[24:25], 1, s[14:15]
	v_lshl_add_u64 v[24:25], v[24:25], 0, s[0:1]
	v_cvt_pk_bf16_f32 v20, v28, v29
	v_cvt_pk_bf16_f32 v21, v30, v31
	v_cvt_pk_bf16_f32 v23, v26, v27
	v_lshl_add_u64 v[24:25], v[24:25], 0, v[2:3]
	flat_store_dwordx4 v[24:25], v[20:23] sc1
	s_nop 1
	v_mul_f32_e32 v20, 0xbfb8aa3b, v16
	v_mul_f32_e32 v21, 0xbfb8aa3b, v17
	v_exp_f32_e32 v20, v20
	v_exp_f32_e32 v21, v21
	v_add_f32_e32 v20, 1.0, v20
	v_add_f32_e32 v21, 1.0, v21
	v_rcp_f32_e32 v20, v20
	v_rcp_f32_e32 v21, v21
	s_nop 0
	v_pk_mul_f32 v[16:17], v[16:17], v[20:21]
	s_nop 0
	v_pk_mul_f32 v[12:13], v[12:13], v[16:17]
	v_pk_mul_f32 v[16:17], v[18:19], v[152:153] op_sel_hi:[1,0]
	s_nop 0
	v_mul_f32_e32 v18, 0xbfb8aa3b, v16
	v_mul_f32_e32 v19, 0xbfb8aa3b, v17
	v_exp_f32_e32 v18, v18
	v_exp_f32_e32 v19, v19
	v_add_f32_e32 v18, 1.0, v18
	v_add_f32_e32 v19, 1.0, v19
	v_rcp_f32_e32 v18, v18
	v_rcp_f32_e32 v19, v19
	s_nop 0
	v_pk_mul_f32 v[16:17], v[16:17], v[18:19]
	s_nop 0
	v_pk_mul_f32 v[14:15], v[14:15], v[16:17]
	v_mul_f32_e32 v16, 0xbfb8aa3b, v8
	v_mul_f32_e32 v17, 0xbfb8aa3b, v9
	v_exp_f32_e32 v16, v16
	v_exp_f32_e32 v17, v17
	v_add_f32_e32 v16, 1.0, v16
	v_add_f32_e32 v17, 1.0, v17
	v_rcp_f32_e32 v16, v16
	v_rcp_f32_e32 v17, v17
	s_nop 0
	v_pk_mul_f32 v[8:9], v[8:9], v[16:17]
	s_nop 0
	v_pk_mul_f32 v[8:9], v[4:5], v[8:9]
	v_pk_mul_f32 v[4:5], v[10:11], v[152:153] op_sel_hi:[1,0]
	v_add_u32_e32 v16, 0xb0, v210
	v_mul_f32_e32 v10, 0xbfb8aa3b, v4
	v_mul_f32_e32 v11, 0xbfb8aa3b, v5
	v_exp_f32_e32 v10, v10
	v_exp_f32_e32 v11, v11
	v_add_f32_e32 v10, 1.0, v10
	v_add_f32_e32 v11, 1.0, v11
	v_rcp_f32_e32 v10, v10
	v_rcp_f32_e32 v11, v11
	s_nop 0
	v_pk_mul_f32 v[4:5], v[4:5], v[10:11]
	s_nop 0
	v_pk_mul_f32 v[10:11], v[6:7], v[4:5]
	v_cvt_pk_bf16_f32 v6, v8, v9
	v_mad_i64_i32 v[8:9], s[16:17], s72, v16, 0
	v_lshl_add_u64 v[8:9], v[8:9], 1, s[14:15]
	v_lshl_add_u64 v[8:9], v[8:9], 0, s[0:1]
	v_cvt_pk_bf16_f32 v4, v12, v13
	v_cvt_pk_bf16_f32 v5, v14, v15
	v_cvt_pk_bf16_f32 v7, v10, v11
	v_lshl_add_u64 v[8:9], v[8:9], 0, v[2:3]
	flat_store_dwordx4 v[8:9], v[4:7] sc1

; __device__ __forceinline__ unsigned pk2(float lo, float hi) { const f32x2 v = {lo, hi}; return __builtin_bit_cast(unsigned, __builtin_convertvector(v, hbf2)); }
; __device__ __forceinline__ float sigmoidf_(float x) { return __builtin_amdgcn_rcpf(1.f + __builtin_amdgcn_exp2f(-1.4426950408889634f * x)); }
;     __device__ __forceinline__ void operator()(const f32x4 (&acc)[2][2][4][2], const Unit& u, int wr, int wc, int fr, int fq, LAS f32x4* rsc, bool reuse) const {
;     ...
;             if (mode == E_GU) {
; #pragma unroll
;                 for (int ai = 0; ai < 2; ++ai)
; #pragma unroll
;                     for (int m = 0; m < 4; ++m) {
;                         const int row = row0 + ai * HALF + m * 16; const float r = rs[ai][m];
;                         float o[8];
; #pragma unroll
;                         for (int n = 0; n < 2; ++n)
; #pragma unroll
;                             for (int e = 0; e < 4; ++e) { const float g = acc[ai][0][m][n][e] * r, up = acc[ai][1][m][n][e] * r; o[n * 4 + e] = g * sigmoidf_(g) * up; }
;                         u32x4 w; w.x = pk2(o[0], o[1]); w.y = pk2(o[2], o[3]); w.z = pk2(o[4], o[5]); w.w = pk2(o[6], o[7]);
;                         *(u32x4*)(outb + (size_t)row * ldo + u.pn * 128 + cl) = w;
;                     }
.LBB0_2080:
	v_pk_mul_f32 v[128:129], v[128:129], v[136:137] op_sel_hi:[1,0]
	v_pk_mul_f32 v[124:125], v[124:125], v[136:137] op_sel_hi:[1,0]
	v_mul_f32_e32 v2, 0xbfb8aa3b, v128
	v_exp_f32_e32 v2, v2
	v_pk_mul_f32 v[120:121], v[120:121], v[136:137] op_sel_hi:[1,0]
	v_pk_mul_f32 v[126:127], v[126:127], v[136:137] op_sel_hi:[1,0]
	v_pk_mul_f32 v[116:117], v[116:117], v[136:137] op_sel_hi:[1,0]
	v_add_f32_e32 v2, 1.0, v2
	v_rcp_f32_e32 v140, v2
	v_mul_f32_e32 v2, 0xbfb8aa3b, v129
	v_exp_f32_e32 v2, v2
	s_lshl_b32 s0, s84, 7
	v_pk_mul_f32 v[118:119], v[118:119], v[136:137] op_sel_hi:[1,0]
	s_ashr_i32 s1, s0, 31
	v_add_f32_e32 v2, 1.0, v2
	v_rcp_f32_e32 v141, v2
	s_lshl_b64 s[0:1], s[0:1], 1
	v_pk_mul_f32 v[112:113], v[112:113], v[158:159] op_sel_hi:[1,0]
	v_pk_mul_f32 v[108:109], v[108:109], v[158:159] op_sel_hi:[1,0]
	v_pk_mul_f32 v[128:129], v[128:129], v[140:141]
	v_pk_mul_f32 v[110:111], v[110:111], v[158:159] op_sel_hi:[1,0]
	v_pk_mul_f32 v[124:125], v[124:125], v[128:129]
	v_pk_mul_f32 v[128:129], v[130:131], v[136:137] op_sel_hi:[1,0]
	v_pk_mul_f32 v[104:105], v[104:105], v[158:159] op_sel_hi:[1,0]
	v_mul_f32_e32 v2, 0xbfb8aa3b, v128
	v_exp_f32_e32 v2, v2
	v_pk_mul_f32 v[100:101], v[100:101], v[158:159] op_sel_hi:[1,0]
	v_pk_mul_f32 v[102:103], v[102:103], v[158:159] op_sel_hi:[1,0]
	v_pk_mul_f32 v[96:97], v[96:97], v[138:139] op_sel_hi:[1,0]
	v_add_f32_e32 v2, 1.0, v2
	v_rcp_f32_e32 v130, v2
	v_mul_f32_e32 v2, 0xbfb8aa3b, v129
	v_exp_f32_e32 v2, v2
	v_pk_mul_f32 v[92:93], v[92:93], v[138:139] op_sel_hi:[1,0]
	v_pk_mul_f32 v[94:95], v[94:95], v[138:139] op_sel_hi:[1,0]
	v_pk_mul_f32 v[88:89], v[88:89], v[138:139] op_sel_hi:[1,0]
	v_add_f32_e32 v2, 1.0, v2
	v_rcp_f32_e32 v131, v2
	v_mul_f32_e32 v2, 0xbfb8aa3b, v120
	v_exp_f32_e32 v2, v2
	v_pk_mul_f32 v[84:85], v[84:85], v[138:139] op_sel_hi:[1,0]
	v_pk_mul_f32 v[128:129], v[128:129], v[130:131]
	v_pk_mul_f32 v[86:87], v[86:87], v[138:139] op_sel_hi:[1,0]
	v_add_f32_e32 v2, 1.0, v2
	v_pk_mul_f32 v[126:127], v[126:127], v[128:129]
	v_rcp_f32_e32 v128, v2
	v_mul_f32_e32 v2, 0xbfb8aa3b, v121
	v_exp_f32_e32 v2, v2
	v_pk_mul_f32 v[80:81], v[80:81], v[156:157] op_sel_hi:[1,0]
	v_pk_mul_f32 v[76:77], v[76:77], v[156:157] op_sel_hi:[1,0]
	v_pk_mul_f32 v[78:79], v[78:79], v[156:157] op_sel_hi:[1,0]
	v_add_f32_e32 v2, 1.0, v2
	v_rcp_f32_e32 v129, v2
	v_pk_mul_f32 v[72:73], v[72:73], v[156:157] op_sel_hi:[1,0]
	v_pk_mul_f32 v[68:69], v[68:69], v[156:157] op_sel_hi:[1,0]
	v_pk_mul_f32 v[70:71], v[70:71], v[156:157] op_sel_hi:[1,0]
	v_pk_mul_f32 v[120:121], v[120:121], v[128:129]
	s_waitcnt lgkmcnt(0)
	v_pk_mul_f32 v[64:65], v[64:65], v[132:133] op_sel_hi:[1,0]
	v_pk_mul_f32 v[120:121], v[116:117], v[120:121]
	v_pk_mul_f32 v[116:117], v[122:123], v[136:137] op_sel_hi:[1,0]
	v_pk_mul_f32 v[60:61], v[60:61], v[132:133] op_sel_hi:[1,0]
	v_mul_f32_e32 v2, 0xbfb8aa3b, v116
	v_exp_f32_e32 v2, v2
	v_pk_mul_f32 v[62:63], v[62:63], v[132:133] op_sel_hi:[1,0]
	v_pk_mul_f32 v[56:57], v[56:57], v[132:133] op_sel_hi:[1,0]
	v_pk_mul_f32 v[52:53], v[52:53], v[132:133] op_sel_hi:[1,0]
	v_add_f32_e32 v2, 1.0, v2
	v_rcp_f32_e32 v122, v2
	v_mul_f32_e32 v2, 0xbfb8aa3b, v117
	v_exp_f32_e32 v2, v2
	v_pk_mul_f32 v[54:55], v[54:55], v[132:133] op_sel_hi:[1,0]
	v_pk_mul_f32 v[48:49], v[48:49], v[154:155] op_sel_hi:[1,0]
	v_pk_mul_f32 v[44:45], v[44:45], v[154:155] op_sel_hi:[1,0]
	v_add_f32_e32 v2, 1.0, v2
	v_rcp_f32_e32 v123, v2
	v_lshlrev_b32_e32 v2, 1, v204
	v_pk_mul_f32 v[46:47], v[46:47], v[154:155] op_sel_hi:[1,0]
	v_pk_mul_f32 v[40:41], v[40:41], v[154:155] op_sel_hi:[1,0]
	v_pk_mul_f32 v[116:117], v[116:117], v[122:123]
	v_pk_mul_f32 v[36:37], v[36:37], v[154:155] op_sel_hi:[1,0]
	v_pk_mul_f32 v[122:123], v[118:119], v[116:117]
	v_cvt_pk_bf16_f32 v118, v120, v121
	v_mad_i64_i32 v[120:121], s[12:13], s85, v210, 0
	v_lshl_add_u64 v[120:121], v[120:121], 1, s[10:11]
	v_lshl_add_u64 v[120:121], v[120:121], 0, s[0:1]
	v_cvt_pk_bf16_f32 v116, v124, v125
	v_cvt_pk_bf16_f32 v117, v126, v127
	v_cvt_pk_bf16_f32 v119, v122, v123
	v_lshl_add_u64 v[120:121], v[120:121], 0, v[2:3]
	flat_store_dwordx4 v[120:121], v[116:119] sc1
	v_pk_mul_f32 v[38:39], v[38:39], v[154:155] op_sel_hi:[1,0]
	v_pk_mul_f32 v[32:33], v[32:33], v[134:135] op_sel_hi:[1,0]
	v_mul_f32_e32 v116, 0xbfb8aa3b, v112
	v_mul_f32_e32 v117, 0xbfb8aa3b, v113
	v_exp_f32_e32 v116, v116
	v_exp_f32_e32 v117, v117
	v_pk_mul_f32 v[28:29], v[28:29], v[134:135] op_sel_hi:[1,0]
	v_pk_mul_f32 v[30:31], v[30:31], v[134:135] op_sel_hi:[1,0]
	v_add_f32_e32 v116, 1.0, v116
	v_add_f32_e32 v117, 1.0, v117
	v_rcp_f32_e32 v116, v116
	v_rcp_f32_e32 v117, v117
	v_pk_mul_f32 v[24:25], v[24:25], v[134:135] op_sel_hi:[1,0]
	v_pk_mul_f32 v[20:21], v[20:21], v[134:135] op_sel_hi:[1,0]
	v_pk_mul_f32 v[22:23], v[22:23], v[134:135] op_sel_hi:[1,0]
	v_pk_mul_f32 v[112:113], v[112:113], v[116:117]
	v_pk_mul_f32 v[16:17], v[16:17], v[152:153] op_sel_hi:[1,0]
	v_pk_mul_f32 v[108:109], v[108:109], v[112:113]
	v_pk_mul_f32 v[112:113], v[114:115], v[158:159] op_sel_hi:[1,0]
	v_pk_mul_f32 v[12:13], v[12:13], v[152:153] op_sel_hi:[1,0]
	v_mul_f32_e32 v114, 0xbfb8aa3b, v112
	v_mul_f32_e32 v115, 0xbfb8aa3b, v113
	v_exp_f32_e32 v114, v114
	v_exp_f32_e32 v115, v115
	v_pk_mul_f32 v[14:15], v[14:15], v[152:153] op_sel_hi:[1,0]
	v_pk_mul_f32 v[8:9], v[8:9], v[152:153] op_sel_hi:[1,0]
	v_add_f32_e32 v114, 1.0, v114
	v_add_f32_e32 v115, 1.0, v115
	v_rcp_f32_e32 v114, v114
	v_rcp_f32_e32 v115, v115
	v_pk_mul_f32 v[4:5], v[4:5], v[152:153] op_sel_hi:[1,0]
	v_pk_mul_f32 v[6:7], v[6:7], v[152:153] op_sel_hi:[1,0]
	v_pk_mul_f32 v[112:113], v[112:113], v[114:115]
	s_nop 0
	v_pk_mul_f32 v[110:111], v[110:111], v[112:113]
; __device__ __forceinline__ unsigned pk2(float lo, float hi) { const f32x2 v = {lo, hi}; return __builtin_bit_cast(unsigned, __builtin_convertvector(v, hbf2)); }
; __device__ __forceinline__ float sigmoidf_(float x) { return __builtin_amdgcn_rcpf(1.f + __builtin_amdgcn_exp2f(-1.4426950408889634f * x)); }
;     __device__ __forceinline__ void operator()(const f32x4 (&acc)[2][2][4][2], const Unit& u, int wr, int wc, int fr, int fq, LAS f32x4* rsc, bool reuse) const {
;     ...
;             if (mode == E_GU) {
; #pragma unroll
;                 for (int ai = 0; ai < 2; ++ai)
; #pragma unroll
;                     for (int m = 0; m < 4; ++m) {
;                         const int row = row0 + ai * HALF + m * 16; const float r = rs[ai][m];
;                         float o[8];
; #pragma unroll
;                         for (int n = 0; n < 2; ++n)
; #pragma unroll
;                             for (int e = 0; e < 4; ++e) { const float g = acc[ai][0][m][n][e] * r, up = acc[ai][1][m][n][e] * r; o[n * 4 + e] = g * sigmoidf_(g) * up; }
;                         u32x4 w; w.x = pk2(o[0], o[1]); w.y = pk2(o[2], o[3]); w.z = pk2(o[4], o[5]); w.w = pk2(o[6], o[7]);
;                         *(u32x4*)(outb + (size_t)row * ldo + u.pn * 128 + cl) = w;
;                     }
	v_mul_f32_e32 v112, 0xbfb8aa3b, v104
	v_mul_f32_e32 v113, 0xbfb8aa3b, v105
	v_exp_f32_e32 v112, v112
	v_exp_f32_e32 v113, v113
	v_add_f32_e32 v112, 1.0, v112
	v_add_f32_e32 v113, 1.0, v113
	v_rcp_f32_e32 v112, v112
	v_rcp_f32_e32 v113, v113
	s_nop 0
	v_pk_mul_f32 v[104:105], v[104:105], v[112:113]
	s_nop 0
	v_pk_mul_f32 v[104:105], v[100:101], v[104:105]
	v_pk_mul_f32 v[100:101], v[106:107], v[158:159] op_sel_hi:[1,0]
	v_or_b32_e32 v112, 16, v210
	v_mul_f32_e32 v106, 0xbfb8aa3b, v100
	v_mul_f32_e32 v107, 0xbfb8aa3b, v101
	v_exp_f32_e32 v106, v106
	v_exp_f32_e32 v107, v107
	v_add_f32_e32 v106, 1.0, v106
	v_add_f32_e32 v107, 1.0, v107
	v_rcp_f32_e32 v106, v106
	v_rcp_f32_e32 v107, v107
	s_nop 0
	v_pk_mul_f32 v[100:101], v[100:101], v[106:107]
	s_nop 0
	v_pk_mul_f32 v[106:107], v[102:103], v[100:101]
	v_cvt_pk_bf16_f32 v102, v104, v105
	v_mad_i64_i32 v[104:105], s[12:13], s85, v112, 0
	v_lshl_add_u64 v[104:105], v[104:105], 1, s[10:11]
	v_lshl_add_u64 v[104:105], v[104:105], 0, s[0:1]
	v_cvt_pk_bf16_f32 v100, v108, v109
	v_cvt_pk_bf16_f32 v101, v110, v111
	v_cvt_pk_bf16_f32 v103, v106, v107
	v_lshl_add_u64 v[104:105], v[104:105], 0, v[2:3]
	flat_store_dwordx4 v[104:105], v[100:103] sc1
	s_nop 1
	v_mul_f32_e32 v100, 0xbfb8aa3b, v96
	v_mul_f32_e32 v101, 0xbfb8aa3b, v97
	v_exp_f32_e32 v100, v100
	v_exp_f32_e32 v101, v101
	v_add_f32_e32 v100, 1.0, v100
	v_add_f32_e32 v101, 1.0, v101
	v_rcp_f32_e32 v100, v100
	v_rcp_f32_e32 v101, v101
	s_nop 0
	v_pk_mul_f32 v[96:97], v[96:97], v[100:101]
	s_nop 0
	v_pk_mul_f32 v[92:93], v[92:93], v[96:97]
	v_pk_mul_f32 v[96:97], v[98:99], v[138:139] op_sel_hi:[1,0]
	s_nop 0
	v_mul_f32_e32 v98, 0xbfb8aa3b, v96
	v_mul_f32_e32 v99, 0xbfb8aa3b, v97
	v_exp_f32_e32 v98, v98
	v_exp_f32_e32 v99, v99
	v_add_f32_e32 v98, 1.0, v98
	v_add_f32_e32 v99, 1.0, v99
	v_rcp_f32_e32 v98, v98
	v_rcp_f32_e32 v99, v99
	s_nop 0
	v_pk_mul_f32 v[96:97], v[96:97], v[98:99]
	s_nop 0
	v_pk_mul_f32 v[94:95], v[94:95], v[96:97]
	v_mul_f32_e32 v96, 0xbfb8aa3b, v88
	v_mul_f32_e32 v97, 0xbfb8aa3b, v89
	v_exp_f32_e32 v96, v96
	v_exp_f32_e32 v97, v97
	v_add_f32_e32 v96, 1.0, v96
	v_add_f32_e32 v97, 1.0, v97
	v_rcp_f32_e32 v96, v96
	v_rcp_f32_e32 v97, v97
	s_nop 0
	v_pk_mul_f32 v[88:89], v[88:89], v[96:97]
	s_nop 0
	v_pk_mul_f32 v[88:89], v[84:85], v[88:89]
	v_pk_mul_f32 v[84:85], v[90:91], v[138:139] op_sel_hi:[1,0]
	v_or_b32_e32 v96, 32, v210
	v_mul_f32_e32 v90, 0xbfb8aa3b, v84
	v_mul_f32_e32 v91, 0xbfb8aa3b, v85
	v_exp_f32_e32 v90, v90
	v_exp_f32_e32 v91, v91
	v_add_f32_e32 v90, 1.0, v90
	v_add_f32_e32 v91, 1.0, v91
	v_rcp_f32_e32 v90, v90
	v_rcp_f32_e32 v91, v91
	s_nop 0
	v_pk_mul_f32 v[84:85], v[84:85], v[90:91]
	s_nop 0
	v_pk_mul_f32 v[90:91], v[86:87], v[84:85]
	v_cvt_pk_bf16_f32 v86, v88, v89
	v_mad_i64_i32 v[88:89], s[12:13], s85, v96, 0
	v_lshl_add_u64 v[88:89], v[88:89], 1, s[10:11]
	v_lshl_add_u64 v[88:89], v[88:89], 0, s[0:1]
	v_cvt_pk_bf16_f32 v84, v92, v93
	v_cvt_pk_bf16_f32 v85, v94, v95
	v_cvt_pk_bf16_f32 v87, v90, v91
	v_lshl_add_u64 v[88:89], v[88:89], 0, v[2:3]
	flat_store_dwordx4 v[88:89], v[84:87] sc1
	s_nop 1
	v_mul_f32_e32 v84, 0xbfb8aa3b, v80
	v_mul_f32_e32 v85, 0xbfb8aa3b, v81
	v_exp_f32_e32 v84, v84
	v_exp_f32_e32 v85, v85
	v_add_f32_e32 v84, 1.0, v84
	v_add_f32_e32 v85, 1.0, v85
	v_rcp_f32_e32 v84, v84
	v_rcp_f32_e32 v85, v85
	s_nop 0
	v_pk_mul_f32 v[80:81], v[80:81], v[84:85]
	s_nop 0
	v_pk_mul_f32 v[76:77], v[76:77], v[80:81]
	v_pk_mul_f32 v[80:81], v[82:83], v[156:157] op_sel_hi:[1,0]
	s_nop 0
	v_mul_f32_e32 v82, 0xbfb8aa3b, v80
	v_mul_f32_e32 v83, 0xbfb8aa3b, v81
	v_exp_f32_e32 v82, v82
	v_exp_f32_e32 v83, v83
	v_add_f32_e32 v82, 1.0, v82
	v_add_f32_e32 v83, 1.0, v83
	v_rcp_f32_e32 v82, v82
	v_rcp_f32_e32 v83, v83
	s_nop 0
	v_pk_mul_f32 v[80:81], v[80:81], v[82:83]
	s_nop 0
	v_pk_mul_f32 v[78:79], v[78:79], v[80:81]
	v_mul_f32_e32 v80, 0xbfb8aa3b, v72
	v_mul_f32_e32 v81, 0xbfb8aa3b, v73
	v_exp_f32_e32 v80, v80
	v_exp_f32_e32 v81, v81
	v_add_f32_e32 v80, 1.0, v80
	v_add_f32_e32 v81, 1.0, v81
	v_rcp_f32_e32 v80, v80
	v_rcp_f32_e32 v81, v81
	s_nop 0
	v_pk_mul_f32 v[72:73], v[72:73], v[80:81]
	s_nop 0
	v_pk_mul_f32 v[72:73], v[68:69], v[72:73]
	v_pk_mul_f32 v[68:69], v[74:75], v[156:157] op_sel_hi:[1,0]
	v_or_b32_e32 v80, 48, v210
	v_mul_f32_e32 v74, 0xbfb8aa3b, v68
	v_mul_f32_e32 v75, 0xbfb8aa3b, v69
	v_exp_f32_e32 v74, v74
	v_exp_f32_e32 v75, v75
	v_add_f32_e32 v74, 1.0, v74
	v_add_f32_e32 v75, 1.0, v75
	v_rcp_f32_e32 v74, v74
	v_rcp_f32_e32 v75, v75
	s_nop 0
	v_pk_mul_f32 v[68:69], v[68:69], v[74:75]
	s_nop 0
	v_pk_mul_f32 v[74:75], v[70:71], v[68:69]
	v_cvt_pk_bf16_f32 v70, v72, v73
	v_mad_i64_i32 v[72:73], s[12:13], s85, v80, 0
	v_lshl_add_u64 v[72:73], v[72:73], 1, s[10:11]
	v_lshl_add_u64 v[72:73], v[72:73], 0, s[0:1]
	v_cvt_pk_bf16_f32 v68, v76, v77
	v_cvt_pk_bf16_f32 v69, v78, v79
	v_cvt_pk_bf16_f32 v71, v74, v75
	v_lshl_add_u64 v[72:73], v[72:73], 0, v[2:3]
	flat_store_dwordx4 v[72:73], v[68:71] sc1
	s_nop 1
	v_mul_f32_e32 v68, 0xbfb8aa3b, v64
	v_mul_f32_e32 v69, 0xbfb8aa3b, v65
	v_exp_f32_e32 v68, v68
	v_exp_f32_e32 v69, v69
	v_add_u32_e32 v70, 0x80, v210
	v_add_f32_e32 v68, 1.0, v68
	v_add_f32_e32 v69, 1.0, v69
	v_rcp_f32_e32 v68, v68
	v_rcp_f32_e32 v69, v69
	s_nop 0
	v_pk_mul_f32 v[64:65], v[64:65], v[68:69]
	s_nop 0
	v_pk_mul_f32 v[60:61], v[60:61], v[64:65]
	v_pk_mul_f32 v[64:65], v[66:67], v[132:133] op_sel_hi:[1,0]
	s_nop 0
	v_mul_f32_e32 v66, 0xbfb8aa3b, v64
	v_mul_f32_e32 v67, 0xbfb8aa3b, v65
	v_exp_f32_e32 v66, v66
	v_exp_f32_e32 v67, v67
	v_add_f32_e32 v66, 1.0, v66
	v_add_f32_e32 v67, 1.0, v67
	v_rcp_f32_e32 v66, v66
	v_rcp_f32_e32 v67, v67
	s_nop 0
	v_pk_mul_f32 v[64:65], v[64:65], v[66:67]
; __device__ __forceinline__ unsigned pk2(float lo, float hi) { const f32x2 v = {lo, hi}; return __builtin_bit_cast(unsigned, __builtin_convertvector(v, hbf2)); }
; __device__ __forceinline__ float sigmoidf_(float x) { return __builtin_amdgcn_rcpf(1.f + __builtin_amdgcn_exp2f(-1.4426950408889634f * x)); }
;     __device__ __forceinline__ void operator()(const f32x4 (&acc)[2][2][4][2], const Unit& u, int wr, int wc, int fr, int fq, LAS f32x4* rsc, bool reuse) const {
;     ...
;             if (mode == E_GU) {
; #pragma unroll
;                 for (int ai = 0; ai < 2; ++ai)
; #pragma unroll
;                     for (int m = 0; m < 4; ++m) {
;                         const int row = row0 + ai * HALF + m * 16; const float r = rs[ai][m];
;                         float o[8];
; #pragma unroll
;                         for (int n = 0; n < 2; ++n)
; #pragma unroll
;                             for (int e = 0; e < 4; ++e) { const float g = acc[ai][0][m][n][e] * r, up = acc[ai][1][m][n][e] * r; o[n * 4 + e] = g * sigmoidf_(g) * up; }
;                         u32x4 w; w.x = pk2(o[0], o[1]); w.y = pk2(o[2], o[3]); w.z = pk2(o[4], o[5]); w.w = pk2(o[6], o[7]);
;                         *(u32x4*)(outb + (size_t)row * ldo + u.pn * 128 + cl) = w;
;                     }
	s_nop 0
	v_pk_mul_f32 v[62:63], v[62:63], v[64:65]
	v_mul_f32_e32 v64, 0xbfb8aa3b, v56
	v_mul_f32_e32 v65, 0xbfb8aa3b, v57
	v_exp_f32_e32 v64, v64
	v_exp_f32_e32 v65, v65
	v_add_f32_e32 v64, 1.0, v64
	v_add_f32_e32 v65, 1.0, v65
	v_rcp_f32_e32 v64, v64
	v_rcp_f32_e32 v65, v65
	s_nop 0
	v_pk_mul_f32 v[56:57], v[56:57], v[64:65]
	s_nop 0
	v_pk_mul_f32 v[56:57], v[52:53], v[56:57]
	v_pk_mul_f32 v[52:53], v[58:59], v[132:133] op_sel_hi:[1,0]
	s_nop 0
	v_mul_f32_e32 v58, 0xbfb8aa3b, v52
	v_mul_f32_e32 v59, 0xbfb8aa3b, v53
	v_exp_f32_e32 v58, v58
	v_exp_f32_e32 v59, v59
	v_add_f32_e32 v58, 1.0, v58
	v_add_f32_e32 v59, 1.0, v59
	v_rcp_f32_e32 v58, v58
	v_rcp_f32_e32 v59, v59
	s_nop 0
	v_pk_mul_f32 v[52:53], v[52:53], v[58:59]
	s_nop 0
	v_pk_mul_f32 v[58:59], v[54:55], v[52:53]
	v_cvt_pk_bf16_f32 v54, v56, v57
	v_mad_i64_i32 v[56:57], s[12:13], s85, v70, 0
	v_lshl_add_u64 v[56:57], v[56:57], 1, s[10:11]
	v_lshl_add_u64 v[56:57], v[56:57], 0, s[0:1]
	v_cvt_pk_bf16_f32 v52, v60, v61
	v_cvt_pk_bf16_f32 v53, v62, v63
	v_cvt_pk_bf16_f32 v55, v58, v59
	v_lshl_add_u64 v[56:57], v[56:57], 0, v[2:3]
	flat_store_dwordx4 v[56:57], v[52:55] sc1
	s_nop 1
	v_mul_f32_e32 v52, 0xbfb8aa3b, v48
	v_mul_f32_e32 v53, 0xbfb8aa3b, v49
	v_exp_f32_e32 v52, v52
	v_exp_f32_e32 v53, v53
	v_add_f32_e32 v52, 1.0, v52
	v_add_f32_e32 v53, 1.0, v53
	v_rcp_f32_e32 v52, v52
	v_rcp_f32_e32 v53, v53
	s_nop 0
	v_pk_mul_f32 v[48:49], v[48:49], v[52:53]
	s_nop 0
	v_pk_mul_f32 v[44:45], v[44:45], v[48:49]
	v_pk_mul_f32 v[48:49], v[50:51], v[154:155] op_sel_hi:[1,0]
	s_nop 0
	v_mul_f32_e32 v50, 0xbfb8aa3b, v48
	v_mul_f32_e32 v51, 0xbfb8aa3b, v49
	v_exp_f32_e32 v50, v50
	v_exp_f32_e32 v51, v51
	v_add_f32_e32 v50, 1.0, v50
	v_add_f32_e32 v51, 1.0, v51
	v_rcp_f32_e32 v50, v50
	v_rcp_f32_e32 v51, v51
	s_nop 0
	v_pk_mul_f32 v[48:49], v[48:49], v[50:51]
	s_nop 0
	v_pk_mul_f32 v[46:47], v[46:47], v[48:49]
	v_mul_f32_e32 v48, 0xbfb8aa3b, v40
	v_mul_f32_e32 v49, 0xbfb8aa3b, v41
	v_exp_f32_e32 v48, v48
	v_exp_f32_e32 v49, v49
	v_add_f32_e32 v48, 1.0, v48
	v_add_f32_e32 v49, 1.0, v49
	v_rcp_f32_e32 v48, v48
	v_rcp_f32_e32 v49, v49
	s_nop 0
	v_pk_mul_f32 v[40:41], v[40:41], v[48:49]
	s_nop 0
	v_pk_mul_f32 v[40:41], v[36:37], v[40:41]
	v_pk_mul_f32 v[36:37], v[42:43], v[154:155] op_sel_hi:[1,0]
	v_add_u32_e32 v48, 0x90, v210
	v_mul_f32_e32 v42, 0xbfb8aa3b, v36
	v_mul_f32_e32 v43, 0xbfb8aa3b, v37
	v_exp_f32_e32 v42, v42
	v_exp_f32_e32 v43, v43
	v_add_f32_e32 v42, 1.0, v42
	v_add_f32_e32 v43, 1.0, v43
	v_rcp_f32_e32 v42, v42
	v_rcp_f32_e32 v43, v43
	s_nop 0
	v_pk_mul_f32 v[36:37], v[36:37], v[42:43]
	s_nop 0
	v_pk_mul_f32 v[42:43], v[38:39], v[36:37]
	v_cvt_pk_bf16_f32 v38, v40, v41
	v_mad_i64_i32 v[40:41], s[12:13], s85, v48, 0
	v_lshl_add_u64 v[40:41], v[40:41], 1, s[10:11]
	v_lshl_add_u64 v[40:41], v[40:41], 0, s[0:1]
	v_cvt_pk_bf16_f32 v36, v44, v45
	v_cvt_pk_bf16_f32 v37, v46, v47
	v_cvt_pk_bf16_f32 v39, v42, v43
	v_lshl_add_u64 v[40:41], v[40:41], 0, v[2:3]
	flat_store_dwordx4 v[40:41], v[36:39] sc1
	s_nop 1
	v_mul_f32_e32 v36, 0xbfb8aa3b, v32
	v_mul_f32_e32 v37, 0xbfb8aa3b, v33
	v_exp_f32_e32 v36, v36
	v_exp_f32_e32 v37, v37
	v_add_f32_e32 v36, 1.0, v36
	v_add_f32_e32 v37, 1.0, v37
	v_rcp_f32_e32 v36, v36
	v_rcp_f32_e32 v37, v37
	s_nop 0
	v_pk_mul_f32 v[32:33], v[32:33], v[36:37]
	s_nop 0
	v_pk_mul_f32 v[28:29], v[28:29], v[32:33]
	v_pk_mul_f32 v[32:33], v[34:35], v[134:135] op_sel_hi:[1,0]
	s_nop 0
	v_mul_f32_e32 v34, 0xbfb8aa3b, v32
	v_mul_f32_e32 v35, 0xbfb8aa3b, v33
	v_exp_f32_e32 v34, v34
	v_exp_f32_e32 v35, v35
	v_add_f32_e32 v34, 1.0, v34
	v_add_f32_e32 v35, 1.0, v35
	v_rcp_f32_e32 v34, v34
	v_rcp_f32_e32 v35, v35
	s_nop 0
	v_pk_mul_f32 v[32:33], v[32:33], v[34:35]
	s_nop 0
	v_pk_mul_f32 v[30:31], v[30:31], v[32:33]
	v_mul_f32_e32 v32, 0xbfb8aa3b, v24
	v_mul_f32_e32 v33, 0xbfb8aa3b, v25
	v_exp_f32_e32 v32, v32
	v_exp_f32_e32 v33, v33
	v_add_f32_e32 v32, 1.0, v32
	v_add_f32_e32 v33, 1.0, v33
	v_rcp_f32_e32 v32, v32
	v_rcp_f32_e32 v33, v33
	s_nop 0
	v_pk_mul_f32 v[24:25], v[24:25], v[32:33]
	s_nop 0
	v_pk_mul_f32 v[24:25], v[20:21], v[24:25]
	v_pk_mul_f32 v[20:21], v[26:27], v[134:135] op_sel_hi:[1,0]
	v_add_u32_e32 v32, 0xa0, v210
	v_mul_f32_e32 v26, 0xbfb8aa3b, v20
	v_mul_f32_e32 v27, 0xbfb8aa3b, v21
	v_exp_f32_e32 v26, v26
	v_exp_f32_e32 v27, v27
	v_add_f32_e32 v26, 1.0, v26
	v_add_f32_e32 v27, 1.0, v27
	v_rcp_f32_e32 v26, v26
	v_rcp_f32_e32 v27, v27
	s_nop 0
	v_pk_mul_f32 v[20:21], v[20:21], v[26:27]
	s_nop 0
	v_pk_mul_f32 v[26:27], v[22:23], v[20:21]
	v_cvt_pk_bf16_f32 v22, v24, v25
	v_mad_i64_i32 v[24:25], s[12:13], s85, v32, 0
	v_lshl_add_u64 v[24:25], v[24:25], 1, s[10:11]
	v_lshl_add_u64 v[24:25], v[24:25], 0, s[0:1]
	v_cvt_pk_bf16_f32 v20, v28, v29
	v_cvt_pk_bf16_f32 v21, v30, v31
	v_cvt_pk_bf16_f32 v23, v26, v27
	v_lshl_add_u64 v[24:25], v[24:25], 0, v[2:3]
	flat_store_dwordx4 v[24:25], v[20:23] sc1
	s_nop 1
	v_mul_f32_e32 v20, 0xbfb8aa3b, v16
	v_mul_f32_e32 v21, 0xbfb8aa3b, v17
	v_exp_f32_e32 v20, v20
	v_exp_f32_e32 v21, v21
	v_add_f32_e32 v20, 1.0, v20
	v_add_f32_e32 v21, 1.0, v21
	v_rcp_f32_e32 v20, v20
	v_rcp_f32_e32 v21, v21
	s_nop 0
	v_pk_mul_f32 v[16:17], v[16:17], v[20:21]
	s_nop 0
	v_pk_mul_f32 v[12:13], v[12:13], v[16:17]
	v_pk_mul_f32 v[16:17], v[18:19], v[152:153] op_sel_hi:[1,0]
	s_nop 0
	v_mul_f32_e32 v18, 0xbfb8aa3b, v16
	v_mul_f32_e32 v19, 0xbfb8aa3b, v17
	v_exp_f32_e32 v18, v18
	v_exp_f32_e32 v19, v19
	v_add_f32_e32 v18, 1.0, v18
	v_add_f32_e32 v19, 1.0, v19
	v_rcp_f32_e32 v18, v18
	v_rcp_f32_e32 v19, v19
	s_nop 0
	v_pk_mul_f32 v[16:17], v[16:17], v[18:19]
	s_nop 0
	v_pk_mul_f32 v[14:15], v[14:15], v[16:17]
	v_mul_f32_e32 v16, 0xbfb8aa3b, v8
	v_mul_f32_e32 v17, 0xbfb8aa3b, v9
	v_exp_f32_e32 v16, v16
	v_exp_f32_e32 v17, v17
	v_add_f32_e32 v16, 1.0, v16
	v_add_f32_e32 v17, 1.0, v17
	v_rcp_f32_e32 v16, v16
	v_rcp_f32_e32 v17, v17
	s_nop 0
	v_pk_mul_f32 v[8:9], v[8:9], v[16:17]
	s_nop 0
	v_pk_mul_f32 v[8:9], v[4:5], v[8:9]
	v_pk_mul_f32 v[4:5], v[10:11], v[152:153] op_sel_hi:[1,0]
	v_add_u32_e32 v16, 0xb0, v210
	v_mul_f32_e32 v10, 0xbfb8aa3b, v4
	v_mul_f32_e32 v11, 0xbfb8aa3b, v5
	v_exp_f32_e32 v10, v10
	v_exp_f32_e32 v11, v11
	v_add_f32_e32 v10, 1.0, v10
	v_add_f32_e32 v11, 1.0, v11
	v_rcp_f32_e32 v10, v10
	v_rcp_f32_e32 v11, v11
	s_nop 0
	v_pk_mul_f32 v[4:5], v[4:5], v[10:11]
	s_nop 0
	v_pk_mul_f32 v[10:11], v[6:7], v[4:5]
	v_cvt_pk_bf16_f32 v6, v8, v9
	v_mad_i64_i32 v[8:9], s[12:13], s85, v16, 0
	v_lshl_add_u64 v[8:9], v[8:9], 1, s[10:11]
	v_lshl_add_u64 v[8:9], v[8:9], 0, s[0:1]
	v_cvt_pk_bf16_f32 v4, v12, v13
	v_cvt_pk_bf16_f32 v5, v14, v15
	v_cvt_pk_bf16_f32 v7, v10, v11
	v_lshl_add_u64 v[8:9], v[8:9], 0, v[2:3]
	flat_store_dwordx4 v[8:9], v[4:7] sc1

; __device__ __forceinline__ float ssq_val(u64 v) { return (float)v * (1.f / 4294967296.f); }
; __global__ void __launch_bounds__(NTHREADS, 2) mega(Args a) {
;     ...
;     if (lo <= P_FINAL && P_FINAL < hi) {
;         PHASE_HEAD
;         const u64* ssq = ssqx + 4 * TOK; const float* fn = AIN(I_FN);
;         for (int row = gw; row < TOK; row += NGW) { const float rs = 1.f / sqrtf(ssq_val(ssq[row]) * (1.f / DM) + EPS);
;             const u32x4* hp = (const u32x4*)(hb + (size_t)row * DM) + lane; f32x4* p = (f32x4*)(a.out + (size_t)row * DM);
;             u32x4 hv[4];
; #pragma unroll
;             for (int j = 0; j < 4; ++j) hv[j] = hp[64 * j];
; #pragma unroll
;             for (int j = 0; j < 4; ++j) { const int c = (lane + 64 * j) * 8; const f32x4 g0 = *(const f32x4*)(fn + c), g1 = *(const f32x4*)(fn + c + 4); const u32x4 r = hv[j];
;                 p[(c >> 2)] = (f32x4){bflo(r.x), bfhi(r.x), bflo(r.y), bfhi(r.y)} * rs * g0; p[(c >> 2) + 1] = (f32x4){bflo(r.z), bfhi(r.z), bflo(r.w), bfhi(r.w)} * rs * g1; } }
;     }
.LBB0_2189:
	global_load_dwordx2 v[38:39], v1, s[2:3]
	global_load_dwordx4 v[14:17], v[10:11], off offset:-2048
	global_load_dwordx4 v[18:21], v[2:3], off
	global_load_dwordx4 v[22:25], v[2:3], off offset:16
	global_load_dwordx4 v[26:29], v[10:11], off offset:-1024
	global_load_dwordx4 v[30:33], v[10:11], off
	global_load_dwordx4 v[34:37], v[10:11], off offset:1024
	s_add_i32 s10, s10, s62
	s_add_u32 s2, s2, s4
	s_addc_u32 s3, s3, s5
	v_lshl_add_u64 v[10:11], v[10:11], 0, s[8:9]
	s_cmpk_lt_i32 s10, 0x4000
	s_waitcnt vmcnt(6)
	v_ffbh_u32_e32 v13, v39
	v_min_u32_e32 v13, 32, v13
	v_lshlrev_b64 v[38:39], v13, v[38:39]
	v_min_u32_e32 v38, 1, v38
	v_or_b32_e32 v38, v39, v38
	v_cvt_f32_u32_e32 v38, v38
	v_sub_u32_e32 v13, 32, v13
	s_waitcnt vmcnt(5)
	v_lshlrev_b32_e32 v40, 16, v14
	v_and_b32_e32 v41, 0xffff0000, v14
	v_ldexp_f32 v13, v38, v13
	v_mul_f32_e32 v13, 0x2f800000, v13
	v_fmamk_f32 v13, v13, 0x3a000000, v0
	v_mul_f32_e32 v38, 0x4f800000, v13
	v_cmp_gt_f32_e32 vcc, s11, v13
	v_lshlrev_b32_e32 v14, 16, v15
	v_and_b32_e32 v15, 0xffff0000, v15
	v_cndmask_b32_e32 v13, v13, v38, vcc
	v_sqrt_f32_e32 v38, v13
	v_lshlrev_b32_e32 v42, 16, v16
	v_and_b32_e32 v43, 0xffff0000, v16
	v_lshlrev_b32_e32 v16, 16, v17
	v_add_u32_e32 v39, -1, v38
	v_add_u32_e32 v44, 1, v38
	v_fma_f32 v45, -v39, v38, v13
	v_fma_f32 v46, -v44, v38, v13
	v_cmp_ge_f32_e64 s[0:1], 0, v45
	v_and_b32_e32 v17, 0xffff0000, v17
	s_nop 0
	v_cndmask_b32_e64 v38, v38, v39, s[0:1]
	v_cmp_lt_f32_e64 s[0:1], 0, v46
	s_nop 1
	v_cndmask_b32_e64 v38, v38, v44, s[0:1]
	v_mul_f32_e32 v39, 0x37800000, v38
	v_cndmask_b32_e32 v38, v38, v39, vcc
	v_cmp_class_f32_e32 vcc, v13, v12
	s_nop 1
	v_cndmask_b32_e32 v13, v38, v13, vcc
	v_div_scale_f32 v38, s[0:1], v13, v13, 1.0
	v_rcp_f32_e32 v44, v38
	v_div_scale_f32 v39, vcc, 1.0, v13, 1.0
	v_fma_f32 v45, -v38, v44, 1.0
	v_fmac_f32_e32 v44, v45, v44
	v_mul_f32_e32 v45, v39, v44
	v_fma_f32 v46, -v38, v45, v39
	v_fmac_f32_e32 v45, v46, v44
	v_fma_f32 v38, -v38, v45, v39
	v_div_fmas_f32 v38, v38, v44, v45
	v_div_fixup_f32 v38, v38, v13, 1.0
	v_pk_mul_f32 v[40:41], v[38:39], v[40:41] op_sel_hi:[0,1]
	v_pk_mul_f32 v[14:15], v[38:39], v[14:15] op_sel_hi:[0,1]
	v_pk_mul_f32 v[42:43], v[38:39], v[42:43] op_sel_hi:[0,1]
	v_pk_mul_f32 v[44:45], v[38:39], v[16:17] op_sel_hi:[0,1]
	s_waitcnt vmcnt(4)
	v_pk_mul_f32 v[16:17], v[14:15], v[20:21]
	v_pk_mul_f32 v[14:15], v[40:41], v[18:19]
	s_waitcnt vmcnt(3)
	v_pk_mul_f32 v[20:21], v[44:45], v[24:25]
	v_pk_mul_f32 v[18:19], v[42:43], v[22:23]
	global_store_dwordx4 v[8:9], v[14:17], off offset:-4096 nt
	global_store_dwordx4 v[8:9], v[18:21], off offset:-4080 nt
	global_load_dwordx4 v[14:17], v[2:3], off offset:2048
	s_nop 0
	global_load_dwordx4 v[18:21], v[2:3], off offset:2064
	s_waitcnt vmcnt(6)
	v_lshlrev_b32_e32 v22, 16, v26
	v_and_b32_e32 v23, 0xffff0000, v26
	v_lshlrev_b32_e32 v24, 16, v27
	v_and_b32_e32 v25, 0xffff0000, v27
	v_lshlrev_b32_e32 v26, 16, v28
	v_and_b32_e32 v27, 0xffff0000, v28
	v_lshlrev_b32_e32 v28, 16, v29
	v_and_b32_e32 v29, 0xffff0000, v29
	v_pk_mul_f32 v[24:25], v[38:39], v[24:25] op_sel_hi:[0,1]
	v_pk_mul_f32 v[22:23], v[38:39], v[22:23] op_sel_hi:[0,1]
	v_pk_mul_f32 v[28:29], v[38:39], v[28:29] op_sel_hi:[0,1]
	v_pk_mul_f32 v[26:27], v[38:39], v[26:27] op_sel_hi:[0,1]
	s_waitcnt vmcnt(1)
	v_pk_mul_f32 v[14:15], v[22:23], v[14:15]
	v_pk_mul_f32 v[16:17], v[24:25], v[16:17]
	s_waitcnt vmcnt(0)
	v_pk_mul_f32 v[18:19], v[26:27], v[18:19]
	v_pk_mul_f32 v[20:21], v[28:29], v[20:21]
	global_store_dwordx4 v[8:9], v[14:17], off offset:-2048 nt
	global_store_dwordx4 v[8:9], v[18:21], off offset:-2032 nt
	global_load_dwordx4 v[14:17], v[4:5], off
	s_nop 0
	global_load_dwordx4 v[18:21], v[4:5], off offset:16
	v_lshlrev_b32_e32 v22, 16, v30
	v_and_b32_e32 v23, 0xffff0000, v30
	v_lshlrev_b32_e32 v24, 16, v31
	v_and_b32_e32 v25, 0xffff0000, v31
	v_lshlrev_b32_e32 v26, 16, v32
	v_and_b32_e32 v27, 0xffff0000, v32
	v_lshlrev_b32_e32 v28, 16, v33
	v_and_b32_e32 v29, 0xffff0000, v33
	v_pk_mul_f32 v[24:25], v[38:39], v[24:25] op_sel_hi:[0,1]
	v_pk_mul_f32 v[22:23], v[38:39], v[22:23] op_sel_hi:[0,1]
	v_pk_mul_f32 v[28:29], v[38:39], v[28:29] op_sel_hi:[0,1]
	v_pk_mul_f32 v[26:27], v[38:39], v[26:27] op_sel_hi:[0,1]
	s_waitcnt vmcnt(1)
	v_pk_mul_f32 v[14:15], v[22:23], v[14:15]
	v_pk_mul_f32 v[16:17], v[24:25], v[16:17]
	s_waitcnt vmcnt(0)
	v_pk_mul_f32 v[18:19], v[26:27], v[18:19]
	v_pk_mul_f32 v[20:21], v[28:29], v[20:21]
	global_store_dwordx4 v[8:9], v[14:17], off nt
	global_store_dwordx4 v[8:9], v[18:21], off offset:16 nt
	global_load_dwordx4 v[14:17], v[6:7], off
	s_nop 0
	global_load_dwordx4 v[18:21], v[6:7], off offset:16
	v_lshlrev_b32_e32 v22, 16, v34
	v_and_b32_e32 v23, 0xffff0000, v34
	v_lshlrev_b32_e32 v24, 16, v35
	v_and_b32_e32 v25, 0xffff0000, v35
	v_lshlrev_b32_e32 v26, 16, v36
	v_and_b32_e32 v27, 0xffff0000, v36
	v_lshlrev_b32_e32 v28, 16, v37
	v_and_b32_e32 v29, 0xffff0000, v37
	v_pk_mul_f32 v[24:25], v[38:39], v[24:25] op_sel_hi:[0,1]
	v_pk_mul_f32 v[22:23], v[38:39], v[22:23] op_sel_hi:[0,1]
	v_pk_mul_f32 v[28:29], v[38:39], v[28:29] op_sel_hi:[0,1]
	v_pk_mul_f32 v[26:27], v[38:39], v[26:27] op_sel_hi:[0,1]
	s_waitcnt vmcnt(1)
	v_pk_mul_f32 v[14:15], v[22:23], v[14:15]
	v_pk_mul_f32 v[16:17], v[24:25], v[16:17]
	s_waitcnt vmcnt(0)
	v_pk_mul_f32 v[18:19], v[26:27], v[18:19]
	v_pk_mul_f32 v[20:21], v[28:29], v[20:21]
	global_store_dwordx4 v[8:9], v[14:17], off offset:2048 nt
	global_store_dwordx4 v[8:9], v[18:21], off offset:2064 nt
	v_lshl_add_u64 v[8:9], v[8:9], 0, s[6:7]
	s_cbranch_scc1 .LBB0_2189
